# GEMM operand staging with full 128-byte lines per row (LDS half-tile image 128 rows x 128 B, chunk index xor row&7; fragment reads re-addressed) in all six GEMM phases
# speedup vs baseline: 1.0092x; 1.0092x over previous
.LBB0_207:
	s_cmp_lt_i32 s84, 3
	s_cselect_b64 s[2:3], -1, 0
	s_add_u32 s92, s82, 0x7000000
	s_addc_u32 s93, s83, 0
	s_and_b64 s[4:5], s[2:3], s[6:7]
	s_andn2_b64 vcc, exec, s[4:5]
	s_cbranch_vccnz .LBB0_224
	v_mov_b32_e32 v9, v236
	s_cmpk_gt_i32 s96, 0xaff
	s_nop 0
	v_readfirstlane_b32 s7, v9
	s_cbranch_scc1 .LBB0_224
	v_lshlrev_b32_e32 v0, 4, v9
	v_add_u32_e32 v1, 0x2000, v0
	v_ashrrev_i32_e32 v2, 31, v1
	v_lshrrev_b32_e32 v2, 22, v2
	v_add_u32_e32 v2, v1, v2
	v_ashrrev_i32_e32 v8, 10, v2
	v_mul_i32_i24_e32 v2, 0x400, v8
	v_sub_u32_e32 v1, v1, v2
	v_lshrrev_b32_e32 v2, 4, v1
	v_bitop3_b32 v1, v2, v1, 32 bitop3:0x6c
	v_ashrrev_i32_e32 v2, 31, v1
	v_lshrrev_b32_e32 v2, 26, v2
	v_add_u32_e32 v2, v1, v2
	v_lshlrev_b32_e32 v3, 3, v8
	v_ashrrev_i32_e32 v10, 6, v2
	v_and_b32_e32 v3, -16, v3
	v_add_u32_e32 v3, v10, v3
	v_and_b32_e32 v4, 3, v10
	s_mov_b32 s6, 0x1fffe0
	v_lshrrev_b32_e32 v5, 2, v3
	v_lshlrev_b32_e32 v6, 1, v3
	v_and_b32_e32 v2, 0xc0, v2
	v_and_or_b32 v4, v3, s6, v4
	v_and_b32_e32 v5, 4, v5
	v_and_b32_e32 v6, 24, v6
	v_sub_u32_e32 v1, v1, v2
	v_mov_b32_e32 v2, 1
	v_or3_b32 v4, v4, v5, v6
	v_lshlrev_b32_e32 v5, 5, v8
	v_ashrrev_i16_sdwa v1, v2, sext(v1) dst_sel:DWORD dst_unused:UNUSED_PAD src0_sel:DWORD src1_sel:BYTE_0
	v_and_b32_e32 v5, 32, v5
	v_bfe_i32 v11, v1, 0, 16
	v_add_lshl_u32 v1, v5, v11, 1
	v_lshrrev_b32_e32 v250, 6, v236
	v_and_b32_e32 v251, 63, v236
	v_lshrrev_b32_e32 v252, 3, v251
	v_and_b32_e32 v251, 7, v251
	v_xor_b32_e32 v251, v251, v252
	v_lshlrev_b32_e32 v251, 4, v251
	v_lshl_add_u32 v253, v250, 3, v252
	v_lshl_add_u32 v246, v253, 11, v251
	v_add_u32_e32 v247, 0x20000, v246
	v_lshrrev_b32_e32 v253, 2, v250
	v_lshlrev_b32_e32 v253, 5, v253
	v_and_b32_e32 v248, 1, v250
	v_lshl_add_u32 v253, v248, 4, v253
	v_bfe_u32 v248, v250, 1, 1
	v_lshl_add_u32 v253, v248, 2, v253
	v_lshrrev_b32_e32 v248, 2, v252
	v_lshl_add_u32 v253, v248, 3, v253
	v_and_b32_e32 v248, 3, v252
	v_add_u32_e32 v253, v253, v248
	v_lshl_add_u32 v248, v253, 11, v251
	v_add_u32_e32 v249, 0x20000, v248
	v_lshl_add_u32 v128, v4, 11, v1
	v_mov_b32_e32 v128, v249
	v_lshl_add_u32 v130, v3, 11, v1
	v_mov_b32_e32 v253, v130
	v_mov_b32_e32 v130, v247
	v_bfe_i32 v1, v9, 27, 1
	v_lshrrev_b32_e32 v1, 22, v1
	v_add_u32_e32 v1, v0, v1
	v_and_b32_e32 v1, 0xfffffc00, v1
	v_sub_u32_e32 v0, v0, v1
	v_lshrrev_b32_e32 v1, 4, v0
	v_bitop3_b32 v1, v1, v0, 32 bitop3:0x6c
	v_ashrrev_i32_e32 v0, 31, v0
	v_lshrrev_b32_e32 v0, 26, v0
	v_add_u32_e32 v0, v1, v0
	v_ashrrev_i32_e32 v12, 6, v0
	v_ashrrev_i32_e32 v0, 31, v9
	v_lshrrev_b32_e32 v0, 26, v0
	v_add_u32_e32 v0, v9, v0
	v_ashrrev_i32_e32 v13, 6, v0
	v_lshlrev_b32_e32 v0, 3, v13
	s_add_u32 s2, s82, 0x200000
	v_and_b32_e32 v0, -16, v0
	s_addc_u32 s3, s83, 0
	v_add_u32_e32 v0, v12, v0
	v_and_b32_e32 v3, 3, v12
	s_ashr_i32 s31, s96, 31
	v_and_or_b32 v3, v0, s6, v3
	s_lshr_b32 s6, s31, 29
	s_add_i32 s6, s96, s6
	s_ashr_i32 s10, s7, 6
	s_ashr_i32 s8, s6, 3
	s_and_b32 s6, s6, -8
	s_ashr_i32 s12, s7, 8
	s_lshl_b32 s30, s10, 10
	s_sub_i32 s6, s96, s6
	s_cmp_lt_i32 s6, 0
	s_movk_i32 s33, 0x161
	s_cselect_b32 s9, s33, 0x160
	s_mul_i32 s6, s6, s9
	s_add_i32 s6, s6, s8
	s_mul_hi_i32 s8, s6, 0x2e8ba2e9
	s_lshr_b32 s9, s8, 31
	s_ashr_i32 s8, s8, 5
	s_add_i32 s8, s8, s9
	s_lshl_b32 s9, s8, 3
	s_mulk_i32 s8, 0xb0
	s_sub_i32 s8, s6, s8
	s_sext_i32_i16 s6, s8
	s_bfe_u32 s6, s6, 0x3001c
	s_add_i32 s11, s8, s6
	s_sext_i32_i16 s6, s11
	s_and_b32 s11, s11, 0xfff8
	v_lshrrev_b32_e32 v4, 2, v0
	v_lshlrev_b32_e32 v5, 1, v0
	s_sub_i32 s8, s8, s11
	v_and_b32_e32 v4, 4, v4
	v_and_b32_e32 v5, 24, v5
	s_sext_i32_i16 s8, s8
	v_or3_b32 v3, v3, v4, v5
	v_mul_i32_i24_e32 v5, 64, v12
	s_lshr_b32 s6, s6, 3
	s_add_i32 s22, s9, s8
	v_sub_u32_e32 v1, v1, v5
	s_ashr_i32 s23, s22, 31
	s_bfe_i64 s[14:15], s[6:7], 0x100000
	v_lshlrev_b32_e32 v4, 5, v13
	v_ashrrev_i16_sdwa v1, v2, sext(v1) dst_sel:DWORD dst_unused:UNUSED_PAD src0_sel:DWORD src1_sel:BYTE_0
	s_lshl_b64 s[8:9], s[22:23], 19
	s_lshl_b64 s[14:15], s[14:15], 19
	v_and_b32_e32 v4, 32, v4
	v_bfe_i32 v14, v1, 0, 16
	s_add_u32 s26, s2, s14
	v_add_lshl_u32 v1, v4, v14, 1
	s_addc_u32 s27, s3, s15
	s_add_i32 s23, s30, 0
	v_lshl_add_u32 v132, v3, 11, v1
	v_mov_b32_e32 v132, v248
	s_add_i32 m0, s23, 0x10000
	v_lshl_add_u32 v134, v0, 11, v1
	v_mov_b32_e32 v252, v134
	v_mov_b32_e32 v134, v246
	global_load_lds_dwordx4 v132, s[26:27]
	s_add_i32 m0, s23, 0x12000
	s_add_u32 s14, s26, 0x40000
	global_load_lds_dwordx4 v128, s[26:27]
	s_addc_u32 s15, s27, 0
	s_add_i32 m0, s23, 0x14000
	v_mov_b32_e32 v133, 0
	global_load_lds_dwordx4 v132, s[14:15]
	s_add_i32 m0, s23, 0x16000
	s_add_u32 s24, s90, s8
	s_addc_u32 s25, s91, s9
	s_add_i32 s34, s23, 0x2000
	global_load_lds_dwordx4 v128, s[14:15]
	s_mov_b32 m0, s23
	s_add_u32 s8, s24, 0x40000
	global_load_lds_dwordx4 v134, s[24:25]
	s_mov_b32 m0, s34
	s_addc_u32 s9, s25, 0
	s_add_i32 s35, s23, 0x4000
	global_load_lds_dwordx4 v130, s[24:25]
	s_mov_b32 m0, s35
	s_add_i32 s36, s23, 0x6000
	global_load_lds_dwordx4 v134, s[8:9]
	s_mov_b32 m0, s36
	v_mov_b32_e32 v129, v133
	global_load_lds_dwordx4 v130, s[8:9]
	v_mov_b32_e32 v135, v133
	v_mov_b32_e32 v131, v133
	s_cmp_eq_u32 s12, 1
	s_mov_b32 s37, 0
	v_lshl_add_u64 v[6:7], s[26:27], 0, v[132:133]
	v_lshl_add_u64 v[4:5], s[26:27], 0, v[128:129]
	v_lshl_add_u64 v[0:1], s[24:25], 0, v[134:135]
	s_cselect_b64 s[8:9], -1, 0
	s_cmp_lg_u32 s12, 1
	v_lshl_add_u64 v[2:3], s[24:25], 0, v[130:131]
	s_cbranch_scc1 .LBB0_211
	s_barrier
.LBB0_211:
	s_lshl_b32 s10, s10, 5
	s_and_b32 s16, s10, 0x60
	s_mov_b64 s[10:11], 0x80
	s_add_i32 m0, s23, 0x18000
	v_lshl_add_u64 v[6:7], v[6:7], 0, s[10:11]
	s_ashr_i32 s38, s86, 31
	s_lshl_b32 s13, s12, 13
	s_lshl_b32 s17, s16, 7
	s_waitcnt vmcnt(2)
	s_barrier
	global_load_lds_dwordx4 v[6:7], off
	v_lshl_add_u64 v[4:5], v[4:5], 0, s[10:11]
	s_add_i32 m0, s23, 0x1a000
	s_add_i32 s39, s23, 0x8000
	s_add_i32 s40, s23, 0xa000
	global_load_lds_dwordx4 v[4:5], off
	v_lshl_add_u64 v[0:1], v[0:1], 0, s[10:11]
	s_mov_b32 m0, s39
	s_add_u32 s14, s26, 0x40080
	global_load_lds_dwordx4 v[0:1], off
	v_lshl_add_u64 v[0:1], v[2:3], 0, s[10:11]
	s_mov_b32 m0, s40
	s_addc_u32 s15, s27, 0
	global_load_lds_dwordx4 v[0:1], off
	s_add_i32 m0, s23, 0x1c000
	v_lshl_add_u64 v[0:1], s[14:15], 0, v[132:133]
	global_load_lds_dwordx4 v[0:1], off
	v_lshl_add_u64 v[0:1], s[14:15], 0, v[128:129]
	s_add_i32 m0, s23, 0x1e000
	s_cmpk_lt_u32 s7, 0x100
	global_load_lds_dwordx4 v[0:1], off
	v_lshrrev_b32_e32 v1, 1, v9
	v_and_b32_e32 v1, 24, v1
	v_and_b32_e32 v0, 15, v9
	v_lshlrev_b32_e32 v2, 1, v1
	v_lshl_or_b32 v148, s12, 6, v0
	v_lshl_or_b32 v0, v0, 6, v2
	v_lshlrev_b32_e32 v2, 2, v9
	v_and_b32_e32 v2, 32, v2
	v_bitop3_b32 v3, v0, s13, v2 bitop3:0xde
	v_bitop3_b32 v149, v0, s17, v2 bitop3:0xde
	v_lshlrev_b32_e32 v0, 14, v13
	v_and_b32_e32 v0, 0xffff8000, v0
	v_or_b32_e32 v150, s16, v1
	v_lshl_add_u32 v0, v12, 11, v0
	v_and_b32_e32 v1, 1, v13
	v_lshl_or_b32 v0, v1, 6, v0
	v_lshl_add_u32 v136, v14, 1, v0
	v_lshlrev_b32_e32 v0, 14, v8
	v_and_b32_e32 v0, 0xffff8000, v0
	s_waitcnt vmcnt(6)
	v_lshl_add_u32 v0, v10, 11, v0
	v_and_b32_e32 v1, 1, v8
	s_cselect_b64 s[12:13], -1, 0
	v_lshl_or_b32 v0, v1, 6, v0
	s_add_i32 s42, 0, 0x10000
	s_add_i32 s43, 0, 0x14000
	s_sext_i32_i16 s45, s6
	s_mov_b32 s41, s86
	v_mov_b32_e32 v137, v133
	v_lshl_add_u32 v138, v11, 1, v0
	v_mov_b32_e32 v139, v133
	v_mov_b64_e32 v[140:141], 0xb00
	v_mov_b64_e32 v[142:143], 0xaff
	v_add_u32_e32 v151, s42, v149
	v_add_u32_e32 v152, s43, v149
	v_add_u32_e32 v153, 0, v3
	s_movk_i32 s44, 0x1600
	s_barrier
	v_sub_u32_e32 v136, v136, v252
	v_add_u32_e32 v136, v136, v134
	v_sub_u32_e32 v138, v138, v253
	v_add_u32_e32 v138, v138, v130
	v_and_b32_e32 v250, 63, v236
	v_and_b32_e32 v251, 15, v250
	v_lshrrev_b32_e32 v252, 4, v250
	v_and_b32_e32 v253, 7, v251
	v_xor_b32_e32 v252, v252, v253
	v_lshlrev_b32_e32 v252, 4, v252
	v_lshl_add_u32 v252, v251, 7, v252
	v_lshrrev_b32_e32 v250, 6, v236
	v_lshrrev_b32_e32 v251, 2, v250
	v_lshl_add_u32 v153, v251, 13, v252
	v_and_b32_e32 v251, 3, v250
	v_lshl_add_u32 v149, v251, 12, v252
	v_add_u32_e32 v151, s42, v149
	v_add_u32_e32 v152, s43, v149
	s_branch .LBB0_214

.LBB0_216:
	s_ashr_i32 s17, s16, 31
	s_lshl_b64 s[18:19], s[16:17], 19
	s_add_u32 s18, s90, s18
	s_addc_u32 s19, s91, s19
	s_and_b64 s[20:21], s[6:7], exec
	s_cselect_b32 s17, s19, s25
	s_cselect_b32 s46, s18, s24
	s_ashr_i32 s15, s14, 31
	s_lshl_b64 s[20:21], s[14:15], 19
	s_add_u32 s20, s2, s20
	s_addc_u32 s21, s3, s21
	s_and_b64 s[28:29], s[6:7], exec
	s_cselect_b32 s15, s21, s27
	s_cselect_b32 s47, s20, s26
	s_add_u32 s24, s24, 0x40080
	s_addc_u32 s25, s25, 0
	s_add_u32 s48, s26, 0x100
	v_mov_b32_e32 v0, 0
	s_addc_u32 s49, s27, 0
	s_mov_b32 s50, -2
	v_mov_b32_e32 v1, v0
	v_mov_b32_e32 v2, v0
	v_mov_b32_e32 v3, v0
	v_mov_b32_e32 v4, v0
	v_mov_b32_e32 v5, v0
	v_mov_b32_e32 v6, v0
	v_mov_b32_e32 v7, v0
	v_mov_b32_e32 v16, v0
	v_mov_b32_e32 v17, v0
	v_mov_b32_e32 v18, v0
	v_mov_b32_e32 v19, v0
	v_mov_b32_e32 v20, v0
	v_mov_b32_e32 v21, v0
	v_mov_b32_e32 v22, v0
	v_mov_b32_e32 v23, v0
	v_mov_b32_e32 v32, v0
	v_mov_b32_e32 v33, v0
	s_waitcnt lgkmcnt(0)
	v_mov_b32_e32 v34, v0
	v_mov_b32_e32 v35, v0
	v_mov_b32_e32 v36, v0
	v_mov_b32_e32 v37, v0
	v_mov_b32_e32 v38, v0
	v_mov_b32_e32 v39, v0
	v_mov_b32_e32 v48, v0
	v_mov_b32_e32 v49, v0
	v_mov_b32_e32 v50, v0
	v_mov_b32_e32 v51, v0
	v_mov_b32_e32 v52, v0
	v_mov_b32_e32 v53, v0
	v_mov_b32_e32 v54, v0
	v_mov_b32_e32 v55, v0
	v_mov_b32_e32 v8, v0
	v_mov_b32_e32 v9, v0
	v_mov_b32_e32 v10, v0
	v_mov_b32_e32 v11, v0
	v_mov_b32_e32 v12, v0
	v_mov_b32_e32 v13, v0
	v_mov_b32_e32 v14, v0
	v_mov_b32_e32 v15, v0
	v_mov_b32_e32 v24, v0
	v_mov_b32_e32 v25, v0
	v_mov_b32_e32 v26, v0
	v_mov_b32_e32 v27, v0
	v_mov_b32_e32 v28, v0
	v_mov_b32_e32 v29, v0
	v_mov_b32_e32 v30, v0
	v_mov_b32_e32 v31, v0
	v_mov_b32_e32 v40, v0
	v_mov_b32_e32 v41, v0
	v_mov_b32_e32 v42, v0
	v_mov_b32_e32 v43, v0
	v_mov_b32_e32 v44, v0
	v_mov_b32_e32 v45, v0
	v_mov_b32_e32 v46, v0
	v_mov_b32_e32 v47, v0
	v_mov_b32_e32 v56, v0
	v_mov_b32_e32 v57, v0
	v_mov_b32_e32 v58, v0
	v_mov_b32_e32 v59, v0
	v_mov_b32_e32 v60, v0
	v_mov_b32_e32 v61, v0
	v_mov_b32_e32 v62, v0
	v_mov_b32_e32 v63, v0
	v_mov_b32_e32 v64, v0
	v_mov_b32_e32 v65, v0
	v_mov_b32_e32 v66, v0
	v_mov_b32_e32 v67, v0
	v_mov_b32_e32 v68, v0
	v_mov_b32_e32 v69, v0
	v_mov_b32_e32 v70, v0
	v_mov_b32_e32 v71, v0
	v_mov_b32_e32 v80, v0
	v_mov_b32_e32 v81, v0
	v_mov_b32_e32 v82, v0
	v_mov_b32_e32 v83, v0
	v_mov_b32_e32 v84, v0
	v_mov_b32_e32 v85, v0
	v_mov_b32_e32 v86, v0
	v_mov_b32_e32 v87, v0
	v_mov_b32_e32 v96, v0
	v_mov_b32_e32 v97, v0
	v_mov_b32_e32 v98, v0
	v_mov_b32_e32 v99, v0
	v_mov_b32_e32 v100, v0
	v_mov_b32_e32 v101, v0
	v_mov_b32_e32 v102, v0
	v_mov_b32_e32 v103, v0
	v_mov_b32_e32 v112, v0
	v_mov_b32_e32 v113, v0
	v_mov_b32_e32 v114, v0
	v_mov_b32_e32 v115, v0
	v_mov_b32_e32 v116, v0
	v_mov_b32_e32 v117, v0
	v_mov_b32_e32 v118, v0
	v_mov_b32_e32 v119, v0
	v_mov_b32_e32 v72, v0
	v_mov_b32_e32 v73, v0
	v_mov_b32_e32 v74, v0
	v_mov_b32_e32 v75, v0
	v_mov_b32_e32 v76, v0
	v_mov_b32_e32 v77, v0
	v_mov_b32_e32 v78, v0
	v_mov_b32_e32 v79, v0
	v_mov_b32_e32 v88, v0
	v_mov_b32_e32 v89, v0
	v_mov_b32_e32 v90, v0
	v_mov_b32_e32 v91, v0
	v_mov_b32_e32 v92, v0
	v_mov_b32_e32 v93, v0
	v_mov_b32_e32 v94, v0
	v_mov_b32_e32 v95, v0
	v_mov_b32_e32 v104, v0
	v_mov_b32_e32 v105, v0
	v_mov_b32_e32 v106, v0
	v_mov_b32_e32 v107, v0
	v_mov_b32_e32 v108, v0
	v_mov_b32_e32 v109, v0
	v_mov_b32_e32 v110, v0
	v_mov_b32_e32 v111, v0
	v_mov_b32_e32 v120, v0
	v_mov_b32_e32 v121, v0
	v_mov_b32_e32 v122, v0
	v_mov_b32_e32 v123, v0
	v_mov_b32_e32 v124, v0
	v_mov_b32_e32 v125, v0
	v_mov_b32_e32 v126, v0
	v_mov_b32_e32 v127, v0
	v_xor_b32_e32 v246, 64, v153
	v_xor_b32_e32 v247, 64, v149
	v_add_u32_e32 v248, s42, v247
	v_add_u32_e32 v249, s43, v247
.LBB0_217:
	ds_read_b128 v[144:147], v151
	ds_read_b128 v[154:157], v248
	ds_read_b128 v[158:161], v151 offset:2048
	ds_read_b128 v[162:165], v248 offset:2048
	ds_read_b128 v[166:169], v152
	ds_read_b128 v[170:173], v249
	ds_read_b128 v[174:177], v152 offset:2048
	ds_read_b128 v[178:181], v249 offset:2048
	s_add_u32 s26, s24, 0xfffc0080
	s_addc_u32 s27, s25, -1
	s_cmp_eq_u32 s50, 12
	s_cselect_b32 s29, s17, s27
	s_cselect_b32 s28, s46, s26
	s_cselect_b32 s27, s15, s49
	s_cselect_b32 s26, s47, s48
	v_lshl_add_u64 v[214:215], s[24:25], 0, v[136:137]
	s_add_i32 m0, s23, 0xc000
	ds_read_b128 v[182:185], v153
	ds_read_b128 v[186:189], v246
	ds_read_b128 v[190:193], v153 offset:2048
	ds_read_b128 v[194:197], v246 offset:2048
	ds_read_b128 v[198:201], v153 offset:4096
	ds_read_b128 v[202:205], v246 offset:4096
	ds_read_b128 v[206:209], v153 offset:6144
	ds_read_b128 v[210:213], v246 offset:6144
	global_load_lds_dwordx4 v[214:215], off
	v_lshl_add_u64 v[214:215], s[24:25], 0, v[138:139]
	s_add_i32 m0, s23, 0xe000
	s_nop 0
	global_load_lds_dwordx4 v[214:215], off
	s_waitcnt vmcnt(8)
	s_waitcnt lgkmcnt(0)
	s_barrier
	s_setprio 0
	s_waitcnt lgkmcnt(0)
	v_mfma_f32_16x16x32_bf16 v[124:127], v[144:147], v[182:185], v[124:127]
	v_mfma_f32_16x16x32_bf16 v[120:123], v[158:161], v[182:185], v[120:123]
	v_mfma_f32_16x16x32_bf16 v[108:111], v[144:147], v[190:193], v[108:111]
	v_mfma_f32_16x16x32_bf16 v[104:107], v[158:161], v[190:193], v[104:107]
	v_mfma_f32_16x16x32_bf16 v[92:95], v[144:147], v[198:201], v[92:95]
	v_mfma_f32_16x16x32_bf16 v[88:91], v[158:161], v[198:201], v[88:91]
	v_mfma_f32_16x16x32_bf16 v[76:79], v[144:147], v[206:209], v[76:79]
	v_mfma_f32_16x16x32_bf16 v[72:75], v[158:161], v[206:209], v[72:75]
	v_mfma_f32_16x16x32_bf16 v[124:127], v[154:157], v[186:189], v[124:127]
	v_mfma_f32_16x16x32_bf16 v[120:123], v[162:165], v[186:189], v[120:123]
	v_mfma_f32_16x16x32_bf16 v[108:111], v[154:157], v[194:197], v[108:111]
	v_mfma_f32_16x16x32_bf16 v[104:107], v[162:165], v[194:197], v[104:107]
	v_mfma_f32_16x16x32_bf16 v[92:95], v[154:157], v[202:205], v[92:95]
	v_mfma_f32_16x16x32_bf16 v[88:91], v[162:165], v[202:205], v[88:91]
	v_mfma_f32_16x16x32_bf16 v[76:79], v[154:157], v[210:213], v[76:79]
	v_mfma_f32_16x16x32_bf16 v[72:75], v[162:165], v[210:213], v[72:75]
	s_setprio 0
	s_setprio 0
	v_mfma_f32_16x16x32_bf16 v[116:119], v[166:169], v[182:185], v[116:119]
	v_mfma_f32_16x16x32_bf16 v[112:115], v[174:177], v[182:185], v[112:115]
	v_mfma_f32_16x16x32_bf16 v[100:103], v[166:169], v[190:193], v[100:103]
	v_mfma_f32_16x16x32_bf16 v[96:99], v[174:177], v[190:193], v[96:99]
	v_mfma_f32_16x16x32_bf16 v[84:87], v[166:169], v[198:201], v[84:87]
	v_mfma_f32_16x16x32_bf16 v[80:83], v[174:177], v[198:201], v[80:83]
	v_mfma_f32_16x16x32_bf16 v[68:71], v[166:169], v[206:209], v[68:71]
	v_mfma_f32_16x16x32_bf16 v[64:67], v[174:177], v[206:209], v[64:67]
	v_mfma_f32_16x16x32_bf16 v[116:119], v[170:173], v[186:189], v[116:119]
	v_mfma_f32_16x16x32_bf16 v[112:115], v[178:181], v[186:189], v[112:115]
	v_mfma_f32_16x16x32_bf16 v[100:103], v[170:173], v[194:197], v[100:103]
	v_mfma_f32_16x16x32_bf16 v[96:99], v[178:181], v[194:197], v[96:99]
	v_mfma_f32_16x16x32_bf16 v[84:87], v[170:173], v[202:205], v[84:87]
	v_mfma_f32_16x16x32_bf16 v[80:83], v[178:181], v[202:205], v[80:83]
	v_mfma_f32_16x16x32_bf16 v[68:71], v[170:173], v[210:213], v[68:71]
	v_mfma_f32_16x16x32_bf16 v[64:67], v[178:181], v[210:213], v[64:67]
	s_setprio 0
	s_barrier
	s_add_i32 s51, s42, s30
	v_lshl_add_u64 v[214:215], s[26:27], 0, v[132:133]
	s_mov_b32 m0, s51
	ds_read_b128 v[182:185], v153 offset:16384
	ds_read_b128 v[186:189], v246 offset:16384
	ds_read_b128 v[190:193], v153 offset:18432
	ds_read_b128 v[194:197], v246 offset:18432
	ds_read_b128 v[198:201], v153 offset:20480
	ds_read_b128 v[202:205], v246 offset:20480
	ds_read_b128 v[206:209], v153 offset:22528
	ds_read_b128 v[210:213], v246 offset:22528
	global_load_lds_dwordx4 v[214:215], off
	s_add_i32 m0, s51, 0x2000
	s_add_u32 s52, s26, 0x40000
	v_lshl_add_u64 v[216:217], s[26:27], 0, v[128:129]
	s_addc_u32 s53, s27, 0
	s_add_i32 s51, s43, s30
	global_load_lds_dwordx4 v[216:217], off
	v_lshl_add_u64 v[218:219], s[52:53], 0, v[132:133]
	s_mov_b32 m0, s51
	v_lshl_add_u64 v[220:221], s[28:29], 0, v[130:131]
	global_load_lds_dwordx4 v[218:219], off
	v_lshl_add_u64 v[218:219], s[52:53], 0, v[128:129]
	s_add_i32 m0, s51, 0x2000
	s_nop 0
	global_load_lds_dwordx4 v[218:219], off
	v_lshl_add_u64 v[218:219], s[28:29], 0, v[134:135]
	s_mov_b32 m0, s23
	s_nop 0
	global_load_lds_dwordx4 v[218:219], off
	s_mov_b32 m0, s34
	s_nop 0
	global_load_lds_dwordx4 v[220:221], off
	s_waitcnt vmcnt(8)
	s_waitcnt lgkmcnt(0)
	s_barrier
	s_setprio 0
	s_waitcnt lgkmcnt(0)
	v_mfma_f32_16x16x32_bf16 v[60:63], v[144:147], v[182:185], v[60:63]
	v_mfma_f32_16x16x32_bf16 v[56:59], v[158:161], v[182:185], v[56:59]
	v_mfma_f32_16x16x32_bf16 v[44:47], v[144:147], v[190:193], v[44:47]
	v_mfma_f32_16x16x32_bf16 v[40:43], v[158:161], v[190:193], v[40:43]
	v_mfma_f32_16x16x32_bf16 v[28:31], v[144:147], v[198:201], v[28:31]
	v_mfma_f32_16x16x32_bf16 v[24:27], v[158:161], v[198:201], v[24:27]
	v_mfma_f32_16x16x32_bf16 v[12:15], v[144:147], v[206:209], v[12:15]
	v_mfma_f32_16x16x32_bf16 v[8:11], v[158:161], v[206:209], v[8:11]
	v_mfma_f32_16x16x32_bf16 v[60:63], v[154:157], v[186:189], v[60:63]
	v_mfma_f32_16x16x32_bf16 v[56:59], v[162:165], v[186:189], v[56:59]
	v_mfma_f32_16x16x32_bf16 v[44:47], v[154:157], v[194:197], v[44:47]
	v_mfma_f32_16x16x32_bf16 v[40:43], v[162:165], v[194:197], v[40:43]
	v_mfma_f32_16x16x32_bf16 v[28:31], v[154:157], v[202:205], v[28:31]
	v_mfma_f32_16x16x32_bf16 v[24:27], v[162:165], v[202:205], v[24:27]
	v_mfma_f32_16x16x32_bf16 v[12:15], v[154:157], v[210:213], v[12:15]
	v_mfma_f32_16x16x32_bf16 v[8:11], v[162:165], v[210:213], v[8:11]
	s_setprio 0
	s_setprio 0
	v_mfma_f32_16x16x32_bf16 v[52:55], v[166:169], v[182:185], v[52:55]
	v_mfma_f32_16x16x32_bf16 v[48:51], v[174:177], v[182:185], v[48:51]
	v_mfma_f32_16x16x32_bf16 v[36:39], v[166:169], v[190:193], v[36:39]
	v_mfma_f32_16x16x32_bf16 v[32:35], v[174:177], v[190:193], v[32:35]
	v_mfma_f32_16x16x32_bf16 v[20:23], v[166:169], v[198:201], v[20:23]
	v_mfma_f32_16x16x32_bf16 v[16:19], v[174:177], v[198:201], v[16:19]
	v_mfma_f32_16x16x32_bf16 v[4:7], v[166:169], v[206:209], v[4:7]
	v_mfma_f32_16x16x32_bf16 v[0:3], v[174:177], v[206:209], v[0:3]
	v_mfma_f32_16x16x32_bf16 v[52:55], v[170:173], v[186:189], v[52:55]
	v_mfma_f32_16x16x32_bf16 v[48:51], v[178:181], v[186:189], v[48:51]
	v_mfma_f32_16x16x32_bf16 v[36:39], v[170:173], v[194:197], v[36:39]
	v_mfma_f32_16x16x32_bf16 v[32:35], v[178:181], v[194:197], v[32:35]
	v_mfma_f32_16x16x32_bf16 v[20:23], v[170:173], v[202:205], v[20:23]
	v_mfma_f32_16x16x32_bf16 v[16:19], v[178:181], v[202:205], v[16:19]
	v_mfma_f32_16x16x32_bf16 v[4:7], v[170:173], v[210:213], v[4:7]
	v_mfma_f32_16x16x32_bf16 v[0:3], v[178:181], v[210:213], v[0:3]
	s_setprio 0
	s_barrier
	s_add_i32 s51, 0, 0x18000
	s_add_i32 s52, 0, 0x1c000
	v_add_u32_e32 v162, s51, v149
	v_add_u32_e32 v250, s51, v247
	v_add_u32_e32 v178, s52, v149
	v_add_u32_e32 v251, s52, v247
	ds_read_b128 v[144:147], v162
	ds_read_b128 v[154:157], v250
	ds_read_b128 v[158:161], v162 offset:2048
	ds_read_b128 v[162:165], v250 offset:2048
	ds_read_b128 v[166:169], v178
	ds_read_b128 v[170:173], v251
	ds_read_b128 v[174:177], v178 offset:2048
	ds_read_b128 v[178:181], v251 offset:2048
	s_add_u32 s28, s28, 0x40000
	s_addc_u32 s29, s29, 0
	s_mov_b32 m0, s35
	v_lshl_add_u64 v[222:223], s[28:29], 0, v[134:135]
	ds_read_b128 v[182:185], v153 offset:32768
	ds_read_b128 v[186:189], v246 offset:32768
	ds_read_b128 v[190:193], v153 offset:34816
	ds_read_b128 v[194:197], v246 offset:34816
	ds_read_b128 v[198:201], v153 offset:36864
	ds_read_b128 v[202:205], v246 offset:36864
	ds_read_b128 v[206:209], v153 offset:38912
	ds_read_b128 v[210:213], v246 offset:38912
	global_load_lds_dwordx4 v[222:223], off
	v_lshl_add_u64 v[222:223], s[28:29], 0, v[130:131]
	s_mov_b32 m0, s36
	s_nop 0
	global_load_lds_dwordx4 v[222:223], off
	s_waitcnt vmcnt(8)
	s_waitcnt lgkmcnt(0)
	s_barrier
	s_setprio 0
	s_waitcnt lgkmcnt(0)
	v_mfma_f32_16x16x32_bf16 v[124:127], v[144:147], v[182:185], v[124:127]
	v_mfma_f32_16x16x32_bf16 v[120:123], v[158:161], v[182:185], v[120:123]
	v_mfma_f32_16x16x32_bf16 v[108:111], v[144:147], v[190:193], v[108:111]
	v_mfma_f32_16x16x32_bf16 v[104:107], v[158:161], v[190:193], v[104:107]
	v_mfma_f32_16x16x32_bf16 v[92:95], v[144:147], v[198:201], v[92:95]
	v_mfma_f32_16x16x32_bf16 v[88:91], v[158:161], v[198:201], v[88:91]
	v_mfma_f32_16x16x32_bf16 v[76:79], v[144:147], v[206:209], v[76:79]
	v_mfma_f32_16x16x32_bf16 v[72:75], v[158:161], v[206:209], v[72:75]
	v_mfma_f32_16x16x32_bf16 v[124:127], v[154:157], v[186:189], v[124:127]
	v_mfma_f32_16x16x32_bf16 v[120:123], v[162:165], v[186:189], v[120:123]
	v_mfma_f32_16x16x32_bf16 v[108:111], v[154:157], v[194:197], v[108:111]
	v_mfma_f32_16x16x32_bf16 v[104:107], v[162:165], v[194:197], v[104:107]
	v_mfma_f32_16x16x32_bf16 v[92:95], v[154:157], v[202:205], v[92:95]
	v_mfma_f32_16x16x32_bf16 v[88:91], v[162:165], v[202:205], v[88:91]
	v_mfma_f32_16x16x32_bf16 v[76:79], v[154:157], v[210:213], v[76:79]
	v_mfma_f32_16x16x32_bf16 v[72:75], v[162:165], v[210:213], v[72:75]
	s_setprio 0
	s_setprio 0
	v_mfma_f32_16x16x32_bf16 v[116:119], v[166:169], v[182:185], v[116:119]
	v_mfma_f32_16x16x32_bf16 v[112:115], v[174:177], v[182:185], v[112:115]
	v_mfma_f32_16x16x32_bf16 v[100:103], v[166:169], v[190:193], v[100:103]
	v_mfma_f32_16x16x32_bf16 v[96:99], v[174:177], v[190:193], v[96:99]
	v_mfma_f32_16x16x32_bf16 v[84:87], v[166:169], v[198:201], v[84:87]
	v_mfma_f32_16x16x32_bf16 v[80:83], v[174:177], v[198:201], v[80:83]
	v_mfma_f32_16x16x32_bf16 v[68:71], v[166:169], v[206:209], v[68:71]
	v_mfma_f32_16x16x32_bf16 v[64:67], v[174:177], v[206:209], v[64:67]
	v_mfma_f32_16x16x32_bf16 v[116:119], v[170:173], v[186:189], v[116:119]
	v_mfma_f32_16x16x32_bf16 v[112:115], v[178:181], v[186:189], v[112:115]
	v_mfma_f32_16x16x32_bf16 v[100:103], v[170:173], v[194:197], v[100:103]
	v_mfma_f32_16x16x32_bf16 v[96:99], v[178:181], v[194:197], v[96:99]
	v_mfma_f32_16x16x32_bf16 v[84:87], v[170:173], v[202:205], v[84:87]
	v_mfma_f32_16x16x32_bf16 v[80:83], v[178:181], v[202:205], v[80:83]
	v_mfma_f32_16x16x32_bf16 v[68:71], v[170:173], v[210:213], v[68:71]
	v_mfma_f32_16x16x32_bf16 v[64:67], v[178:181], v[210:213], v[64:67]
	s_setprio 0
	s_barrier
	s_add_i32 s28, s51, s30
	v_lshl_add_u64 v[214:215], v[214:215], 0, s[10:11]
	s_mov_b32 m0, s28
	ds_read_b128 v[182:185], v153 offset:49152
	ds_read_b128 v[186:189], v246 offset:49152
	ds_read_b128 v[190:193], v153 offset:51200
	ds_read_b128 v[194:197], v246 offset:51200
	ds_read_b128 v[198:201], v153 offset:53248
	ds_read_b128 v[202:205], v246 offset:53248
	ds_read_b128 v[206:209], v153 offset:55296
	ds_read_b128 v[210:213], v246 offset:55296
	global_load_lds_dwordx4 v[214:215], off
	s_add_i32 m0, s28, 0x2000
	s_add_u32 s26, s26, 0x40080
	v_lshl_add_u64 v[214:215], v[216:217], 0, s[10:11]
	s_addc_u32 s27, s27, 0
	s_add_i32 s28, s52, s30
	global_load_lds_dwordx4 v[214:215], off
	v_lshl_add_u64 v[214:215], s[26:27], 0, v[132:133]
	s_mov_b32 m0, s28
	s_nop 0
	global_load_lds_dwordx4 v[214:215], off
	v_lshl_add_u64 v[214:215], s[26:27], 0, v[128:129]
	s_add_i32 m0, s28, 0x2000
	s_nop 0
	global_load_lds_dwordx4 v[214:215], off
	v_lshl_add_u64 v[214:215], v[218:219], 0, s[10:11]
	s_mov_b32 m0, s39
	s_nop 0
	global_load_lds_dwordx4 v[214:215], off
	v_lshl_add_u64 v[214:215], v[220:221], 0, s[10:11]
	s_mov_b32 m0, s40
	s_nop 0
	global_load_lds_dwordx4 v[214:215], off
	s_waitcnt vmcnt(8)
	s_waitcnt lgkmcnt(0)
	s_barrier
	s_setprio 0
	s_waitcnt lgkmcnt(0)
	v_mfma_f32_16x16x32_bf16 v[60:63], v[144:147], v[182:185], v[60:63]
	v_mfma_f32_16x16x32_bf16 v[56:59], v[158:161], v[182:185], v[56:59]
	v_mfma_f32_16x16x32_bf16 v[44:47], v[144:147], v[190:193], v[44:47]
	v_mfma_f32_16x16x32_bf16 v[40:43], v[158:161], v[190:193], v[40:43]
	v_mfma_f32_16x16x32_bf16 v[28:31], v[144:147], v[198:201], v[28:31]
	v_mfma_f32_16x16x32_bf16 v[24:27], v[158:161], v[198:201], v[24:27]
	v_mfma_f32_16x16x32_bf16 v[12:15], v[144:147], v[206:209], v[12:15]
	v_mfma_f32_16x16x32_bf16 v[8:11], v[158:161], v[206:209], v[8:11]
	v_mfma_f32_16x16x32_bf16 v[60:63], v[154:157], v[186:189], v[60:63]
	v_mfma_f32_16x16x32_bf16 v[56:59], v[162:165], v[186:189], v[56:59]
	v_mfma_f32_16x16x32_bf16 v[44:47], v[154:157], v[194:197], v[44:47]
	v_mfma_f32_16x16x32_bf16 v[40:43], v[162:165], v[194:197], v[40:43]
	v_mfma_f32_16x16x32_bf16 v[28:31], v[154:157], v[202:205], v[28:31]
	v_mfma_f32_16x16x32_bf16 v[24:27], v[162:165], v[202:205], v[24:27]
	v_mfma_f32_16x16x32_bf16 v[12:15], v[154:157], v[210:213], v[12:15]
	v_mfma_f32_16x16x32_bf16 v[8:11], v[162:165], v[210:213], v[8:11]
	s_setprio 0
	s_setprio 0
	v_mfma_f32_16x16x32_bf16 v[52:55], v[166:169], v[182:185], v[52:55]
	v_mfma_f32_16x16x32_bf16 v[48:51], v[174:177], v[182:185], v[48:51]
	v_mfma_f32_16x16x32_bf16 v[36:39], v[166:169], v[190:193], v[36:39]
	v_mfma_f32_16x16x32_bf16 v[32:35], v[174:177], v[190:193], v[32:35]
	v_mfma_f32_16x16x32_bf16 v[20:23], v[166:169], v[198:201], v[20:23]
	v_mfma_f32_16x16x32_bf16 v[16:19], v[174:177], v[198:201], v[16:19]
	v_mfma_f32_16x16x32_bf16 v[4:7], v[166:169], v[206:209], v[4:7]
	v_mfma_f32_16x16x32_bf16 v[0:3], v[174:177], v[206:209], v[0:3]
	v_mfma_f32_16x16x32_bf16 v[52:55], v[170:173], v[186:189], v[52:55]
	v_mfma_f32_16x16x32_bf16 v[48:51], v[178:181], v[186:189], v[48:51]
	v_mfma_f32_16x16x32_bf16 v[36:39], v[170:173], v[194:197], v[36:39]
	v_mfma_f32_16x16x32_bf16 v[32:35], v[178:181], v[194:197], v[32:35]
	v_mfma_f32_16x16x32_bf16 v[20:23], v[170:173], v[202:205], v[20:23]
	v_mfma_f32_16x16x32_bf16 v[16:19], v[178:181], v[202:205], v[16:19]
	v_mfma_f32_16x16x32_bf16 v[4:7], v[170:173], v[210:213], v[4:7]
	v_mfma_f32_16x16x32_bf16 v[0:3], v[178:181], v[210:213], v[0:3]
	s_setprio 0
	s_barrier
	s_add_i32 s50, s50, 2
	s_add_u32 s24, s24, 0x100
	s_addc_u32 s25, s25, 0
	s_add_u32 s48, s48, 0x100
	s_addc_u32 s49, s49, 0
	s_cmp_gt_u32 s50, 13
	s_cbranch_scc0 .LBB0_217
	s_and_b64 vcc, exec, s[12:13]
	s_cbranch_vccz .LBB0_220
	s_barrier

.LBB0_278:
	s_cmp_lt_i32 s84, 4
	s_cselect_b64 s[2:3], -1, 0
	s_and_b64 s[4:5], s[2:3], s[6:7]
	s_andn2_b64 vcc, exec, s[4:5]
	s_cbranch_vccnz .LBB0_303
	v_mov_b32_e32 v9, v236
	s_cmpk_gt_i32 s96, 0x1ff
	s_nop 0
	v_readfirstlane_b32 s6, v9
	s_cbranch_scc1 .LBB0_303
	v_lshlrev_b32_e32 v0, 4, v9
	v_add_u32_e32 v1, 0x2000, v0
	v_ashrrev_i32_e32 v2, 31, v1
	v_lshrrev_b32_e32 v2, 22, v2
	v_add_u32_e32 v2, v1, v2
	v_ashrrev_i32_e32 v8, 10, v2
	v_mul_i32_i24_e32 v2, 0x400, v8
	v_sub_u32_e32 v1, v1, v2
	v_lshrrev_b32_e32 v2, 4, v1
	v_bitop3_b32 v1, v2, v1, 32 bitop3:0x6c
	v_ashrrev_i32_e32 v2, 31, v1
	v_lshrrev_b32_e32 v2, 26, v2
	v_add_u32_e32 v2, v1, v2
	v_lshlrev_b32_e32 v3, 3, v8
	v_ashrrev_i32_e32 v10, 6, v2
	v_and_b32_e32 v3, -16, v3
	v_add_u32_e32 v3, v10, v3
	v_and_b32_e32 v4, 3, v10
	s_mov_b32 s10, 0xffffe0
	v_lshrrev_b32_e32 v5, 2, v3
	v_lshlrev_b32_e32 v6, 1, v3
	v_and_b32_e32 v2, 0xc0, v2
	v_and_or_b32 v4, v3, s10, v4
	v_and_b32_e32 v5, 4, v5
	v_and_b32_e32 v6, 24, v6
	v_sub_u32_e32 v1, v1, v2
	v_mov_b32_e32 v2, 1
	v_or3_b32 v4, v4, v5, v6
	v_lshlrev_b32_e32 v5, 5, v8
	v_ashrrev_i16_sdwa v1, v2, sext(v1) dst_sel:DWORD dst_unused:UNUSED_PAD src0_sel:DWORD src1_sel:BYTE_0
	s_movk_i32 s8, 0xb00
	v_and_b32_e32 v11, 32, v5
	v_bfe_i32 v12, v1, 0, 16
	v_mul_u32_u24_e32 v4, 0xb00, v4
	v_add_u32_e32 v1, v11, v12
	v_mul_lo_u32 v3, v3, s8
	v_lshrrev_b32_e32 v250, 6, v236
	v_and_b32_e32 v251, 63, v236
	v_lshrrev_b32_e32 v252, 3, v251
	v_and_b32_e32 v251, 7, v251
	v_xor_b32_e32 v251, v251, v252
	v_lshlrev_b32_e32 v251, 4, v251
	v_lshl_add_u32 v253, v250, 3, v252
	v_mul_u32_u24_e32 v246, 0x1600, v253
	v_add_u32_e32 v246, v246, v251
	v_add_u32_e32 v247, 0x58000, v246
	v_lshrrev_b32_e32 v253, 2, v250
	v_lshlrev_b32_e32 v253, 5, v253
	v_and_b32_e32 v248, 1, v250
	v_lshl_add_u32 v253, v248, 4, v253
	v_bfe_u32 v248, v250, 1, 1
	v_lshl_add_u32 v253, v248, 2, v253
	v_lshrrev_b32_e32 v248, 2, v252
	v_lshl_add_u32 v253, v248, 3, v253
	v_and_b32_e32 v248, 3, v252
	v_add_u32_e32 v253, v253, v248
	v_mul_u32_u24_e32 v248, 0x1600, v253
	v_add_u32_e32 v248, v248, v251
	v_add_u32_e32 v249, 0x58000, v248
	v_add_lshl_u32 v128, v4, v1, 1
	v_mov_b32_e32 v128, v249
	v_add_lshl_u32 v130, v1, v3, 1
	v_mov_b32_e32 v253, v130
	v_mov_b32_e32 v130, v247
	v_bfe_i32 v1, v9, 27, 1
	v_lshrrev_b32_e32 v1, 22, v1
	v_add_u32_e32 v1, v0, v1
	v_and_b32_e32 v1, 0xfffffc00, v1
	v_sub_u32_e32 v0, v0, v1
	v_lshrrev_b32_e32 v1, 4, v0
	v_bitop3_b32 v1, v1, v0, 32 bitop3:0x6c
	v_ashrrev_i32_e32 v0, 31, v0
	v_lshrrev_b32_e32 v0, 26, v0
	v_add_u32_e32 v0, v1, v0
	v_ashrrev_i32_e32 v13, 6, v0
	v_ashrrev_i32_e32 v0, 31, v9
	v_lshrrev_b32_e32 v0, 26, v0
	v_add_u32_e32 v0, v9, v0
	v_ashrrev_i32_e32 v14, 6, v0
	v_lshlrev_b32_e32 v0, 3, v14
	s_add_u32 s2, s82, 0xd00000
	v_and_b32_e32 v0, -16, v0
	s_addc_u32 s3, s83, 0
	v_add_u32_e32 v0, v13, v0
	v_and_b32_e32 v3, 3, v13
	s_ashr_i32 s27, s96, 31
	v_and_or_b32 v3, v0, s10, v3
	s_lshr_b32 s10, s27, 29
	s_add_i32 s10, s96, s10
	s_and_b32 s11, s10, -8
	s_ashr_i32 s9, s6, 6
	s_sub_i32 s11, s96, s11
	s_ashr_i32 s7, s6, 8
	s_lshl_b32 s26, s9, 10
	s_lshl_b32 s13, s11, 6
	s_ashr_i32 s10, s10, 3
	s_mul_i32 s12, s11, 0x41
	s_cmp_lt_i32 s11, 0
	s_cselect_b32 s11, s12, s13
	s_add_i32 s10, s11, s10
	s_ashr_i32 s11, s10, 31
	s_lshr_b32 s11, s11, 27
	s_add_i32 s11, s10, s11
	s_ashr_i32 s12, s11, 5
	s_andn2_b32 s11, s11, 31
	s_sub_i32 s10, s10, s11
	s_bfe_i32 s11, s10, 0x80000
	s_bfe_u32 s11, s11, 0x3000c
	v_lshrrev_b32_e32 v4, 2, v0
	v_lshlrev_b32_e32 v5, 1, v0
	s_add_i32 s11, s10, s11
	v_and_b32_e32 v4, 4, v4
	v_and_b32_e32 v5, 24, v5
	s_bfe_i32 s13, s11, 0x80000
	s_and_b32 s11, s11, 0xf8
	v_or3_b32 v3, v3, v4, v5
	v_lshlrev_b32_e32 v4, 5, v14
	s_sub_i32 s10, s10, s11
	v_and_b32_e32 v15, 32, v4
	v_mul_i32_i24_e32 v4, 64, v13
	s_lshl_b32 s12, s12, 3
	s_sext_i32_i16 s13, s13
	s_sext_i32_i8 s10, s10
	v_sub_u32_e32 v1, v1, v4
	s_add_i32 s44, s12, s10
	s_ashr_i32 s10, s13, 3
	v_ashrrev_i16_sdwa v1, v2, sext(v1) dst_sel:DWORD dst_unused:UNUSED_PAD src0_sel:DWORD src1_sel:BYTE_0
	s_lshr_b32 s14, s13, 3
	s_mul_hi_i32 s11, s10, 0x160000
	s_mul_i32 s10, s10, 0x160000
	v_bfe_i32 v16, v1, 0, 16
	s_add_u32 s20, s2, s10
	v_mul_u32_u24_e32 v3, 0xb00, v3
	v_add_u32_e32 v1, v15, v16
	s_addc_u32 s21, s3, s11
	s_add_i32 s28, s26, 0
	v_add_lshl_u32 v132, v3, v1, 1
	v_mov_b32_e32 v132, v248
	s_add_i32 m0, s28, 0x10000
	s_mul_i32 s15, s44, 0x160000
	global_load_lds_dwordx4 v132, s[20:21]
	s_add_i32 m0, s28, 0x12000
	s_add_u32 s10, s20, 0xb0000
	global_load_lds_dwordx4 v128, s[20:21]
	s_addc_u32 s11, s21, 0
	s_add_i32 m0, s28, 0x14000
	s_mul_hi_i32 s12, s44, 0x160000
	global_load_lds_dwordx4 v132, s[10:11]
	s_add_i32 m0, s28, 0x16000
	s_add_u32 s18, s92, s15
	v_mul_lo_u32 v0, v0, s8
	s_addc_u32 s19, s93, s12
	s_add_i32 s29, s28, 0x2000
	v_add_lshl_u32 v134, v1, v0, 1
	v_mov_b32_e32 v252, v134
	v_mov_b32_e32 v134, v246
	global_load_lds_dwordx4 v128, s[10:11]
	s_mov_b32 m0, s28
	s_add_u32 s10, s18, 0xb0000
	global_load_lds_dwordx4 v134, s[18:19]
	s_mov_b32 m0, s29
	s_addc_u32 s11, s19, 0
	s_add_i32 s30, s28, 0x4000
	global_load_lds_dwordx4 v130, s[18:19]
	s_mov_b32 m0, s30
	s_add_i32 s31, s28, 0x6000
	global_load_lds_dwordx4 v134, s[10:11]
	s_mov_b32 m0, s31
	v_mov_b32_e32 v133, 0
	global_load_lds_dwordx4 v130, s[10:11]
	v_mov_b32_e32 v129, v133
	v_mov_b32_e32 v135, v133
	v_mov_b32_e32 v131, v133
	s_cmp_eq_u32 s7, 1
	s_mov_b32 s33, 0
	v_lshl_add_u64 v[6:7], s[20:21], 0, v[132:133]
	v_lshl_add_u64 v[4:5], s[20:21], 0, v[128:129]
	v_lshl_add_u64 v[0:1], s[18:19], 0, v[134:135]
	s_cselect_b64 s[10:11], -1, 0
	s_cmp_lg_u32 s7, 1
	v_lshl_add_u64 v[2:3], s[18:19], 0, v[130:131]
	s_cbranch_scc1 .LBB0_282
	s_barrier
.LBB0_282:
	s_add_u32 s34, s82, 0x12000
	s_addc_u32 s35, s83, 0
	s_lshl_b32 s9, s9, 5
	s_mov_b64 s[12:13], 0x80
	s_and_b32 s9, s9, 0x60
	s_add_i32 m0, s28, 0x18000
	v_lshl_add_u64 v[6:7], v[6:7], 0, s[12:13]
	s_ashr_i32 s36, s86, 31
	s_lshl_b32 s15, s7, 13
	s_lshl_b32 s22, s9, 7
	s_waitcnt vmcnt(2)
	s_barrier
	global_load_lds_dwordx4 v[6:7], off
	v_lshl_add_u64 v[4:5], v[4:5], 0, s[12:13]
	s_add_i32 m0, s28, 0x1a000
	s_add_i32 s37, s28, 0x8000
	s_add_i32 s38, s28, 0xa000
	global_load_lds_dwordx4 v[4:5], off
	v_lshl_add_u64 v[0:1], v[0:1], 0, s[12:13]
	s_mov_b32 m0, s37
	s_add_u32 s16, s20, 0xb0080
	global_load_lds_dwordx4 v[0:1], off
	v_lshl_add_u64 v[0:1], v[2:3], 0, s[12:13]
	s_mov_b32 m0, s38
	s_addc_u32 s17, s21, 0
	global_load_lds_dwordx4 v[0:1], off
	s_add_i32 m0, s28, 0x1c000
	v_lshl_add_u64 v[0:1], s[16:17], 0, v[132:133]
	global_load_lds_dwordx4 v[0:1], off
	v_lshl_add_u64 v[0:1], s[16:17], 0, v[128:129]
	s_add_i32 m0, s28, 0x1e000
	s_cmpk_lt_u32 s6, 0x100
	global_load_lds_dwordx4 v[0:1], off
	v_lshrrev_b32_e32 v1, 1, v9
	v_and_b32_e32 v1, 24, v1
	v_and_b32_e32 v0, 15, v9
	v_lshlrev_b32_e32 v2, 1, v1
	v_lshl_or_b32 v166, s7, 6, v0
	v_lshl_or_b32 v0, v0, 6, v2
	v_lshlrev_b32_e32 v2, 2, v9
	v_and_b32_e32 v2, 32, v2
	v_bitop3_b32 v3, v0, s15, v2 bitop3:0xde
	v_bitop3_b32 v167, v0, s22, v2 bitop3:0xde
	v_or_b32_e32 v168, s9, v1
	v_lshrrev_b32_e32 v1, 1, v14
	v_mul_lo_u32 v0, v13, s8
	s_mov_b32 s9, 0xb000
	v_mad_u64_u32 v[0:1], s[6:7], v1, s9, v[0:1]
	v_or_b32_e32 v0, v0, v15
	s_mov_b64 s[16:17], 0xb0080
	v_add_lshl_u32 v0, v0, v16, 1
	v_mov_b32_e32 v1, v133
	v_lshl_add_u64 v[136:137], v[0:1], 0, s[16:17]
	v_lshrrev_b32_e32 v1, 1, v8
	v_mul_lo_u32 v0, v10, s8
	v_mad_u64_u32 v[0:1], s[6:7], v1, s9, v[0:1]
	s_waitcnt vmcnt(6)
	v_or_b32_e32 v0, v0, v11
	s_sext_i32_i8 s45, s14
	s_cselect_b64 s[14:15], -1, 0
	v_add_lshl_u32 v0, v0, v12, 1
	v_mov_b32_e32 v1, v133
	s_add_i32 s40, 0, 0x10000
	s_add_i32 s41, 0, 0x14000
	s_mov_b32 s39, s86
	v_lshl_add_u64 v[138:139], v[0:1], 0, s[16:17]
	v_mov_b64_e32 v[140:141], 0x200
	v_mov_b64_e32 v[142:143], 0x1ff
	v_add_u32_e32 v169, s40, v167
	v_add_u32_e32 v170, s41, v167
	v_add_u32_e32 v171, 0, v3
	s_barrier
	v_sub_u32_e32 v136, v136, v252
	v_add_u32_e32 v136, v136, v134
	v_sub_u32_e32 v138, v138, v253
	v_add_u32_e32 v138, v138, v130
	v_and_b32_e32 v250, 63, v236
	v_and_b32_e32 v251, 15, v250
	v_lshrrev_b32_e32 v252, 4, v250
	v_and_b32_e32 v253, 7, v251
	v_xor_b32_e32 v252, v252, v253
	v_lshlrev_b32_e32 v252, 4, v252
	v_lshl_add_u32 v252, v251, 7, v252
	v_lshrrev_b32_e32 v250, 6, v236
	v_lshrrev_b32_e32 v251, 2, v250
	v_lshl_add_u32 v171, v251, 13, v252
	v_and_b32_e32 v251, 3, v250
	v_lshl_add_u32 v167, v251, 12, v252
	v_add_u32_e32 v169, s40, v167
	v_add_u32_e32 v170, s41, v167
	s_branch .LBB0_285

.LBB0_295:
	s_add_u32 s46, s20, 0x100
	v_mov_b32_e32 v0, 0
	s_addc_u32 s47, s21, 0
	s_mov_b32 s48, -2
	v_mov_b32_e32 v1, v0
	v_mov_b32_e32 v2, v0
	v_mov_b32_e32 v3, v0
	v_mov_b32_e32 v4, v0
	v_mov_b32_e32 v5, v0
	v_mov_b32_e32 v6, v0
	v_mov_b32_e32 v7, v0
	v_mov_b32_e32 v12, v0
	v_mov_b32_e32 v13, v0
	v_mov_b32_e32 v14, v0
	v_mov_b32_e32 v15, v0
	v_mov_b32_e32 v20, v0
	v_mov_b32_e32 v21, v0
	v_mov_b32_e32 v22, v0
	v_mov_b32_e32 v23, v0
	v_mov_b32_e32 v28, v0
	v_mov_b32_e32 v29, v0
	v_mov_b32_e32 v30, v0
	v_mov_b32_e32 v31, v0
	v_mov_b32_e32 v36, v0
	v_mov_b32_e32 v37, v0
	v_mov_b32_e32 v38, v0
	v_mov_b32_e32 v39, v0
	v_mov_b32_e32 v44, v0
	v_mov_b32_e32 v45, v0
	v_mov_b32_e32 v46, v0
	v_mov_b32_e32 v47, v0
	v_mov_b32_e32 v52, v0
	v_mov_b32_e32 v53, v0
	v_mov_b32_e32 v54, v0
	v_mov_b32_e32 v55, v0
	v_mov_b32_e32 v8, v0
	v_mov_b32_e32 v9, v0
	v_mov_b32_e32 v10, v0
	v_mov_b32_e32 v11, v0
	v_mov_b32_e32 v16, v0
	v_mov_b32_e32 v17, v0
	v_mov_b32_e32 v18, v0
	v_mov_b32_e32 v19, v0
	v_mov_b32_e32 v24, v0
	v_mov_b32_e32 v25, v0
	v_mov_b32_e32 v26, v0
	v_mov_b32_e32 v27, v0
	v_mov_b32_e32 v32, v0
	v_mov_b32_e32 v33, v0
	s_waitcnt lgkmcnt(0)
	v_mov_b32_e32 v34, v0
	v_mov_b32_e32 v35, v0
	v_mov_b32_e32 v40, v0
	v_mov_b32_e32 v41, v0
	v_mov_b32_e32 v42, v0
	v_mov_b32_e32 v43, v0
	v_mov_b32_e32 v48, v0
	v_mov_b32_e32 v49, v0
	v_mov_b32_e32 v50, v0
	v_mov_b32_e32 v51, v0
	v_mov_b32_e32 v56, v0
	v_mov_b32_e32 v57, v0
	v_mov_b32_e32 v58, v0
	v_mov_b32_e32 v59, v0
	v_mov_b32_e32 v60, v0
	v_mov_b32_e32 v61, v0
	v_mov_b32_e32 v62, v0
	v_mov_b32_e32 v63, v0
	v_mov_b32_e32 v64, v0
	v_mov_b32_e32 v65, v0
	v_mov_b32_e32 v66, v0
	v_mov_b32_e32 v67, v0
	v_mov_b32_e32 v68, v0
	v_mov_b32_e32 v69, v0
	v_mov_b32_e32 v70, v0
	v_mov_b32_e32 v71, v0
	v_mov_b32_e32 v76, v0
	v_mov_b32_e32 v77, v0
	v_mov_b32_e32 v78, v0
	v_mov_b32_e32 v79, v0
	v_mov_b32_e32 v84, v0
	v_mov_b32_e32 v85, v0
	v_mov_b32_e32 v86, v0
	v_mov_b32_e32 v87, v0
	v_mov_b32_e32 v92, v0
	v_mov_b32_e32 v93, v0
	v_mov_b32_e32 v94, v0
	v_mov_b32_e32 v95, v0
	v_mov_b32_e32 v100, v0
	v_mov_b32_e32 v101, v0
	v_mov_b32_e32 v102, v0
	v_mov_b32_e32 v103, v0
	v_mov_b32_e32 v104, v0
	v_mov_b32_e32 v105, v0
	v_mov_b32_e32 v106, v0
	v_mov_b32_e32 v107, v0
	v_mov_b32_e32 v108, v0
	v_mov_b32_e32 v109, v0
	v_mov_b32_e32 v110, v0
	v_mov_b32_e32 v111, v0
	v_mov_b32_e32 v72, v0
	v_mov_b32_e32 v73, v0
	v_mov_b32_e32 v74, v0
	v_mov_b32_e32 v75, v0
	v_mov_b32_e32 v80, v0
	v_mov_b32_e32 v81, v0
	v_mov_b32_e32 v82, v0
	v_mov_b32_e32 v83, v0
	v_mov_b32_e32 v88, v0
	v_mov_b32_e32 v89, v0
	v_mov_b32_e32 v90, v0
	v_mov_b32_e32 v91, v0
	v_mov_b32_e32 v96, v0
	v_mov_b32_e32 v97, v0
	v_mov_b32_e32 v98, v0
	v_mov_b32_e32 v99, v0
	v_mov_b32_e32 v112, v0
	v_mov_b32_e32 v113, v0
	v_mov_b32_e32 v114, v0
	v_mov_b32_e32 v115, v0
	v_mov_b32_e32 v116, v0
	v_mov_b32_e32 v117, v0
	v_mov_b32_e32 v118, v0
	v_mov_b32_e32 v119, v0
	v_mov_b32_e32 v120, v0
	v_mov_b32_e32 v121, v0
	v_mov_b32_e32 v122, v0
	v_mov_b32_e32 v123, v0
	v_mov_b32_e32 v124, v0
	v_mov_b32_e32 v125, v0
	v_mov_b32_e32 v126, v0
	v_mov_b32_e32 v127, v0
	v_xor_b32_e32 v246, 64, v171
	v_xor_b32_e32 v247, 64, v167
	v_add_u32_e32 v248, s40, v247
	v_add_u32_e32 v249, s41, v247
.LBB0_296:
	ds_read_b128 v[144:147], v169
	ds_read_b128 v[148:151], v248
	ds_read_b128 v[152:155], v169 offset:2048
	ds_read_b128 v[156:159], v248 offset:2048
	ds_read_b128 v[160:163], v170
	ds_read_b128 v[172:175], v249
	ds_read_b128 v[176:179], v170 offset:2048
	ds_read_b128 v[180:183], v249 offset:2048
	s_add_u32 s20, s18, 0x100
	s_addc_u32 s21, s19, 0
	s_cmp_eq_u32 s48, 40
	s_cselect_b32 s25, s9, s21
	s_cselect_b32 s24, s8, s20
	s_cselect_b32 s23, s17, s47
	s_cselect_b32 s22, s16, s46
	v_lshl_add_u64 v[164:165], s[18:19], 0, v[136:137]
	s_add_i32 m0, s28, 0xc000
	ds_read_b128 v[184:187], v171
	ds_read_b128 v[188:191], v246
	ds_read_b128 v[192:195], v171 offset:2048
	ds_read_b128 v[196:199], v246 offset:2048
	ds_read_b128 v[200:203], v171 offset:4096
	ds_read_b128 v[204:207], v246 offset:4096
	ds_read_b128 v[208:211], v171 offset:6144
	ds_read_b128 v[212:215], v246 offset:6144
	global_load_lds_dwordx4 v[164:165], off
	v_lshl_add_u64 v[164:165], s[18:19], 0, v[138:139]
	s_add_i32 m0, s28, 0xe000
	s_nop 0
	global_load_lds_dwordx4 v[164:165], off
	s_waitcnt vmcnt(8)
	s_waitcnt lgkmcnt(0)
	s_barrier
	s_setprio 0
	s_waitcnt lgkmcnt(0)
	v_mfma_f32_16x16x32_bf16 v[124:127], v[144:147], v[184:187], v[124:127]
	v_mfma_f32_16x16x32_bf16 v[120:123], v[152:155], v[184:187], v[120:123]
	v_mfma_f32_16x16x32_bf16 v[116:119], v[144:147], v[192:195], v[116:119]
	v_mfma_f32_16x16x32_bf16 v[112:115], v[152:155], v[192:195], v[112:115]
	v_mfma_f32_16x16x32_bf16 v[96:99], v[144:147], v[200:203], v[96:99]
	v_mfma_f32_16x16x32_bf16 v[88:91], v[152:155], v[200:203], v[88:91]
	v_mfma_f32_16x16x32_bf16 v[80:83], v[144:147], v[208:211], v[80:83]
	v_mfma_f32_16x16x32_bf16 v[72:75], v[152:155], v[208:211], v[72:75]
	v_mfma_f32_16x16x32_bf16 v[124:127], v[148:151], v[188:191], v[124:127]
	v_mfma_f32_16x16x32_bf16 v[120:123], v[156:159], v[188:191], v[120:123]
	v_mfma_f32_16x16x32_bf16 v[116:119], v[148:151], v[196:199], v[116:119]
	v_mfma_f32_16x16x32_bf16 v[112:115], v[156:159], v[196:199], v[112:115]
	v_mfma_f32_16x16x32_bf16 v[96:99], v[148:151], v[204:207], v[96:99]
	v_mfma_f32_16x16x32_bf16 v[88:91], v[156:159], v[204:207], v[88:91]
	v_mfma_f32_16x16x32_bf16 v[80:83], v[148:151], v[212:215], v[80:83]
	v_mfma_f32_16x16x32_bf16 v[72:75], v[156:159], v[212:215], v[72:75]
	s_setprio 0
	s_setprio 0
	v_mfma_f32_16x16x32_bf16 v[108:111], v[160:163], v[184:187], v[108:111]
	v_mfma_f32_16x16x32_bf16 v[104:107], v[176:179], v[184:187], v[104:107]
	v_mfma_f32_16x16x32_bf16 v[100:103], v[160:163], v[192:195], v[100:103]
	v_mfma_f32_16x16x32_bf16 v[92:95], v[176:179], v[192:195], v[92:95]
	v_mfma_f32_16x16x32_bf16 v[84:87], v[160:163], v[200:203], v[84:87]
	v_mfma_f32_16x16x32_bf16 v[76:79], v[176:179], v[200:203], v[76:79]
	v_mfma_f32_16x16x32_bf16 v[68:71], v[160:163], v[208:211], v[68:71]
	v_mfma_f32_16x16x32_bf16 v[64:67], v[176:179], v[208:211], v[64:67]
	v_mfma_f32_16x16x32_bf16 v[108:111], v[172:175], v[188:191], v[108:111]
	v_mfma_f32_16x16x32_bf16 v[104:107], v[180:183], v[188:191], v[104:107]
	v_mfma_f32_16x16x32_bf16 v[100:103], v[172:175], v[196:199], v[100:103]
	v_mfma_f32_16x16x32_bf16 v[92:95], v[180:183], v[196:199], v[92:95]
	v_mfma_f32_16x16x32_bf16 v[84:87], v[172:175], v[204:207], v[84:87]
	v_mfma_f32_16x16x32_bf16 v[76:79], v[180:183], v[204:207], v[76:79]
	v_mfma_f32_16x16x32_bf16 v[68:71], v[172:175], v[212:215], v[68:71]
	v_mfma_f32_16x16x32_bf16 v[64:67], v[180:183], v[212:215], v[64:67]
	s_setprio 0
	s_barrier
	s_add_i32 s18, s40, s26
	v_lshl_add_u64 v[164:165], s[22:23], 0, v[132:133]
	s_mov_b32 m0, s18
	ds_read_b128 v[184:187], v171 offset:16384
	ds_read_b128 v[188:191], v246 offset:16384
	ds_read_b128 v[192:195], v171 offset:18432
	ds_read_b128 v[196:199], v246 offset:18432
	ds_read_b128 v[200:203], v171 offset:20480
	ds_read_b128 v[204:207], v246 offset:20480
	ds_read_b128 v[208:211], v171 offset:22528
	ds_read_b128 v[212:215], v246 offset:22528
	global_load_lds_dwordx4 v[164:165], off
	s_add_i32 m0, s18, 0x2000
	s_add_u32 s18, s22, 0xb0000
	v_lshl_add_u64 v[216:217], s[22:23], 0, v[128:129]
	s_addc_u32 s19, s23, 0
	s_add_i32 s49, s41, s26
	global_load_lds_dwordx4 v[216:217], off
	v_lshl_add_u64 v[218:219], s[18:19], 0, v[132:133]
	s_mov_b32 m0, s49
	v_lshl_add_u64 v[220:221], s[24:25], 0, v[130:131]
	global_load_lds_dwordx4 v[218:219], off
	v_lshl_add_u64 v[218:219], s[18:19], 0, v[128:129]
	s_add_i32 m0, s49, 0x2000
	s_nop 0
	global_load_lds_dwordx4 v[218:219], off
	v_lshl_add_u64 v[218:219], s[24:25], 0, v[134:135]
	s_mov_b32 m0, s28
	s_nop 0
	global_load_lds_dwordx4 v[218:219], off
	s_mov_b32 m0, s29
	s_nop 0
	global_load_lds_dwordx4 v[220:221], off
	s_waitcnt vmcnt(8)
	s_waitcnt lgkmcnt(0)
	s_barrier
	s_setprio 0
	s_waitcnt lgkmcnt(0)
	v_mfma_f32_16x16x32_bf16 v[60:63], v[144:147], v[184:187], v[60:63]
	v_mfma_f32_16x16x32_bf16 v[56:59], v[152:155], v[184:187], v[56:59]
	v_mfma_f32_16x16x32_bf16 v[48:51], v[144:147], v[192:195], v[48:51]
	v_mfma_f32_16x16x32_bf16 v[40:43], v[152:155], v[192:195], v[40:43]
	v_mfma_f32_16x16x32_bf16 v[32:35], v[144:147], v[200:203], v[32:35]
	v_mfma_f32_16x16x32_bf16 v[24:27], v[152:155], v[200:203], v[24:27]
	v_mfma_f32_16x16x32_bf16 v[16:19], v[144:147], v[208:211], v[16:19]
	v_mfma_f32_16x16x32_bf16 v[8:11], v[152:155], v[208:211], v[8:11]
	v_mfma_f32_16x16x32_bf16 v[60:63], v[148:151], v[188:191], v[60:63]
	v_mfma_f32_16x16x32_bf16 v[56:59], v[156:159], v[188:191], v[56:59]
	v_mfma_f32_16x16x32_bf16 v[48:51], v[148:151], v[196:199], v[48:51]
	v_mfma_f32_16x16x32_bf16 v[40:43], v[156:159], v[196:199], v[40:43]
	v_mfma_f32_16x16x32_bf16 v[32:35], v[148:151], v[204:207], v[32:35]
	v_mfma_f32_16x16x32_bf16 v[24:27], v[156:159], v[204:207], v[24:27]
	v_mfma_f32_16x16x32_bf16 v[16:19], v[148:151], v[212:215], v[16:19]
	v_mfma_f32_16x16x32_bf16 v[8:11], v[156:159], v[212:215], v[8:11]
	s_setprio 0
	s_setprio 0
	v_mfma_f32_16x16x32_bf16 v[52:55], v[160:163], v[184:187], v[52:55]
	v_mfma_f32_16x16x32_bf16 v[44:47], v[176:179], v[184:187], v[44:47]
	v_mfma_f32_16x16x32_bf16 v[36:39], v[160:163], v[192:195], v[36:39]
	v_mfma_f32_16x16x32_bf16 v[28:31], v[176:179], v[192:195], v[28:31]
	v_mfma_f32_16x16x32_bf16 v[20:23], v[160:163], v[200:203], v[20:23]
	v_mfma_f32_16x16x32_bf16 v[12:15], v[176:179], v[200:203], v[12:15]
	v_mfma_f32_16x16x32_bf16 v[4:7], v[160:163], v[208:211], v[4:7]
	v_mfma_f32_16x16x32_bf16 v[0:3], v[176:179], v[208:211], v[0:3]
	v_mfma_f32_16x16x32_bf16 v[52:55], v[172:175], v[188:191], v[52:55]
	v_mfma_f32_16x16x32_bf16 v[44:47], v[180:183], v[188:191], v[44:47]
	v_mfma_f32_16x16x32_bf16 v[36:39], v[172:175], v[196:199], v[36:39]
	v_mfma_f32_16x16x32_bf16 v[28:31], v[180:183], v[196:199], v[28:31]
	v_mfma_f32_16x16x32_bf16 v[20:23], v[172:175], v[204:207], v[20:23]
	v_mfma_f32_16x16x32_bf16 v[12:15], v[180:183], v[204:207], v[12:15]
	v_mfma_f32_16x16x32_bf16 v[4:7], v[172:175], v[212:215], v[4:7]
	v_mfma_f32_16x16x32_bf16 v[0:3], v[180:183], v[212:215], v[0:3]
	s_setprio 0
	s_barrier
	s_add_i32 s49, 0, 0x18000
	s_add_i32 s50, 0, 0x1c000
	v_add_u32_e32 v156, s49, v167
	v_add_u32_e32 v250, s49, v247
	v_add_u32_e32 v180, s50, v167
	v_add_u32_e32 v251, s50, v247
	ds_read_b128 v[144:147], v156
	ds_read_b128 v[148:151], v250
	ds_read_b128 v[152:155], v156 offset:2048
	ds_read_b128 v[156:159], v250 offset:2048
	ds_read_b128 v[160:163], v180
	ds_read_b128 v[172:175], v251
	ds_read_b128 v[176:179], v180 offset:2048
	ds_read_b128 v[180:183], v251 offset:2048
	s_add_u32 s18, s24, 0xb0000
	s_addc_u32 s19, s25, 0
	s_mov_b32 m0, s30
	v_lshl_add_u64 v[222:223], s[18:19], 0, v[134:135]
	ds_read_b128 v[184:187], v171 offset:32768
	ds_read_b128 v[188:191], v246 offset:32768
	ds_read_b128 v[192:195], v171 offset:34816
	ds_read_b128 v[196:199], v246 offset:34816
	ds_read_b128 v[200:203], v171 offset:36864
	ds_read_b128 v[204:207], v246 offset:36864
	ds_read_b128 v[208:211], v171 offset:38912
	ds_read_b128 v[212:215], v246 offset:38912
	global_load_lds_dwordx4 v[222:223], off
	v_lshl_add_u64 v[222:223], s[18:19], 0, v[130:131]
	s_mov_b32 m0, s31
	s_nop 0
	global_load_lds_dwordx4 v[222:223], off
	s_waitcnt vmcnt(8)
	s_waitcnt lgkmcnt(0)
	s_barrier
	s_setprio 0
	s_waitcnt lgkmcnt(0)
	v_mfma_f32_16x16x32_bf16 v[124:127], v[144:147], v[184:187], v[124:127]
	v_mfma_f32_16x16x32_bf16 v[120:123], v[152:155], v[184:187], v[120:123]
	v_mfma_f32_16x16x32_bf16 v[116:119], v[144:147], v[192:195], v[116:119]
	v_mfma_f32_16x16x32_bf16 v[112:115], v[152:155], v[192:195], v[112:115]
	v_mfma_f32_16x16x32_bf16 v[96:99], v[144:147], v[200:203], v[96:99]
	v_mfma_f32_16x16x32_bf16 v[88:91], v[152:155], v[200:203], v[88:91]
	v_mfma_f32_16x16x32_bf16 v[80:83], v[144:147], v[208:211], v[80:83]
	v_mfma_f32_16x16x32_bf16 v[72:75], v[152:155], v[208:211], v[72:75]
	v_mfma_f32_16x16x32_bf16 v[124:127], v[148:151], v[188:191], v[124:127]
	v_mfma_f32_16x16x32_bf16 v[120:123], v[156:159], v[188:191], v[120:123]
	v_mfma_f32_16x16x32_bf16 v[116:119], v[148:151], v[196:199], v[116:119]
	v_mfma_f32_16x16x32_bf16 v[112:115], v[156:159], v[196:199], v[112:115]
	v_mfma_f32_16x16x32_bf16 v[96:99], v[148:151], v[204:207], v[96:99]
	v_mfma_f32_16x16x32_bf16 v[88:91], v[156:159], v[204:207], v[88:91]
	v_mfma_f32_16x16x32_bf16 v[80:83], v[148:151], v[212:215], v[80:83]
	v_mfma_f32_16x16x32_bf16 v[72:75], v[156:159], v[212:215], v[72:75]
	s_setprio 0
	s_setprio 0
	v_mfma_f32_16x16x32_bf16 v[108:111], v[160:163], v[184:187], v[108:111]
	v_mfma_f32_16x16x32_bf16 v[104:107], v[176:179], v[184:187], v[104:107]
	v_mfma_f32_16x16x32_bf16 v[100:103], v[160:163], v[192:195], v[100:103]
	v_mfma_f32_16x16x32_bf16 v[92:95], v[176:179], v[192:195], v[92:95]
	v_mfma_f32_16x16x32_bf16 v[84:87], v[160:163], v[200:203], v[84:87]
	v_mfma_f32_16x16x32_bf16 v[76:79], v[176:179], v[200:203], v[76:79]
	v_mfma_f32_16x16x32_bf16 v[68:71], v[160:163], v[208:211], v[68:71]
	v_mfma_f32_16x16x32_bf16 v[64:67], v[176:179], v[208:211], v[64:67]
	v_mfma_f32_16x16x32_bf16 v[108:111], v[172:175], v[188:191], v[108:111]
	v_mfma_f32_16x16x32_bf16 v[104:107], v[180:183], v[188:191], v[104:107]
	v_mfma_f32_16x16x32_bf16 v[100:103], v[172:175], v[196:199], v[100:103]
	v_mfma_f32_16x16x32_bf16 v[92:95], v[180:183], v[196:199], v[92:95]
	v_mfma_f32_16x16x32_bf16 v[84:87], v[172:175], v[204:207], v[84:87]
	v_mfma_f32_16x16x32_bf16 v[76:79], v[180:183], v[204:207], v[76:79]
	v_mfma_f32_16x16x32_bf16 v[68:71], v[172:175], v[212:215], v[68:71]
	v_mfma_f32_16x16x32_bf16 v[64:67], v[180:183], v[212:215], v[64:67]
	s_setprio 0
	s_barrier
	s_add_i32 s18, s49, s26
	v_lshl_add_u64 v[164:165], v[164:165], 0, s[12:13]
	s_mov_b32 m0, s18
	ds_read_b128 v[184:187], v171 offset:49152
	ds_read_b128 v[188:191], v246 offset:49152
	ds_read_b128 v[192:195], v171 offset:51200
	ds_read_b128 v[196:199], v246 offset:51200
	ds_read_b128 v[200:203], v171 offset:53248
	ds_read_b128 v[204:207], v246 offset:53248
	ds_read_b128 v[208:211], v171 offset:55296
	ds_read_b128 v[212:215], v246 offset:55296
	global_load_lds_dwordx4 v[164:165], off
	s_add_i32 m0, s18, 0x2000
	s_add_u32 s18, s22, 0xb0080
	v_lshl_add_u64 v[164:165], v[216:217], 0, s[12:13]
	s_addc_u32 s19, s23, 0
	s_add_i32 s22, s50, s26
	global_load_lds_dwordx4 v[164:165], off
	v_lshl_add_u64 v[164:165], s[18:19], 0, v[132:133]
	s_mov_b32 m0, s22
	s_nop 0
	global_load_lds_dwordx4 v[164:165], off
	v_lshl_add_u64 v[164:165], s[18:19], 0, v[128:129]
	s_add_i32 m0, s22, 0x2000
	s_nop 0
	global_load_lds_dwordx4 v[164:165], off
	v_lshl_add_u64 v[164:165], v[218:219], 0, s[12:13]
	s_mov_b32 m0, s37
	s_nop 0
	global_load_lds_dwordx4 v[164:165], off
	v_lshl_add_u64 v[164:165], v[220:221], 0, s[12:13]
	s_mov_b32 m0, s38
	s_nop 0
	global_load_lds_dwordx4 v[164:165], off
	s_waitcnt vmcnt(8)
	s_waitcnt lgkmcnt(0)
	s_barrier
	s_setprio 0
	s_waitcnt lgkmcnt(0)
	v_mfma_f32_16x16x32_bf16 v[60:63], v[144:147], v[184:187], v[60:63]
	v_mfma_f32_16x16x32_bf16 v[56:59], v[152:155], v[184:187], v[56:59]
	v_mfma_f32_16x16x32_bf16 v[48:51], v[144:147], v[192:195], v[48:51]
	v_mfma_f32_16x16x32_bf16 v[40:43], v[152:155], v[192:195], v[40:43]
	v_mfma_f32_16x16x32_bf16 v[32:35], v[144:147], v[200:203], v[32:35]
	v_mfma_f32_16x16x32_bf16 v[24:27], v[152:155], v[200:203], v[24:27]
	v_mfma_f32_16x16x32_bf16 v[16:19], v[144:147], v[208:211], v[16:19]
	v_mfma_f32_16x16x32_bf16 v[8:11], v[152:155], v[208:211], v[8:11]
	v_mfma_f32_16x16x32_bf16 v[60:63], v[148:151], v[188:191], v[60:63]
	v_mfma_f32_16x16x32_bf16 v[56:59], v[156:159], v[188:191], v[56:59]
	v_mfma_f32_16x16x32_bf16 v[48:51], v[148:151], v[196:199], v[48:51]
	v_mfma_f32_16x16x32_bf16 v[40:43], v[156:159], v[196:199], v[40:43]
	v_mfma_f32_16x16x32_bf16 v[32:35], v[148:151], v[204:207], v[32:35]
	v_mfma_f32_16x16x32_bf16 v[24:27], v[156:159], v[204:207], v[24:27]
	v_mfma_f32_16x16x32_bf16 v[16:19], v[148:151], v[212:215], v[16:19]
	v_mfma_f32_16x16x32_bf16 v[8:11], v[156:159], v[212:215], v[8:11]
	s_setprio 0
	s_setprio 0
	v_mfma_f32_16x16x32_bf16 v[52:55], v[160:163], v[184:187], v[52:55]
	v_mfma_f32_16x16x32_bf16 v[44:47], v[176:179], v[184:187], v[44:47]
	v_mfma_f32_16x16x32_bf16 v[36:39], v[160:163], v[192:195], v[36:39]
	v_mfma_f32_16x16x32_bf16 v[28:31], v[176:179], v[192:195], v[28:31]
	v_mfma_f32_16x16x32_bf16 v[20:23], v[160:163], v[200:203], v[20:23]
	v_mfma_f32_16x16x32_bf16 v[12:15], v[176:179], v[200:203], v[12:15]
	v_mfma_f32_16x16x32_bf16 v[4:7], v[160:163], v[208:211], v[4:7]
	v_mfma_f32_16x16x32_bf16 v[0:3], v[176:179], v[208:211], v[0:3]
	v_mfma_f32_16x16x32_bf16 v[52:55], v[172:175], v[188:191], v[52:55]
	v_mfma_f32_16x16x32_bf16 v[44:47], v[180:183], v[188:191], v[44:47]
	v_mfma_f32_16x16x32_bf16 v[36:39], v[172:175], v[196:199], v[36:39]
	v_mfma_f32_16x16x32_bf16 v[28:31], v[180:183], v[196:199], v[28:31]
	v_mfma_f32_16x16x32_bf16 v[20:23], v[172:175], v[204:207], v[20:23]
	v_mfma_f32_16x16x32_bf16 v[12:15], v[180:183], v[204:207], v[12:15]
	v_mfma_f32_16x16x32_bf16 v[4:7], v[172:175], v[212:215], v[4:7]
	v_mfma_f32_16x16x32_bf16 v[0:3], v[180:183], v[212:215], v[0:3]
	s_setprio 0
	s_barrier
	s_add_i32 s48, s48, 2
	s_add_u32 s46, s46, 0x100
	s_addc_u32 s47, s47, 0
	s_cmp_gt_u32 s48, 41
	s_mov_b64 s[18:19], s[20:21]
	s_cbranch_scc0 .LBB0_296
	s_and_b64 vcc, exec, s[14:15]
	s_cbranch_vccz .LBB0_299
	s_barrier

.LBB0_424:
	s_andn2_b64 vcc, exec, s[0:1]
	s_cbranch_vccnz .LBB0_460
	v_ashrrev_i32_e32 v1, 31, v8
	v_lshrrev_b32_e32 v1, 26, v1
	v_add_u32_e32 v1, v8, v1
	v_ashrrev_i32_e32 v9, 6, v1
	v_bfe_i32 v1, v8, 27, 1
	v_lshlrev_b32_e32 v0, 4, v8
	v_lshrrev_b32_e32 v1, 22, v1
	v_add_u32_e32 v1, v0, v1
	v_and_b32_e32 v1, 0xfffffc00, v1
	v_sub_u32_e32 v1, v0, v1
	v_lshrrev_b32_e32 v2, 4, v1
	v_bitop3_b32 v2, v2, v1, 32 bitop3:0x6c
	v_ashrrev_i32_e32 v1, 31, v1
	v_lshrrev_b32_e32 v1, 26, v1
	v_add_u32_e32 v1, v2, v1
	v_ashrrev_i32_e32 v10, 6, v1
	v_lshlrev_b32_e32 v3, 3, v9
	v_mul_i32_i24_e32 v4, 64, v10
	v_and_b32_e32 v3, -16, v3
	v_sub_u32_e32 v2, v2, v4
	v_mov_b32_e32 v4, 1
	v_add_u32_e32 v1, v10, v3
	v_lshlrev_b32_e32 v3, 5, v9
	v_ashrrev_i16_sdwa v2, v4, sext(v2) dst_sel:DWORD dst_unused:UNUSED_PAD src0_sel:DWORD src1_sel:BYTE_0
	v_and_b32_e32 v3, 32, v3
	v_bfe_i32 v11, v2, 0, 16
	v_and_b32_e32 v6, 3, v10
	s_mov_b32 s1, 0x1fffe0
	v_add_lshl_u32 v3, v3, v11, 1
	v_add_u32_e32 v0, 0x2000, v0
	v_lshlrev_b32_e32 v2, 1, v1
	v_lshrrev_b32_e32 v5, 2, v1
	v_and_or_b32 v6, v1, s1, v6
	v_lshrrev_b32_e32 v250, 6, v236
	v_and_b32_e32 v251, 63, v236
	v_lshrrev_b32_e32 v252, 3, v251
	v_and_b32_e32 v251, 7, v251
	v_xor_b32_e32 v251, v251, v252
	v_lshlrev_b32_e32 v251, 4, v251
	v_lshl_add_u32 v253, v250, 3, v252
	v_lshl_add_u32 v246, v253, 11, v251
	v_add_u32_e32 v247, 0x20000, v246
	v_lshrrev_b32_e32 v253, 2, v250
	v_lshlrev_b32_e32 v253, 5, v253
	v_and_b32_e32 v248, 1, v250
	v_lshl_add_u32 v253, v248, 4, v253
	v_bfe_u32 v248, v250, 1, 1
	v_lshl_add_u32 v253, v248, 2, v253
	v_lshrrev_b32_e32 v248, 2, v252
	v_lshl_add_u32 v253, v248, 3, v253
	v_and_b32_e32 v248, 3, v252
	v_add_u32_e32 v253, v253, v248
	v_lshl_add_u32 v248, v253, 11, v251
	v_add_u32_e32 v249, 0x20000, v248
	v_lshl_add_u32 v210, v1, 11, v3
	v_mov_b32_e32 v252, v210
	v_mov_b32_e32 v210, v246
	v_ashrrev_i32_e32 v1, 31, v0
	v_lshrrev_b32_e32 v1, 22, v1
	v_add_u32_e32 v1, v0, v1
	v_ashrrev_i32_e32 v12, 10, v1
	v_mul_i32_i24_e32 v1, 0x400, v12
	v_sub_u32_e32 v0, v0, v1
	v_and_b32_e32 v2, 24, v2
	v_and_b32_e32 v5, 4, v5
	v_lshrrev_b32_e32 v1, 4, v0
	v_or3_b32 v2, v6, v5, v2
	v_bitop3_b32 v0, v1, v0, 32 bitop3:0x6c
	v_lshl_add_u32 v212, v2, 11, v3
	v_mov_b32_e32 v212, v248
	v_ashrrev_i32_e32 v2, 31, v0
	v_lshrrev_b32_e32 v2, 26, v2
	v_add_u32_e32 v2, v0, v2
	v_lshlrev_b32_e32 v1, 3, v12
	v_ashrrev_i32_e32 v13, 6, v2
	v_and_b32_e32 v2, 0xc0, v2
	s_add_u32 s2, s82, 0x2400000
	v_and_b32_e32 v1, -16, v1
	v_sub_u32_e32 v0, v0, v2
	s_addc_u32 s3, s83, 0
	s_ashr_i32 s0, s6, 6
	v_add_u32_e32 v1, v13, v1
	v_ashrrev_i16_sdwa v0, v4, sext(v0) dst_sel:DWORD dst_unused:UNUSED_PAD src0_sel:DWORD src1_sel:BYTE_0
	v_and_b32_e32 v4, 3, v13
	s_ashr_i32 s11, s10, 31
	s_ashr_i32 s9, s8, 31
	v_and_or_b32 v4, v1, s1, v4
	s_ashr_i32 s1, s6, 8
	s_lshl_b32 s33, s0, 10
	s_lshl_b64 s[12:13], s[10:11], 19
	s_lshl_b64 s[14:15], s[8:9], 19
	s_add_u32 s30, s2, s14
	v_lshlrev_b32_e32 v3, 5, v12
	v_bfe_i32 v14, v0, 0, 16
	v_lshlrev_b32_e32 v0, 1, v1
	v_lshrrev_b32_e32 v2, 2, v1
	s_addc_u32 s31, s3, s15
	s_add_i32 s36, s33, 0
	v_and_b32_e32 v3, 32, v3
	v_and_b32_e32 v0, 24, v0
	v_and_b32_e32 v2, 4, v2
	s_add_i32 m0, s36, 0x10000
	v_or3_b32 v0, v4, v2, v0
	v_add_lshl_u32 v2, v3, v14, 1
	global_load_lds_dwordx4 v212, s[30:31]
	s_add_i32 m0, s36, 0x12000
	v_lshl_add_u32 v216, v0, 11, v2
	v_mov_b32_e32 v216, v249
	s_add_u32 s14, s30, 0x40000
	global_load_lds_dwordx4 v216, s[30:31]
	s_addc_u32 s15, s31, 0
	s_add_i32 m0, s36, 0x14000
	v_lshl_add_u32 v214, v1, 11, v2
	v_mov_b32_e32 v253, v214
	v_mov_b32_e32 v214, v247
	global_load_lds_dwordx4 v212, s[14:15]
	s_add_i32 m0, s36, 0x16000
	s_add_u32 s28, s90, s12
	s_addc_u32 s29, s91, s13
	s_add_i32 s37, s36, 0x2000
	global_load_lds_dwordx4 v216, s[14:15]
	s_mov_b32 m0, s36
	s_add_u32 s12, s28, 0x40000
	global_load_lds_dwordx4 v210, s[28:29]
	s_mov_b32 m0, s37
	s_addc_u32 s13, s29, 0
	s_add_i32 s38, s36, 0x4000
	global_load_lds_dwordx4 v214, s[28:29]
	s_mov_b32 m0, s38
	s_add_i32 s39, s36, 0x6000
	global_load_lds_dwordx4 v210, s[12:13]
	s_mov_b32 m0, s39
	v_mov_b32_e32 v219, 0
	global_load_lds_dwordx4 v214, s[12:13]
	v_mov_b32_e32 v213, v219
	v_mov_b32_e32 v217, v219
	v_mov_b32_e32 v211, v219
	v_mov_b32_e32 v215, v219
	s_cmp_eq_u32 s1, 1
	s_mov_b32 s11, 0
	v_lshl_add_u64 v[6:7], s[30:31], 0, v[212:213]
	v_lshl_add_u64 v[4:5], s[30:31], 0, v[216:217]
	v_lshl_add_u64 v[0:1], s[28:29], 0, v[210:211]
	s_cselect_b64 s[12:13], -1, 0
	s_cmp_lg_u32 s1, 1
	v_lshl_add_u64 v[2:3], s[28:29], 0, v[214:215]
	s_cbranch_scc1 .LBB0_427
	s_barrier
.LBB0_427:
	s_add_u32 s40, s82, 0x9000000
	s_addc_u32 s41, s83, 0
	s_add_u32 s42, s82, 0x14000000
	s_addc_u32 s43, s83, 0
	s_add_u32 s14, s82, 0x80000
	s_mov_b64 s[16:17], 0x80
	s_addc_u32 s15, s83, 0
	s_and_b32 s46, s0, 3
	s_add_i32 m0, s36, 0x18000
	v_lshl_add_u64 v[6:7], v[6:7], 0, s[16:17]
	s_ashr_i32 s44, s86, 31
	s_ashr_i32 s45, s96, 31
	s_lshl_b32 s0, s1, 13
	s_lshl_b32 s7, s46, 12
	s_waitcnt vmcnt(2)
	s_barrier
	global_load_lds_dwordx4 v[6:7], off
	v_lshl_add_u64 v[4:5], v[4:5], 0, s[16:17]
	s_add_i32 m0, s36, 0x1a000
	s_add_i32 s47, s36, 0x8000
	s_add_i32 s48, s36, 0xa000
	global_load_lds_dwordx4 v[4:5], off
	v_lshl_add_u64 v[0:1], v[0:1], 0, s[16:17]
	s_mov_b32 m0, s47
	s_add_u32 s18, s30, 0x40080
	global_load_lds_dwordx4 v[0:1], off
	v_lshl_add_u64 v[0:1], v[2:3], 0, s[16:17]
	s_mov_b32 m0, s48
	s_addc_u32 s19, s31, 0
	global_load_lds_dwordx4 v[0:1], off
	s_add_i32 m0, s36, 0x1c000
	v_lshl_add_u64 v[0:1], s[18:19], 0, v[212:213]
	global_load_lds_dwordx4 v[0:1], off
	v_lshl_add_u64 v[0:1], s[18:19], 0, v[216:217]
	s_add_i32 m0, s36, 0x1e000
	s_cmpk_lt_u32 s6, 0x100
	global_load_lds_dwordx4 v[0:1], off
	v_bfe_u32 v1, v8, 4, 2
	v_and_b32_e32 v0, 15, v8
	v_lshlrev_b32_e32 v2, 4, v1
	v_lshl_or_b32 v221, s1, 6, v0
	v_lshl_or_b32 v0, v0, 6, v2
	v_lshlrev_b32_e32 v2, 2, v8
	v_and_b32_e32 v2, 32, v2
	v_lshlrev_b32_e32 v220, 3, v1
	v_bitop3_b32 v3, v0, s0, v2 bitop3:0xde
	v_cmp_gt_u32_e64 s[0:1], 2, v1
	v_cmp_eq_u32_e32 vcc, 0, v1
	v_lshlrev_b32_e32 v1, 14, v9
	v_and_b32_e32 v1, 0xffff8000, v1
	v_bitop3_b32 v237, v0, s7, v2 bitop3:0xde
	v_lshl_add_u32 v1, v10, 11, v1
	v_and_b32_e32 v2, 1, v9
	v_lshl_or_b32 v1, v2, 6, v1
	v_lshl_add_u32 v222, v11, 1, v1
	v_lshlrev_b32_e32 v1, 14, v12
	v_and_b32_e32 v1, 0xffff8000, v1
	s_waitcnt vmcnt(6)
	v_lshl_or_b32 v0, s46, 6, v220
	v_lshl_add_u32 v1, v13, 11, v1
	v_and_b32_e32 v2, 1, v12
	s_cselect_b64 s[18:19], -1, 0
	v_lshl_or_b32 v1, v2, 6, v1
	s_add_i32 s50, 0, 0x10000
	s_add_i32 s51, 0, 0x14000
	v_lshlrev_b32_e32 v230, 1, v0
	v_mbcnt_lo_u32_b32 v0, -1, 0
	s_mov_b32 s49, s86
	v_cndmask_b32_e64 v238, 1.0, -1.0, vcc
	v_mov_b32_e32 v223, v219
	v_lshl_add_u32 v224, v14, 1, v1
	v_mov_b32_e32 v225, v219
	v_mov_b64_e32 v[226:227], 0x700
	v_mov_b64_e32 v[228:229], 0x6ff
	v_add_u32_e32 v239, s50, v237
	v_add_u32_e32 v240, s51, v237
	v_add_u32_e32 v241, 0, v3
	v_mov_b32_e32 v242, 0x358637bd
	s_mov_b32 s52, 0xf800000
	v_mov_b32_e32 v243, 0x260
	s_mov_b32 s53, 0x2c000
	v_mov_b32_e32 v244, 0x3e38aa3b
	v_mbcnt_hi_u32_b32 v245, -1, v0
	s_mov_b32 s54, 0
	s_barrier
	v_sub_u32_e32 v222, v222, v252
	v_add_u32_e32 v222, v222, v210
	v_sub_u32_e32 v224, v224, v253
	v_add_u32_e32 v224, v224, v214
	v_and_b32_e32 v250, 63, v236
	v_and_b32_e32 v251, 15, v250
	v_lshrrev_b32_e32 v252, 4, v250
	v_and_b32_e32 v253, 7, v251
	v_xor_b32_e32 v252, v252, v253
	v_lshlrev_b32_e32 v252, 4, v252
	v_lshl_add_u32 v252, v251, 7, v252
	v_lshrrev_b32_e32 v250, 6, v236
	v_lshrrev_b32_e32 v251, 2, v250
	v_lshl_add_u32 v241, v251, 13, v252
	v_and_b32_e32 v251, 3, v250
	v_lshl_add_u32 v237, v251, 12, v252
	v_add_u32_e32 v239, s50, v237
	v_add_u32_e32 v240, s51, v237
	s_branch .LBB0_430

.LBB0_432:
	s_ashr_i32 s23, s22, 31
	s_lshl_b64 s[24:25], s[22:23], 19
	s_add_u32 s24, s90, s24
	s_addc_u32 s25, s91, s25
	s_and_b64 s[26:27], s[6:7], exec
	s_cselect_b32 s9, s25, s29
	s_cselect_b32 s23, s24, s28
	s_ashr_i32 s21, s20, 31
	s_lshl_b64 s[26:27], s[20:21], 19
	s_add_u32 s26, s2, s26
	s_addc_u32 s27, s3, s27
	s_and_b64 s[34:35], s[6:7], exec
	s_cselect_b32 s21, s27, s31
	s_cselect_b32 s55, s26, s30
	s_add_u32 s28, s28, 0x40080
	s_addc_u32 s29, s29, 0
	s_add_u32 s56, s30, 0x100
	v_mov_b32_e32 v0, 0
	s_addc_u32 s57, s31, 0
	s_mov_b32 s58, -2
	v_mov_b32_e32 v1, v0
	v_mov_b32_e32 v2, v0
	v_mov_b32_e32 v3, v0
	v_mov_b32_e32 v4, v0
	v_mov_b32_e32 v5, v0
	v_mov_b32_e32 v6, v0
	v_mov_b32_e32 v7, v0
	v_mov_b32_e32 v16, v0
	v_mov_b32_e32 v17, v0
	v_mov_b32_e32 v18, v0
	v_mov_b32_e32 v19, v0
	v_mov_b32_e32 v20, v0
	v_mov_b32_e32 v21, v0
	v_mov_b32_e32 v22, v0
	v_mov_b32_e32 v23, v0
	v_mov_b32_e32 v32, v0
	v_mov_b32_e32 v33, v0
	v_mov_b32_e32 v34, v0
	v_mov_b32_e32 v35, v0
	v_mov_b32_e32 v36, v0
	v_mov_b32_e32 v37, v0
	v_mov_b32_e32 v38, v0
	v_mov_b32_e32 v39, v0
	v_mov_b32_e32 v48, v0
	v_mov_b32_e32 v49, v0
	v_mov_b32_e32 v50, v0
	v_mov_b32_e32 v51, v0
	v_mov_b32_e32 v52, v0
	v_mov_b32_e32 v53, v0
	v_mov_b32_e32 v54, v0
	v_mov_b32_e32 v55, v0
	v_mov_b32_e32 v8, v0
	v_mov_b32_e32 v9, v0
	v_mov_b32_e32 v10, v0
	v_mov_b32_e32 v11, v0
	v_mov_b32_e32 v12, v0
	v_mov_b32_e32 v13, v0
	v_mov_b32_e32 v14, v0
	v_mov_b32_e32 v15, v0
	v_mov_b32_e32 v24, v0
	v_mov_b32_e32 v25, v0
	v_mov_b32_e32 v26, v0
	v_mov_b32_e32 v27, v0
	v_mov_b32_e32 v28, v0
	v_mov_b32_e32 v29, v0
	v_mov_b32_e32 v30, v0
	v_mov_b32_e32 v31, v0
	v_mov_b32_e32 v40, v0
	v_mov_b32_e32 v41, v0
	v_mov_b32_e32 v42, v0
	v_mov_b32_e32 v43, v0
	v_mov_b32_e32 v44, v0
	v_mov_b32_e32 v45, v0
	v_mov_b32_e32 v46, v0
	v_mov_b32_e32 v47, v0
	v_mov_b32_e32 v56, v0
	v_mov_b32_e32 v57, v0
	v_mov_b32_e32 v58, v0
	v_mov_b32_e32 v59, v0
	v_mov_b32_e32 v60, v0
	v_mov_b32_e32 v61, v0
	v_mov_b32_e32 v62, v0
	v_mov_b32_e32 v63, v0
	v_mov_b32_e32 v64, v0
	v_mov_b32_e32 v65, v0
	v_mov_b32_e32 v66, v0
	v_mov_b32_e32 v67, v0
	v_mov_b32_e32 v68, v0
	v_mov_b32_e32 v69, v0
	v_mov_b32_e32 v70, v0
	v_mov_b32_e32 v71, v0
	v_mov_b32_e32 v82, v0
	v_mov_b32_e32 v83, v0
	v_mov_b32_e32 v84, v0
	v_mov_b32_e32 v85, v0
	v_mov_b32_e32 v86, v0
	v_mov_b32_e32 v87, v0
	v_mov_b32_e32 v88, v0
	v_mov_b32_e32 v89, v0
	v_mov_b32_e32 v98, v0
	v_mov_b32_e32 v99, v0
	v_mov_b32_e32 v100, v0
	v_mov_b32_e32 v101, v0
	v_mov_b32_e32 v102, v0
	v_mov_b32_e32 v103, v0
	v_mov_b32_e32 v104, v0
	v_mov_b32_e32 v105, v0
	v_mov_b32_e32 v114, v0
	v_mov_b32_e32 v115, v0
	v_mov_b32_e32 v116, v0
	v_mov_b32_e32 v117, v0
	v_mov_b32_e32 v118, v0
	v_mov_b32_e32 v119, v0
	v_mov_b32_e32 v120, v0
	v_mov_b32_e32 v121, v0
	v_mov_b32_e32 v72, v0
	v_mov_b32_e32 v73, v0
	v_mov_b32_e32 v74, v0
	v_mov_b32_e32 v75, v0
	v_mov_b32_e32 v76, v0
	v_mov_b32_e32 v77, v0
	v_mov_b32_e32 v78, v0
	v_mov_b32_e32 v79, v0
	v_mov_b32_e32 v90, v0
	v_mov_b32_e32 v91, v0
	v_mov_b32_e32 v92, v0
	v_mov_b32_e32 v93, v0
	v_mov_b32_e32 v94, v0
	v_mov_b32_e32 v95, v0
	v_mov_b32_e32 v96, v0
	v_mov_b32_e32 v97, v0
	v_mov_b32_e32 v106, v0
	v_mov_b32_e32 v107, v0
	v_mov_b32_e32 v108, v0
	v_mov_b32_e32 v109, v0
	v_mov_b32_e32 v110, v0
	v_mov_b32_e32 v111, v0
	v_mov_b32_e32 v112, v0
	v_mov_b32_e32 v113, v0
	v_mov_b32_e32 v122, v0
	v_mov_b32_e32 v123, v0
	v_mov_b32_e32 v124, v0
	v_mov_b32_e32 v125, v0
	v_mov_b32_e32 v126, v0
	v_mov_b32_e32 v127, v0
	v_mov_b32_e32 v128, v0
	v_mov_b32_e32 v129, v0
	v_xor_b32_e32 v246, 64, v241
	v_xor_b32_e32 v247, 64, v237
	v_add_u32_e32 v248, s50, v247
	v_add_u32_e32 v249, s51, v247
.LBB0_433:
	ds_read_b128 v[130:133], v239
	ds_read_b128 v[134:137], v248
	ds_read_b128 v[138:141], v239 offset:2048
	ds_read_b128 v[142:145], v248 offset:2048
	ds_read_b128 v[146:149], v240
	ds_read_b128 v[150:153], v249
	ds_read_b128 v[154:157], v240 offset:2048
	ds_read_b128 v[158:161], v249 offset:2048
	s_add_u32 s30, s28, 0xfffc0080
	s_addc_u32 s31, s29, -1
	s_cmp_eq_u32 s58, 12
	s_cselect_b32 s35, s9, s31
	s_cselect_b32 s34, s23, s30
	s_cselect_b32 s31, s21, s57
	s_cselect_b32 s30, s55, s56
	v_lshl_add_u64 v[80:81], s[28:29], 0, v[222:223]
	s_add_i32 m0, s36, 0xc000
	ds_read_b128 v[162:165], v241
	ds_read_b128 v[166:169], v246
	ds_read_b128 v[170:173], v241 offset:2048
	ds_read_b128 v[174:177], v246 offset:2048
	ds_read_b128 v[178:181], v241 offset:4096
	ds_read_b128 v[182:185], v246 offset:4096
	ds_read_b128 v[186:189], v241 offset:6144
	ds_read_b128 v[190:193], v246 offset:6144
	global_load_lds_dwordx4 v[80:81], off
	v_lshl_add_u64 v[80:81], s[28:29], 0, v[224:225]
	s_add_i32 m0, s36, 0xe000
	s_nop 0
	global_load_lds_dwordx4 v[80:81], off
	s_waitcnt vmcnt(8)
	s_waitcnt lgkmcnt(0)
	s_barrier
	s_setprio 0
	s_waitcnt lgkmcnt(0)
	v_mfma_f32_16x16x32_bf16 v[126:129], v[130:133], v[162:165], v[126:129]
	v_mfma_f32_16x16x32_bf16 v[122:125], v[138:141], v[162:165], v[122:125]
	v_mfma_f32_16x16x32_bf16 v[110:113], v[130:133], v[170:173], v[110:113]
	v_mfma_f32_16x16x32_bf16 v[106:109], v[138:141], v[170:173], v[106:109]
	v_mfma_f32_16x16x32_bf16 v[94:97], v[130:133], v[178:181], v[94:97]
	v_mfma_f32_16x16x32_bf16 v[90:93], v[138:141], v[178:181], v[90:93]
	v_mfma_f32_16x16x32_bf16 v[76:79], v[130:133], v[186:189], v[76:79]
	v_mfma_f32_16x16x32_bf16 v[72:75], v[138:141], v[186:189], v[72:75]
	v_mfma_f32_16x16x32_bf16 v[126:129], v[134:137], v[166:169], v[126:129]
	v_mfma_f32_16x16x32_bf16 v[122:125], v[142:145], v[166:169], v[122:125]
	v_mfma_f32_16x16x32_bf16 v[110:113], v[134:137], v[174:177], v[110:113]
	v_mfma_f32_16x16x32_bf16 v[106:109], v[142:145], v[174:177], v[106:109]
	v_mfma_f32_16x16x32_bf16 v[94:97], v[134:137], v[182:185], v[94:97]
	v_mfma_f32_16x16x32_bf16 v[90:93], v[142:145], v[182:185], v[90:93]
	v_mfma_f32_16x16x32_bf16 v[76:79], v[134:137], v[190:193], v[76:79]
	v_mfma_f32_16x16x32_bf16 v[72:75], v[142:145], v[190:193], v[72:75]
	s_setprio 0
	s_setprio 0
	v_mfma_f32_16x16x32_bf16 v[118:121], v[146:149], v[162:165], v[118:121]
	v_mfma_f32_16x16x32_bf16 v[114:117], v[154:157], v[162:165], v[114:117]
	v_mfma_f32_16x16x32_bf16 v[102:105], v[146:149], v[170:173], v[102:105]
	v_mfma_f32_16x16x32_bf16 v[98:101], v[154:157], v[170:173], v[98:101]
	v_mfma_f32_16x16x32_bf16 v[86:89], v[146:149], v[178:181], v[86:89]
	v_mfma_f32_16x16x32_bf16 v[80:83], v[154:157], v[178:181], v[82:85]
	v_mfma_f32_16x16x32_bf16 v[68:71], v[146:149], v[186:189], v[68:71]
	v_mfma_f32_16x16x32_bf16 v[64:67], v[154:157], v[186:189], v[64:67]
	v_mfma_f32_16x16x32_bf16 v[118:121], v[150:153], v[166:169], v[118:121]
	v_mfma_f32_16x16x32_bf16 v[114:117], v[158:161], v[166:169], v[114:117]
	v_mfma_f32_16x16x32_bf16 v[102:105], v[150:153], v[174:177], v[102:105]
	v_mfma_f32_16x16x32_bf16 v[98:101], v[158:161], v[174:177], v[98:101]
	v_mfma_f32_16x16x32_bf16 v[86:89], v[150:153], v[182:185], v[86:89]
	v_mfma_f32_16x16x32_bf16 v[80:83], v[158:161], v[182:185], v[80:83]
	v_mfma_f32_16x16x32_bf16 v[68:71], v[150:153], v[190:193], v[68:71]
	v_mfma_f32_16x16x32_bf16 v[64:67], v[158:161], v[190:193], v[64:67]
	s_setprio 0
	s_barrier
	s_add_i32 s59, s50, s33
	v_lshl_add_u64 v[194:195], s[30:31], 0, v[212:213]
	s_mov_b32 m0, s59
	ds_read_b128 v[162:165], v241 offset:16384
	ds_read_b128 v[166:169], v246 offset:16384
	ds_read_b128 v[170:173], v241 offset:18432
	ds_read_b128 v[174:177], v246 offset:18432
	ds_read_b128 v[178:181], v241 offset:20480
	ds_read_b128 v[182:185], v246 offset:20480
	ds_read_b128 v[186:189], v241 offset:22528
	ds_read_b128 v[190:193], v246 offset:22528
	global_load_lds_dwordx4 v[194:195], off
	s_add_i32 m0, s59, 0x2000
	s_add_u32 s60, s30, 0x40000
	v_lshl_add_u64 v[196:197], s[30:31], 0, v[216:217]
	s_addc_u32 s61, s31, 0
	s_add_i32 s59, s51, s33
	global_load_lds_dwordx4 v[196:197], off
	v_lshl_add_u64 v[84:85], s[60:61], 0, v[212:213]
	s_mov_b32 m0, s59
	v_lshl_add_u64 v[198:199], s[34:35], 0, v[210:211]
	global_load_lds_dwordx4 v[84:85], off
	v_lshl_add_u64 v[84:85], s[60:61], 0, v[216:217]
	s_add_i32 m0, s59, 0x2000
	v_lshl_add_u64 v[200:201], s[34:35], 0, v[214:215]
	global_load_lds_dwordx4 v[84:85], off
	s_mov_b32 m0, s36
	s_nop 0
	global_load_lds_dwordx4 v[198:199], off
	s_mov_b32 m0, s37
	s_nop 0
	global_load_lds_dwordx4 v[200:201], off
	s_waitcnt vmcnt(8)
	s_waitcnt lgkmcnt(0)
	s_barrier
	s_setprio 0
	s_waitcnt lgkmcnt(0)
	v_mfma_f32_16x16x32_bf16 v[60:63], v[130:133], v[162:165], v[60:63]
	v_mfma_f32_16x16x32_bf16 v[56:59], v[138:141], v[162:165], v[56:59]
	v_mfma_f32_16x16x32_bf16 v[44:47], v[130:133], v[170:173], v[44:47]
	v_mfma_f32_16x16x32_bf16 v[40:43], v[138:141], v[170:173], v[40:43]
	v_mfma_f32_16x16x32_bf16 v[28:31], v[130:133], v[178:181], v[28:31]
	v_mfma_f32_16x16x32_bf16 v[24:27], v[138:141], v[178:181], v[24:27]
	v_mfma_f32_16x16x32_bf16 v[12:15], v[130:133], v[186:189], v[12:15]
	v_mfma_f32_16x16x32_bf16 v[8:11], v[138:141], v[186:189], v[8:11]
	v_mfma_f32_16x16x32_bf16 v[60:63], v[134:137], v[166:169], v[60:63]
	v_mfma_f32_16x16x32_bf16 v[56:59], v[142:145], v[166:169], v[56:59]
	v_mfma_f32_16x16x32_bf16 v[44:47], v[134:137], v[174:177], v[44:47]
	v_mfma_f32_16x16x32_bf16 v[40:43], v[142:145], v[174:177], v[40:43]
	v_mfma_f32_16x16x32_bf16 v[28:31], v[134:137], v[182:185], v[28:31]
	v_mfma_f32_16x16x32_bf16 v[24:27], v[142:145], v[182:185], v[24:27]
	v_mfma_f32_16x16x32_bf16 v[12:15], v[134:137], v[190:193], v[12:15]
	v_mfma_f32_16x16x32_bf16 v[8:11], v[142:145], v[190:193], v[8:11]
	s_setprio 0
	s_setprio 0
	v_mfma_f32_16x16x32_bf16 v[52:55], v[146:149], v[162:165], v[52:55]
	v_mfma_f32_16x16x32_bf16 v[48:51], v[154:157], v[162:165], v[48:51]
	v_mfma_f32_16x16x32_bf16 v[36:39], v[146:149], v[170:173], v[36:39]
	v_mfma_f32_16x16x32_bf16 v[32:35], v[154:157], v[170:173], v[32:35]
	v_mfma_f32_16x16x32_bf16 v[20:23], v[146:149], v[178:181], v[20:23]
	v_mfma_f32_16x16x32_bf16 v[16:19], v[154:157], v[178:181], v[16:19]
	v_mfma_f32_16x16x32_bf16 v[4:7], v[146:149], v[186:189], v[4:7]
	v_mfma_f32_16x16x32_bf16 v[0:3], v[154:157], v[186:189], v[0:3]
	v_mfma_f32_16x16x32_bf16 v[52:55], v[150:153], v[166:169], v[52:55]
	v_mfma_f32_16x16x32_bf16 v[48:51], v[158:161], v[166:169], v[48:51]
	v_mfma_f32_16x16x32_bf16 v[36:39], v[150:153], v[174:177], v[36:39]
	v_mfma_f32_16x16x32_bf16 v[32:35], v[158:161], v[174:177], v[32:35]
	v_mfma_f32_16x16x32_bf16 v[20:23], v[150:153], v[182:185], v[20:23]
	v_mfma_f32_16x16x32_bf16 v[16:19], v[158:161], v[182:185], v[16:19]
	v_mfma_f32_16x16x32_bf16 v[4:7], v[150:153], v[190:193], v[4:7]
	v_mfma_f32_16x16x32_bf16 v[0:3], v[158:161], v[190:193], v[0:3]
	s_setprio 0
	s_barrier
	s_add_i32 s59, 0, 0x18000
	v_add_u32_e32 v84, s59, v237
	v_add_u32_e32 v250, s59, v247
	s_add_i32 s60, 0, 0x1c000
	ds_read_b128 v[130:133], v84
	ds_read_b128 v[134:137], v250
	ds_read_b128 v[138:141], v84 offset:2048
	ds_read_b128 v[142:145], v250 offset:2048
	v_add_u32_e32 v84, s60, v237
	v_add_u32_e32 v251, s60, v247
	ds_read_b128 v[146:149], v84
	ds_read_b128 v[150:153], v251
	ds_read_b128 v[154:157], v84 offset:2048
	ds_read_b128 v[158:161], v251 offset:2048
	s_add_u32 s34, s34, 0x40000
	s_addc_u32 s35, s35, 0
	s_mov_b32 m0, s38
	v_lshl_add_u64 v[84:85], s[34:35], 0, v[210:211]
	ds_read_b128 v[162:165], v241 offset:32768
	ds_read_b128 v[166:169], v246 offset:32768
	ds_read_b128 v[170:173], v241 offset:34816
	ds_read_b128 v[174:177], v246 offset:34816
	ds_read_b128 v[178:181], v241 offset:36864
	ds_read_b128 v[182:185], v246 offset:36864
	ds_read_b128 v[186:189], v241 offset:38912
	ds_read_b128 v[190:193], v246 offset:38912
	global_load_lds_dwordx4 v[84:85], off
	v_lshl_add_u64 v[84:85], s[34:35], 0, v[214:215]
	s_mov_b32 m0, s39
	s_nop 0
	global_load_lds_dwordx4 v[84:85], off
	s_waitcnt vmcnt(8)
	s_waitcnt lgkmcnt(0)
	s_barrier
	s_setprio 0
	s_waitcnt lgkmcnt(0)
	v_mfma_f32_16x16x32_bf16 v[126:129], v[130:133], v[162:165], v[126:129]
	v_mfma_f32_16x16x32_bf16 v[122:125], v[138:141], v[162:165], v[122:125]
	v_mfma_f32_16x16x32_bf16 v[110:113], v[130:133], v[170:173], v[110:113]
	v_mfma_f32_16x16x32_bf16 v[106:109], v[138:141], v[170:173], v[106:109]
	v_mfma_f32_16x16x32_bf16 v[94:97], v[130:133], v[178:181], v[94:97]
	v_mfma_f32_16x16x32_bf16 v[90:93], v[138:141], v[178:181], v[90:93]
	v_mfma_f32_16x16x32_bf16 v[76:79], v[130:133], v[186:189], v[76:79]
	v_mfma_f32_16x16x32_bf16 v[72:75], v[138:141], v[186:189], v[72:75]
	v_mfma_f32_16x16x32_bf16 v[126:129], v[134:137], v[166:169], v[126:129]
	v_mfma_f32_16x16x32_bf16 v[122:125], v[142:145], v[166:169], v[122:125]
	v_mfma_f32_16x16x32_bf16 v[110:113], v[134:137], v[174:177], v[110:113]
	v_mfma_f32_16x16x32_bf16 v[106:109], v[142:145], v[174:177], v[106:109]
	v_mfma_f32_16x16x32_bf16 v[94:97], v[134:137], v[182:185], v[94:97]
	v_mfma_f32_16x16x32_bf16 v[90:93], v[142:145], v[182:185], v[90:93]
	v_mfma_f32_16x16x32_bf16 v[76:79], v[134:137], v[190:193], v[76:79]
	v_mfma_f32_16x16x32_bf16 v[72:75], v[142:145], v[190:193], v[72:75]
	s_setprio 0
	s_setprio 0
	v_mfma_f32_16x16x32_bf16 v[118:121], v[146:149], v[162:165], v[118:121]
	v_mfma_f32_16x16x32_bf16 v[114:117], v[154:157], v[162:165], v[114:117]
	v_mfma_f32_16x16x32_bf16 v[102:105], v[146:149], v[170:173], v[102:105]
	v_mfma_f32_16x16x32_bf16 v[98:101], v[154:157], v[170:173], v[98:101]
	v_mfma_f32_16x16x32_bf16 v[84:87], v[146:149], v[178:181], v[86:89]
	v_mfma_f32_16x16x32_bf16 v[80:83], v[154:157], v[178:181], v[80:83]
	v_mfma_f32_16x16x32_bf16 v[68:71], v[146:149], v[186:189], v[68:71]
	v_mfma_f32_16x16x32_bf16 v[64:67], v[154:157], v[186:189], v[64:67]
	v_mfma_f32_16x16x32_bf16 v[118:121], v[150:153], v[166:169], v[118:121]
	v_mfma_f32_16x16x32_bf16 v[114:117], v[158:161], v[166:169], v[114:117]
	v_mfma_f32_16x16x32_bf16 v[102:105], v[150:153], v[174:177], v[102:105]
	v_mfma_f32_16x16x32_bf16 v[98:101], v[158:161], v[174:177], v[98:101]
	v_mfma_f32_16x16x32_bf16 v[86:89], v[150:153], v[182:185], v[84:87]
	v_mfma_f32_16x16x32_bf16 v[82:85], v[158:161], v[182:185], v[80:83]
	v_mfma_f32_16x16x32_bf16 v[68:71], v[150:153], v[190:193], v[68:71]
	v_mfma_f32_16x16x32_bf16 v[64:67], v[158:161], v[190:193], v[64:67]
	s_setprio 0
	s_barrier
	s_add_i32 s34, s59, s33
	v_lshl_add_u64 v[80:81], v[194:195], 0, s[16:17]
	s_mov_b32 m0, s34
	ds_read_b128 v[162:165], v241 offset:49152
	ds_read_b128 v[166:169], v246 offset:49152
	ds_read_b128 v[170:173], v241 offset:51200
	ds_read_b128 v[174:177], v246 offset:51200
	ds_read_b128 v[178:181], v241 offset:53248
	ds_read_b128 v[182:185], v246 offset:53248
	ds_read_b128 v[186:189], v241 offset:55296
	ds_read_b128 v[190:193], v246 offset:55296
	global_load_lds_dwordx4 v[80:81], off
	s_add_i32 m0, s34, 0x2000
	s_add_u32 s30, s30, 0x40080
	v_lshl_add_u64 v[80:81], v[196:197], 0, s[16:17]
	s_addc_u32 s31, s31, 0
	s_add_i32 s34, s60, s33
	global_load_lds_dwordx4 v[80:81], off
	v_lshl_add_u64 v[80:81], s[30:31], 0, v[212:213]
	s_mov_b32 m0, s34
	s_nop 0
	global_load_lds_dwordx4 v[80:81], off
	v_lshl_add_u64 v[80:81], s[30:31], 0, v[216:217]
	s_add_i32 m0, s34, 0x2000
	s_nop 0
	global_load_lds_dwordx4 v[80:81], off
	v_lshl_add_u64 v[80:81], v[198:199], 0, s[16:17]
	s_mov_b32 m0, s47
	s_nop 0
	global_load_lds_dwordx4 v[80:81], off
	v_lshl_add_u64 v[80:81], v[200:201], 0, s[16:17]
	s_mov_b32 m0, s48
	s_nop 0
	global_load_lds_dwordx4 v[80:81], off
	s_waitcnt vmcnt(8)
	s_waitcnt lgkmcnt(0)
	s_barrier
	s_setprio 0
	s_waitcnt lgkmcnt(0)
	v_mfma_f32_16x16x32_bf16 v[60:63], v[130:133], v[162:165], v[60:63]
	v_mfma_f32_16x16x32_bf16 v[56:59], v[138:141], v[162:165], v[56:59]
	v_mfma_f32_16x16x32_bf16 v[44:47], v[130:133], v[170:173], v[44:47]
	v_mfma_f32_16x16x32_bf16 v[40:43], v[138:141], v[170:173], v[40:43]
	v_mfma_f32_16x16x32_bf16 v[28:31], v[130:133], v[178:181], v[28:31]
	v_mfma_f32_16x16x32_bf16 v[24:27], v[138:141], v[178:181], v[24:27]
	v_mfma_f32_16x16x32_bf16 v[12:15], v[130:133], v[186:189], v[12:15]
	v_mfma_f32_16x16x32_bf16 v[8:11], v[138:141], v[186:189], v[8:11]
	v_mfma_f32_16x16x32_bf16 v[60:63], v[134:137], v[166:169], v[60:63]
	v_mfma_f32_16x16x32_bf16 v[56:59], v[142:145], v[166:169], v[56:59]
	v_mfma_f32_16x16x32_bf16 v[44:47], v[134:137], v[174:177], v[44:47]
	v_mfma_f32_16x16x32_bf16 v[40:43], v[142:145], v[174:177], v[40:43]
	v_mfma_f32_16x16x32_bf16 v[28:31], v[134:137], v[182:185], v[28:31]
	v_mfma_f32_16x16x32_bf16 v[24:27], v[142:145], v[182:185], v[24:27]
	v_mfma_f32_16x16x32_bf16 v[12:15], v[134:137], v[190:193], v[12:15]
	v_mfma_f32_16x16x32_bf16 v[8:11], v[142:145], v[190:193], v[8:11]
	s_setprio 0
	s_setprio 0
	v_mfma_f32_16x16x32_bf16 v[52:55], v[146:149], v[162:165], v[52:55]
	v_mfma_f32_16x16x32_bf16 v[48:51], v[154:157], v[162:165], v[48:51]
	v_mfma_f32_16x16x32_bf16 v[36:39], v[146:149], v[170:173], v[36:39]
	v_mfma_f32_16x16x32_bf16 v[32:35], v[154:157], v[170:173], v[32:35]
	v_mfma_f32_16x16x32_bf16 v[20:23], v[146:149], v[178:181], v[20:23]
	v_mfma_f32_16x16x32_bf16 v[16:19], v[154:157], v[178:181], v[16:19]
	v_mfma_f32_16x16x32_bf16 v[4:7], v[146:149], v[186:189], v[4:7]
	v_mfma_f32_16x16x32_bf16 v[0:3], v[154:157], v[186:189], v[0:3]
	v_mfma_f32_16x16x32_bf16 v[52:55], v[150:153], v[166:169], v[52:55]
	v_mfma_f32_16x16x32_bf16 v[48:51], v[158:161], v[166:169], v[48:51]
	v_mfma_f32_16x16x32_bf16 v[36:39], v[150:153], v[174:177], v[36:39]
	v_mfma_f32_16x16x32_bf16 v[32:35], v[158:161], v[174:177], v[32:35]
	v_mfma_f32_16x16x32_bf16 v[20:23], v[150:153], v[182:185], v[20:23]
	v_mfma_f32_16x16x32_bf16 v[16:19], v[158:161], v[182:185], v[16:19]
	v_mfma_f32_16x16x32_bf16 v[4:7], v[150:153], v[190:193], v[4:7]
	v_mfma_f32_16x16x32_bf16 v[0:3], v[158:161], v[190:193], v[0:3]
	s_setprio 0
	s_barrier
	s_add_i32 s58, s58, 2
	s_add_u32 s28, s28, 0x100
	s_addc_u32 s29, s29, 0
	s_add_u32 s56, s56, 0x100
	s_addc_u32 s57, s57, 0
	s_cmp_gt_u32 s58, 13
	s_cbranch_scc0 .LBB0_433
	s_and_b64 vcc, exec, s[18:19]
	s_cbranch_vccnz .LBB0_438
	v_lshl_add_u32 v234, s10, 8, v221
	s_cmp_gt_i32 s8, 3
	s_mov_b64 s[28:29], -1
	s_cbranch_scc1 .LBB0_439

.LBB0_1013:
	s_andn2_b64 vcc, exec, s[0:1]
	s_cbranch_vccnz .LBB0_1049
	v_ashrrev_i32_e32 v1, 31, v8
	v_lshrrev_b32_e32 v1, 26, v1
	v_add_u32_e32 v1, v8, v1
	v_ashrrev_i32_e32 v9, 6, v1
	v_bfe_i32 v1, v8, 27, 1
	v_lshlrev_b32_e32 v0, 4, v8
	v_lshrrev_b32_e32 v1, 22, v1
	v_add_u32_e32 v1, v0, v1
	v_and_b32_e32 v1, 0xfffffc00, v1
	v_sub_u32_e32 v1, v0, v1
	v_lshrrev_b32_e32 v2, 4, v1
	v_bitop3_b32 v2, v2, v1, 32 bitop3:0x6c
	v_ashrrev_i32_e32 v1, 31, v1
	v_lshrrev_b32_e32 v1, 26, v1
	v_add_u32_e32 v1, v2, v1
	v_ashrrev_i32_e32 v10, 6, v1
	v_lshlrev_b32_e32 v3, 3, v9
	v_mul_i32_i24_e32 v4, 64, v10
	v_and_b32_e32 v3, -16, v3
	v_sub_u32_e32 v2, v2, v4
	v_mov_b32_e32 v4, 1
	v_add_u32_e32 v1, v10, v3
	v_lshlrev_b32_e32 v3, 5, v9
	v_ashrrev_i16_sdwa v2, v4, sext(v2) dst_sel:DWORD dst_unused:UNUSED_PAD src0_sel:DWORD src1_sel:BYTE_0
	v_and_b32_e32 v3, 32, v3
	s_waitcnt lgkmcnt(0)
	v_bfe_i32 v11, v2, 0, 16
	v_and_b32_e32 v6, 3, v10
	s_mov_b32 s1, 0x1fffe0
	v_add_lshl_u32 v3, v3, v11, 1
	v_add_u32_e32 v0, 0x2000, v0
	v_lshlrev_b32_e32 v2, 1, v1
	v_lshrrev_b32_e32 v5, 2, v1
	v_and_or_b32 v6, v1, s1, v6
	v_lshrrev_b32_e32 v250, 6, v236
	v_and_b32_e32 v251, 63, v236
	v_lshrrev_b32_e32 v252, 3, v251
	v_and_b32_e32 v251, 7, v251
	v_xor_b32_e32 v251, v251, v252
	v_lshlrev_b32_e32 v251, 4, v251
	v_lshl_add_u32 v253, v250, 3, v252
	v_lshl_add_u32 v246, v253, 11, v251
	v_add_u32_e32 v247, 0x20000, v246
	v_lshrrev_b32_e32 v253, 2, v250
	v_lshlrev_b32_e32 v253, 5, v253
	v_and_b32_e32 v248, 1, v250
	v_lshl_add_u32 v253, v248, 4, v253
	v_bfe_u32 v248, v250, 1, 1
	v_lshl_add_u32 v253, v248, 2, v253
	v_lshrrev_b32_e32 v248, 2, v252
	v_lshl_add_u32 v253, v248, 3, v253
	v_and_b32_e32 v248, 3, v252
	v_add_u32_e32 v253, v253, v248
	v_lshl_add_u32 v248, v253, 11, v251
	v_add_u32_e32 v249, 0x20000, v248
	v_lshl_add_u32 v136, v1, 11, v3
	v_mov_b32_e32 v252, v136
	v_mov_b32_e32 v136, v246
	v_ashrrev_i32_e32 v1, 31, v0
	v_lshrrev_b32_e32 v1, 22, v1
	v_add_u32_e32 v1, v0, v1
	v_ashrrev_i32_e32 v12, 10, v1
	v_mul_i32_i24_e32 v1, 0x400, v12
	v_sub_u32_e32 v0, v0, v1
	v_and_b32_e32 v2, 24, v2
	v_and_b32_e32 v5, 4, v5
	v_lshrrev_b32_e32 v1, 4, v0
	v_or3_b32 v2, v6, v5, v2
	v_bitop3_b32 v0, v1, v0, 32 bitop3:0x6c
	v_lshl_add_u32 v138, v2, 11, v3
	v_mov_b32_e32 v138, v248
	v_ashrrev_i32_e32 v2, 31, v0
	v_lshrrev_b32_e32 v2, 26, v2
	v_add_u32_e32 v2, v0, v2
	v_lshlrev_b32_e32 v1, 3, v12
	v_ashrrev_i32_e32 v13, 6, v2
	v_and_b32_e32 v2, 0xc0, v2
	v_and_b32_e32 v1, -16, v1
	v_sub_u32_e32 v0, v0, v2
	s_add_u32 s2, s82, 0x2b00000
	v_add_u32_e32 v1, v13, v1
	v_ashrrev_i16_sdwa v0, v4, sext(v0) dst_sel:DWORD dst_unused:UNUSED_PAD src0_sel:DWORD src1_sel:BYTE_0
	v_and_b32_e32 v4, 3, v13
	s_addc_u32 s3, s83, 0
	v_and_or_b32 v4, v1, s1, v4
	s_ashr_i32 s1, s18, 6
	s_ashr_i32 s29, s28, 31
	s_ashr_i32 s31, s30, 31
	s_ashr_i32 s0, s18, 8
	s_lshl_b32 s33, s1, 10
	s_lshl_b64 s[6:7], s[28:29], 19
	s_lshl_b64 s[8:9], s[30:31], 19
	s_add_u32 s36, s2, s8
	v_lshlrev_b32_e32 v3, 5, v12
	v_bfe_i32 v14, v0, 0, 16
	v_lshlrev_b32_e32 v0, 1, v1
	v_lshrrev_b32_e32 v2, 2, v1
	s_addc_u32 s37, s3, s9
	s_add_i32 s31, s33, 0
	v_and_b32_e32 v3, 32, v3
	v_and_b32_e32 v0, 24, v0
	v_and_b32_e32 v2, 4, v2
	s_add_i32 m0, s31, 0x10000
	v_or3_b32 v0, v4, v2, v0
	v_add_lshl_u32 v2, v3, v14, 1
	global_load_lds_dwordx4 v138, s[36:37]
	s_add_i32 m0, s31, 0x12000
	v_lshl_add_u32 v142, v0, 11, v2
	v_mov_b32_e32 v142, v249
	s_add_u32 s8, s36, 0x40000
	global_load_lds_dwordx4 v142, s[36:37]
	s_addc_u32 s9, s37, 0
	s_add_i32 m0, s31, 0x14000
	v_lshl_add_u32 v140, v1, 11, v2
	v_mov_b32_e32 v253, v140
	v_mov_b32_e32 v140, v247
	global_load_lds_dwordx4 v138, s[8:9]
	s_add_i32 m0, s31, 0x16000
	s_add_u32 s34, s90, s6
	s_addc_u32 s35, s91, s7
	s_add_i32 s40, s31, 0x2000
	global_load_lds_dwordx4 v142, s[8:9]
	s_mov_b32 m0, s31
	s_add_u32 s6, s34, 0x40000
	global_load_lds_dwordx4 v136, s[34:35]
	s_mov_b32 m0, s40
	s_addc_u32 s7, s35, 0
	s_add_i32 s41, s31, 0x4000
	global_load_lds_dwordx4 v140, s[34:35]
	s_mov_b32 m0, s41
	s_add_i32 s42, s31, 0x6000
	global_load_lds_dwordx4 v136, s[6:7]
	s_mov_b32 m0, s42
	v_mov_b32_e32 v139, 0
	global_load_lds_dwordx4 v140, s[6:7]
	v_mov_b32_e32 v143, v139
	v_mov_b32_e32 v137, v139
	v_mov_b32_e32 v141, v139
	s_cmp_eq_u32 s0, 1
	s_mov_b32 s43, 0
	v_lshl_add_u64 v[6:7], s[36:37], 0, v[138:139]
	v_lshl_add_u64 v[4:5], s[36:37], 0, v[142:143]
	v_lshl_add_u64 v[0:1], s[34:35], 0, v[136:137]
	s_cselect_b64 s[8:9], -1, 0
	s_cmp_lg_u32 s0, 1
	v_lshl_add_u64 v[2:3], s[34:35], 0, v[140:141]
	s_cbranch_scc1 .LBB0_1016
	s_barrier
.LBB0_1016:
	s_add_u32 s44, s82, 0x15000
	s_addc_u32 s45, s83, 0
	v_readlane_b32 s48, v254, 3
	s_add_u32 s10, s82, 0x16000000
	v_readlane_b32 s56, v254, 11
	v_readlane_b32 s57, v254, 12
	s_addc_u32 s11, s83, 0
	s_mov_b64 s[12:13], s[56:57]
	s_add_u32 s12, s12, 0x2000
	s_addc_u32 s13, s13, 0
	s_add_u32 s46, s82, 0x17000
	s_addc_u32 s47, s83, 0
	s_add_u32 s14, s82, 0x2f00000
	s_addc_u32 s15, s83, 0
	s_lshl_b32 s1, s1, 5
	s_mov_b64 s[16:17], 0x80
	v_readlane_b32 s49, v254, 4
	s_and_b32 s20, s1, 0x60
	s_add_i32 m0, s31, 0x18000
	v_lshl_add_u64 v[6:7], v[6:7], 0, s[16:17]
	s_lshl_b32 s19, s0, 13
	s_lshl_b32 s1, s20, 7
	s_waitcnt vmcnt(2)
	s_barrier
	global_load_lds_dwordx4 v[6:7], off
	v_lshl_add_u64 v[4:5], v[4:5], 0, s[16:17]
	s_add_i32 m0, s31, 0x1a000
	s_add_i32 s48, s31, 0x8000
	s_add_i32 s49, s31, 0xa000
	global_load_lds_dwordx4 v[4:5], off
	v_lshl_add_u64 v[0:1], v[0:1], 0, s[16:17]
	s_mov_b32 m0, s48
	s_add_u32 s6, s36, 0x40080
	global_load_lds_dwordx4 v[0:1], off
	v_lshl_add_u64 v[0:1], v[2:3], 0, s[16:17]
	s_mov_b32 m0, s49
	s_addc_u32 s7, s37, 0
	global_load_lds_dwordx4 v[0:1], off
	s_add_i32 m0, s31, 0x1c000
	v_lshl_add_u64 v[0:1], s[6:7], 0, v[138:139]
	global_load_lds_dwordx4 v[0:1], off
	v_lshl_add_u64 v[0:1], s[6:7], 0, v[142:143]
	s_add_i32 m0, s31, 0x1e000
	v_readlane_b32 s53, v254, 8
	global_load_lds_dwordx4 v[0:1], off
	v_bfe_u32 v1, v8, 4, 2
	v_and_b32_e32 v0, 15, v8
	v_lshlrev_b32_e32 v2, 4, v1
	v_lshl_or_b32 v184, s0, 6, v0
	v_lshl_or_b32 v0, v0, 6, v2
	v_lshlrev_b32_e32 v2, 2, v8
	v_and_b32_e32 v2, 32, v2
	v_bitop3_b32 v3, v0, s19, v2 bitop3:0xde
	v_bitop3_b32 v185, v0, s1, v2 bitop3:0xde
	v_lshlrev_b32_e32 v0, 14, v9
	v_and_b32_e32 v0, 0xffff8000, v0
	v_cmp_eq_u32_e64 s[0:1], 0, v1
	v_lshl_or_b32 v186, v1, 3, s20
	v_lshl_add_u32 v0, v10, 11, v0
	v_and_b32_e32 v1, 1, v9
	v_lshl_or_b32 v0, v1, 6, v0
	v_lshl_add_u32 v144, v11, 1, v0
	v_lshlrev_b32_e32 v0, 14, v12
	v_and_b32_e32 v0, 0xffff8000, v0
	v_lshl_add_u32 v0, v13, 11, v0
	v_and_b32_e32 v1, 1, v12
	v_readlane_b32 s54, v254, 9
	s_waitcnt vmcnt(6)
	s_cmpk_lt_u32 s18, 0x100
	v_lshl_or_b32 v0, v1, 6, v0
	v_readlane_b32 s50, v254, 5
	v_readlane_b32 s51, v254, 6
	v_readlane_b32 s52, v254, 7
	s_cselect_b64 s[18:19], -1, 0
	v_lshl_add_u32 v146, v14, 1, v0
	s_add_i32 s53, 0, 0x10000
	s_add_i32 s54, 0, 0x14000
	v_mbcnt_lo_u32_b32 v0, -1, 0
	s_ashr_i32 s50, s86, 31
	s_mov_b32 s51, s86
	s_ashr_i32 s52, s96, 31
	v_mov_b32_e32 v145, v139
	v_mov_b32_e32 v147, v139
	v_mov_b64_e32 v[148:149], 0x200
	v_mov_b64_e32 v[150:151], 0x1ff
	v_add_u32_e32 v187, s53, v185
	v_add_u32_e32 v188, s54, v185
	v_add_u32_e32 v189, 0, v3
	v_mbcnt_hi_u32_b32 v190, -1, v0
	v_readlane_b32 s55, v254, 10
	v_readlane_b32 s58, v254, 13
	v_readlane_b32 s59, v254, 14
	v_readlane_b32 s60, v254, 15
	v_readlane_b32 s61, v254, 16
	v_readlane_b32 s62, v254, 17
	v_readlane_b32 s63, v254, 18
	s_barrier
	v_sub_u32_e32 v144, v144, v252
	v_add_u32_e32 v144, v144, v136
	v_sub_u32_e32 v146, v146, v253
	v_add_u32_e32 v146, v146, v140
	v_and_b32_e32 v250, 63, v236
	v_and_b32_e32 v251, 15, v250
	v_lshrrev_b32_e32 v252, 4, v250
	v_and_b32_e32 v253, 7, v251
	v_xor_b32_e32 v252, v252, v253
	v_lshlrev_b32_e32 v252, 4, v252
	v_lshl_add_u32 v252, v251, 7, v252
	v_lshrrev_b32_e32 v250, 6, v236
	v_lshrrev_b32_e32 v251, 2, v250
	v_lshl_add_u32 v189, v251, 13, v252
	v_and_b32_e32 v251, 3, v250
	v_lshl_add_u32 v185, v251, 12, v252
	v_add_u32_e32 v187, s53, v185
	v_add_u32_e32 v188, s54, v185
	s_branch .LBB0_1019

.LBB0_1025:
	s_ashr_i32 s23, s22, 31
	s_lshl_b64 s[24:25], s[22:23], 19
	s_add_u32 s24, s90, s24
	s_addc_u32 s25, s91, s25
	s_and_b64 s[26:27], s[6:7], exec
	s_cselect_b32 s23, s25, s35
	s_cselect_b32 s29, s24, s34
	s_ashr_i32 s21, s20, 31
	s_lshl_b64 s[26:27], s[20:21], 19
	s_add_u32 s26, s2, s26
	s_addc_u32 s27, s3, s27
	s_and_b64 s[38:39], s[6:7], exec
	s_cselect_b32 s21, s27, s37
	s_cselect_b32 s55, s26, s36
	s_add_u32 s34, s34, 0x40080
	s_addc_u32 s35, s35, 0
	s_add_u32 s56, s36, 0x100
	v_mov_b32_e32 v0, 0
	s_addc_u32 s57, s37, 0
	s_mov_b32 s58, -2
	s_waitcnt lgkmcnt(0)
	v_mov_b32_e32 v1, v0
	v_mov_b32_e32 v2, v0
	v_mov_b32_e32 v3, v0
	v_mov_b32_e32 v4, v0
	v_mov_b32_e32 v5, v0
	v_mov_b32_e32 v6, v0
	v_mov_b32_e32 v7, v0
	v_mov_b32_e32 v16, v0
	v_mov_b32_e32 v17, v0
	v_mov_b32_e32 v18, v0
	v_mov_b32_e32 v19, v0
	v_mov_b32_e32 v20, v0
	v_mov_b32_e32 v21, v0
	v_mov_b32_e32 v22, v0
	v_mov_b32_e32 v23, v0
	v_mov_b32_e32 v32, v0
	v_mov_b32_e32 v33, v0
	v_mov_b32_e32 v34, v0
	v_mov_b32_e32 v35, v0
	v_mov_b32_e32 v36, v0
	v_mov_b32_e32 v37, v0
	v_mov_b32_e32 v38, v0
	v_mov_b32_e32 v39, v0
	v_mov_b32_e32 v48, v0
	v_mov_b32_e32 v49, v0
	v_mov_b32_e32 v50, v0
	v_mov_b32_e32 v51, v0
	v_mov_b32_e32 v52, v0
	v_mov_b32_e32 v53, v0
	v_mov_b32_e32 v54, v0
	v_mov_b32_e32 v55, v0
	v_mov_b32_e32 v8, v0
	v_mov_b32_e32 v9, v0
	v_mov_b32_e32 v10, v0
	v_mov_b32_e32 v11, v0
	v_mov_b32_e32 v12, v0
	v_mov_b32_e32 v13, v0
	v_mov_b32_e32 v14, v0
	v_mov_b32_e32 v15, v0
	v_mov_b32_e32 v24, v0
	v_mov_b32_e32 v25, v0
	v_mov_b32_e32 v26, v0
	v_mov_b32_e32 v27, v0
	v_mov_b32_e32 v28, v0
	v_mov_b32_e32 v29, v0
	v_mov_b32_e32 v30, v0
	v_mov_b32_e32 v31, v0
	v_mov_b32_e32 v40, v0
	v_mov_b32_e32 v41, v0
	v_mov_b32_e32 v42, v0
	v_mov_b32_e32 v43, v0
	v_mov_b32_e32 v44, v0
	v_mov_b32_e32 v45, v0
	v_mov_b32_e32 v46, v0
	v_mov_b32_e32 v47, v0
	v_mov_b32_e32 v56, v0
	v_mov_b32_e32 v57, v0
	v_mov_b32_e32 v58, v0
	v_mov_b32_e32 v59, v0
	v_mov_b32_e32 v60, v0
	v_mov_b32_e32 v61, v0
	v_mov_b32_e32 v62, v0
	v_mov_b32_e32 v63, v0
	v_mov_b32_e32 v64, v0
	v_mov_b32_e32 v65, v0
	v_mov_b32_e32 v66, v0
	v_mov_b32_e32 v67, v0
	v_mov_b32_e32 v68, v0
	v_mov_b32_e32 v69, v0
	v_mov_b32_e32 v70, v0
	v_mov_b32_e32 v71, v0
	v_mov_b32_e32 v80, v0
	v_mov_b32_e32 v81, v0
	v_mov_b32_e32 v82, v0
	v_mov_b32_e32 v83, v0
	v_mov_b32_e32 v84, v0
	v_mov_b32_e32 v85, v0
	v_mov_b32_e32 v86, v0
	v_mov_b32_e32 v87, v0
	v_mov_b32_e32 v96, v0
	v_mov_b32_e32 v97, v0
	v_mov_b32_e32 v98, v0
	v_mov_b32_e32 v99, v0
	v_mov_b32_e32 v100, v0
	v_mov_b32_e32 v101, v0
	v_mov_b32_e32 v102, v0
	v_mov_b32_e32 v103, v0
	v_mov_b32_e32 v112, v0
	v_mov_b32_e32 v113, v0
	v_mov_b32_e32 v114, v0
	v_mov_b32_e32 v115, v0
	v_mov_b32_e32 v116, v0
	v_mov_b32_e32 v117, v0
	v_mov_b32_e32 v118, v0
	v_mov_b32_e32 v119, v0
	v_mov_b32_e32 v72, v0
	s_waitcnt vmcnt(0)
	v_mov_b32_e32 v73, v0
	v_mov_b32_e32 v74, v0
	v_mov_b32_e32 v75, v0
	v_mov_b32_e32 v76, v0
	v_mov_b32_e32 v77, v0
	v_mov_b32_e32 v78, v0
	v_mov_b32_e32 v79, v0
	v_mov_b32_e32 v88, v0
	v_mov_b32_e32 v89, v0
	v_mov_b32_e32 v90, v0
	v_mov_b32_e32 v91, v0
	v_mov_b32_e32 v92, v0
	v_mov_b32_e32 v93, v0
	v_mov_b32_e32 v94, v0
	v_mov_b32_e32 v95, v0
	v_mov_b32_e32 v104, v0
	v_mov_b32_e32 v105, v0
	v_mov_b32_e32 v106, v0
	v_mov_b32_e32 v107, v0
	v_mov_b32_e32 v108, v0
	v_mov_b32_e32 v109, v0
	v_mov_b32_e32 v110, v0
	v_mov_b32_e32 v111, v0
	v_mov_b32_e32 v120, v0
	v_mov_b32_e32 v121, v0
	v_mov_b32_e32 v122, v0
	v_mov_b32_e32 v123, v0
	v_mov_b32_e32 v124, v0
	v_mov_b32_e32 v125, v0
	v_mov_b32_e32 v126, v0
	v_mov_b32_e32 v127, v0
	v_xor_b32_e32 v246, 64, v189
	v_xor_b32_e32 v247, 64, v185
	v_add_u32_e32 v248, s53, v247
	v_add_u32_e32 v249, s54, v247
.LBB0_1026:
	ds_read_b128 v[128:131], v187
	ds_read_b128 v[132:135], v248
	ds_read_b128 v[152:155], v187 offset:2048
	ds_read_b128 v[156:159], v248 offset:2048
	ds_read_b128 v[160:163], v188
	ds_read_b128 v[164:167], v249
	ds_read_b128 v[168:171], v188 offset:2048
	ds_read_b128 v[172:175], v249 offset:2048
	s_add_u32 s36, s34, 0xfffc0080
	s_addc_u32 s37, s35, -1
	s_cmp_eq_u32 s58, 12
	s_cselect_b32 s39, s23, s37
	s_cselect_b32 s38, s29, s36
	s_cselect_b32 s37, s21, s57
	s_cselect_b32 s36, s55, s56
	v_lshl_add_u64 v[216:217], s[34:35], 0, v[144:145]
	s_add_i32 m0, s31, 0xc000
	ds_read_b128 v[176:179], v189
	ds_read_b128 v[180:183], v246
	ds_read_b128 v[192:195], v189 offset:2048
	ds_read_b128 v[196:199], v246 offset:2048
	ds_read_b128 v[200:203], v189 offset:4096
	ds_read_b128 v[204:207], v246 offset:4096
	ds_read_b128 v[208:211], v189 offset:6144
	ds_read_b128 v[212:215], v246 offset:6144
	global_load_lds_dwordx4 v[216:217], off
	v_lshl_add_u64 v[216:217], s[34:35], 0, v[146:147]
	s_add_i32 m0, s31, 0xe000
	s_nop 0
	global_load_lds_dwordx4 v[216:217], off
	s_waitcnt vmcnt(8)
	s_waitcnt lgkmcnt(0)
	s_barrier
	s_setprio 0
	s_waitcnt lgkmcnt(0)
	v_mfma_f32_16x16x32_bf16 v[124:127], v[128:131], v[176:179], v[124:127]
	v_mfma_f32_16x16x32_bf16 v[120:123], v[152:155], v[176:179], v[120:123]
	v_mfma_f32_16x16x32_bf16 v[108:111], v[128:131], v[192:195], v[108:111]
	v_mfma_f32_16x16x32_bf16 v[104:107], v[152:155], v[192:195], v[104:107]
	v_mfma_f32_16x16x32_bf16 v[92:95], v[128:131], v[200:203], v[92:95]
	v_mfma_f32_16x16x32_bf16 v[88:91], v[152:155], v[200:203], v[88:91]
	v_mfma_f32_16x16x32_bf16 v[76:79], v[128:131], v[208:211], v[76:79]
	v_mfma_f32_16x16x32_bf16 v[72:75], v[152:155], v[208:211], v[72:75]
	v_mfma_f32_16x16x32_bf16 v[124:127], v[132:135], v[180:183], v[124:127]
	v_mfma_f32_16x16x32_bf16 v[120:123], v[156:159], v[180:183], v[120:123]
	v_mfma_f32_16x16x32_bf16 v[108:111], v[132:135], v[196:199], v[108:111]
	v_mfma_f32_16x16x32_bf16 v[104:107], v[156:159], v[196:199], v[104:107]
	v_mfma_f32_16x16x32_bf16 v[92:95], v[132:135], v[204:207], v[92:95]
	v_mfma_f32_16x16x32_bf16 v[88:91], v[156:159], v[204:207], v[88:91]
	v_mfma_f32_16x16x32_bf16 v[76:79], v[132:135], v[212:215], v[76:79]
	v_mfma_f32_16x16x32_bf16 v[72:75], v[156:159], v[212:215], v[72:75]
	s_setprio 0
	s_setprio 0
	v_mfma_f32_16x16x32_bf16 v[116:119], v[160:163], v[176:179], v[116:119]
	v_mfma_f32_16x16x32_bf16 v[112:115], v[168:171], v[176:179], v[112:115]
	v_mfma_f32_16x16x32_bf16 v[100:103], v[160:163], v[192:195], v[100:103]
	v_mfma_f32_16x16x32_bf16 v[96:99], v[168:171], v[192:195], v[96:99]
	v_mfma_f32_16x16x32_bf16 v[84:87], v[160:163], v[200:203], v[84:87]
	v_mfma_f32_16x16x32_bf16 v[80:83], v[168:171], v[200:203], v[80:83]
	v_mfma_f32_16x16x32_bf16 v[68:71], v[160:163], v[208:211], v[68:71]
	v_mfma_f32_16x16x32_bf16 v[64:67], v[168:171], v[208:211], v[64:67]
	v_mfma_f32_16x16x32_bf16 v[116:119], v[164:167], v[180:183], v[116:119]
	v_mfma_f32_16x16x32_bf16 v[112:115], v[172:175], v[180:183], v[112:115]
	v_mfma_f32_16x16x32_bf16 v[100:103], v[164:167], v[196:199], v[100:103]
	v_mfma_f32_16x16x32_bf16 v[96:99], v[172:175], v[196:199], v[96:99]
	v_mfma_f32_16x16x32_bf16 v[84:87], v[164:167], v[204:207], v[84:87]
	v_mfma_f32_16x16x32_bf16 v[80:83], v[172:175], v[204:207], v[80:83]
	v_mfma_f32_16x16x32_bf16 v[68:71], v[164:167], v[212:215], v[68:71]
	v_mfma_f32_16x16x32_bf16 v[64:67], v[172:175], v[212:215], v[64:67]
	s_setprio 0
	s_barrier
	s_add_i32 s59, s53, s33
	v_lshl_add_u64 v[216:217], s[36:37], 0, v[138:139]
	s_mov_b32 m0, s59
	ds_read_b128 v[176:179], v189 offset:16384
	ds_read_b128 v[180:183], v246 offset:16384
	ds_read_b128 v[192:195], v189 offset:18432
	ds_read_b128 v[196:199], v246 offset:18432
	ds_read_b128 v[200:203], v189 offset:20480
	ds_read_b128 v[204:207], v246 offset:20480
	ds_read_b128 v[208:211], v189 offset:22528
	ds_read_b128 v[212:215], v246 offset:22528
	global_load_lds_dwordx4 v[216:217], off
	s_add_i32 m0, s59, 0x2000
	s_add_u32 s60, s36, 0x40000
	v_lshl_add_u64 v[218:219], s[36:37], 0, v[142:143]
	s_addc_u32 s61, s37, 0
	s_add_i32 s59, s54, s33
	global_load_lds_dwordx4 v[218:219], off
	v_lshl_add_u64 v[220:221], s[60:61], 0, v[138:139]
	s_mov_b32 m0, s59
	v_lshl_add_u64 v[222:223], s[38:39], 0, v[140:141]
	global_load_lds_dwordx4 v[220:221], off
	v_lshl_add_u64 v[220:221], s[60:61], 0, v[142:143]
	s_add_i32 m0, s59, 0x2000
	s_nop 0
	global_load_lds_dwordx4 v[220:221], off
	v_lshl_add_u64 v[220:221], s[38:39], 0, v[136:137]
	s_mov_b32 m0, s31
	s_nop 0
	global_load_lds_dwordx4 v[220:221], off
	s_mov_b32 m0, s40
	s_nop 0
	global_load_lds_dwordx4 v[222:223], off
	s_waitcnt vmcnt(8)
	s_waitcnt lgkmcnt(0)
	s_barrier
	s_setprio 0
	s_waitcnt lgkmcnt(0)
	v_mfma_f32_16x16x32_bf16 v[60:63], v[128:131], v[176:179], v[60:63]
	v_mfma_f32_16x16x32_bf16 v[56:59], v[152:155], v[176:179], v[56:59]
	v_mfma_f32_16x16x32_bf16 v[44:47], v[128:131], v[192:195], v[44:47]
	v_mfma_f32_16x16x32_bf16 v[40:43], v[152:155], v[192:195], v[40:43]
	v_mfma_f32_16x16x32_bf16 v[28:31], v[128:131], v[200:203], v[28:31]
	v_mfma_f32_16x16x32_bf16 v[24:27], v[152:155], v[200:203], v[24:27]
	v_mfma_f32_16x16x32_bf16 v[12:15], v[128:131], v[208:211], v[12:15]
	v_mfma_f32_16x16x32_bf16 v[8:11], v[152:155], v[208:211], v[8:11]
	v_mfma_f32_16x16x32_bf16 v[60:63], v[132:135], v[180:183], v[60:63]
	v_mfma_f32_16x16x32_bf16 v[56:59], v[156:159], v[180:183], v[56:59]
	v_mfma_f32_16x16x32_bf16 v[44:47], v[132:135], v[196:199], v[44:47]
	v_mfma_f32_16x16x32_bf16 v[40:43], v[156:159], v[196:199], v[40:43]
	v_mfma_f32_16x16x32_bf16 v[28:31], v[132:135], v[204:207], v[28:31]
	v_mfma_f32_16x16x32_bf16 v[24:27], v[156:159], v[204:207], v[24:27]
	v_mfma_f32_16x16x32_bf16 v[12:15], v[132:135], v[212:215], v[12:15]
	v_mfma_f32_16x16x32_bf16 v[8:11], v[156:159], v[212:215], v[8:11]
	s_setprio 0
	s_setprio 0
	v_mfma_f32_16x16x32_bf16 v[52:55], v[160:163], v[176:179], v[52:55]
	v_mfma_f32_16x16x32_bf16 v[48:51], v[168:171], v[176:179], v[48:51]
	v_mfma_f32_16x16x32_bf16 v[36:39], v[160:163], v[192:195], v[36:39]
	v_mfma_f32_16x16x32_bf16 v[32:35], v[168:171], v[192:195], v[32:35]
	v_mfma_f32_16x16x32_bf16 v[20:23], v[160:163], v[200:203], v[20:23]
	v_mfma_f32_16x16x32_bf16 v[16:19], v[168:171], v[200:203], v[16:19]
	v_mfma_f32_16x16x32_bf16 v[4:7], v[160:163], v[208:211], v[4:7]
	v_mfma_f32_16x16x32_bf16 v[0:3], v[168:171], v[208:211], v[0:3]
	v_mfma_f32_16x16x32_bf16 v[52:55], v[164:167], v[180:183], v[52:55]
	v_mfma_f32_16x16x32_bf16 v[48:51], v[172:175], v[180:183], v[48:51]
	v_mfma_f32_16x16x32_bf16 v[36:39], v[164:167], v[196:199], v[36:39]
	v_mfma_f32_16x16x32_bf16 v[32:35], v[172:175], v[196:199], v[32:35]
	v_mfma_f32_16x16x32_bf16 v[20:23], v[164:167], v[204:207], v[20:23]
	v_mfma_f32_16x16x32_bf16 v[16:19], v[172:175], v[204:207], v[16:19]
	v_mfma_f32_16x16x32_bf16 v[4:7], v[164:167], v[212:215], v[4:7]
	v_mfma_f32_16x16x32_bf16 v[0:3], v[172:175], v[212:215], v[0:3]
	s_setprio 0
	s_barrier
	s_add_i32 s59, 0, 0x18000
	s_add_i32 s60, 0, 0x1c000
	v_add_u32_e32 v156, s59, v185
	v_add_u32_e32 v250, s59, v247
	v_add_u32_e32 v172, s60, v185
	v_add_u32_e32 v251, s60, v247
	ds_read_b128 v[128:131], v156
	ds_read_b128 v[132:135], v250
	ds_read_b128 v[152:155], v156 offset:2048
	ds_read_b128 v[156:159], v250 offset:2048
	ds_read_b128 v[160:163], v172
	ds_read_b128 v[164:167], v251
	ds_read_b128 v[168:171], v172 offset:2048
	ds_read_b128 v[172:175], v251 offset:2048
	s_add_u32 s38, s38, 0x40000
	s_addc_u32 s39, s39, 0
	s_mov_b32 m0, s41
	v_lshl_add_u64 v[224:225], s[38:39], 0, v[136:137]
	ds_read_b128 v[176:179], v189 offset:32768
	ds_read_b128 v[180:183], v246 offset:32768
	ds_read_b128 v[192:195], v189 offset:34816
	ds_read_b128 v[196:199], v246 offset:34816
	ds_read_b128 v[200:203], v189 offset:36864
	ds_read_b128 v[204:207], v246 offset:36864
	ds_read_b128 v[208:211], v189 offset:38912
	ds_read_b128 v[212:215], v246 offset:38912
	global_load_lds_dwordx4 v[224:225], off
	v_lshl_add_u64 v[224:225], s[38:39], 0, v[140:141]
	s_mov_b32 m0, s42
	s_nop 0
	global_load_lds_dwordx4 v[224:225], off
	s_waitcnt vmcnt(8)
	s_waitcnt lgkmcnt(0)
	s_barrier
	s_setprio 0
	s_waitcnt lgkmcnt(0)
	v_mfma_f32_16x16x32_bf16 v[124:127], v[128:131], v[176:179], v[124:127]
	v_mfma_f32_16x16x32_bf16 v[120:123], v[152:155], v[176:179], v[120:123]
	v_mfma_f32_16x16x32_bf16 v[108:111], v[128:131], v[192:195], v[108:111]
	v_mfma_f32_16x16x32_bf16 v[104:107], v[152:155], v[192:195], v[104:107]
	v_mfma_f32_16x16x32_bf16 v[92:95], v[128:131], v[200:203], v[92:95]
	v_mfma_f32_16x16x32_bf16 v[88:91], v[152:155], v[200:203], v[88:91]
	v_mfma_f32_16x16x32_bf16 v[76:79], v[128:131], v[208:211], v[76:79]
	v_mfma_f32_16x16x32_bf16 v[72:75], v[152:155], v[208:211], v[72:75]
	v_mfma_f32_16x16x32_bf16 v[124:127], v[132:135], v[180:183], v[124:127]
	v_mfma_f32_16x16x32_bf16 v[120:123], v[156:159], v[180:183], v[120:123]
	v_mfma_f32_16x16x32_bf16 v[108:111], v[132:135], v[196:199], v[108:111]
	v_mfma_f32_16x16x32_bf16 v[104:107], v[156:159], v[196:199], v[104:107]
	v_mfma_f32_16x16x32_bf16 v[92:95], v[132:135], v[204:207], v[92:95]
	v_mfma_f32_16x16x32_bf16 v[88:91], v[156:159], v[204:207], v[88:91]
	v_mfma_f32_16x16x32_bf16 v[76:79], v[132:135], v[212:215], v[76:79]
	v_mfma_f32_16x16x32_bf16 v[72:75], v[156:159], v[212:215], v[72:75]
	s_setprio 0
	s_setprio 0
	v_mfma_f32_16x16x32_bf16 v[116:119], v[160:163], v[176:179], v[116:119]
	v_mfma_f32_16x16x32_bf16 v[112:115], v[168:171], v[176:179], v[112:115]
	v_mfma_f32_16x16x32_bf16 v[100:103], v[160:163], v[192:195], v[100:103]
	v_mfma_f32_16x16x32_bf16 v[96:99], v[168:171], v[192:195], v[96:99]
	v_mfma_f32_16x16x32_bf16 v[84:87], v[160:163], v[200:203], v[84:87]
	v_mfma_f32_16x16x32_bf16 v[80:83], v[168:171], v[200:203], v[80:83]
	v_mfma_f32_16x16x32_bf16 v[68:71], v[160:163], v[208:211], v[68:71]
	v_mfma_f32_16x16x32_bf16 v[64:67], v[168:171], v[208:211], v[64:67]
	v_mfma_f32_16x16x32_bf16 v[116:119], v[164:167], v[180:183], v[116:119]
	v_mfma_f32_16x16x32_bf16 v[112:115], v[172:175], v[180:183], v[112:115]
	v_mfma_f32_16x16x32_bf16 v[100:103], v[164:167], v[196:199], v[100:103]
	v_mfma_f32_16x16x32_bf16 v[96:99], v[172:175], v[196:199], v[96:99]
	v_mfma_f32_16x16x32_bf16 v[84:87], v[164:167], v[204:207], v[84:87]
	v_mfma_f32_16x16x32_bf16 v[80:83], v[172:175], v[204:207], v[80:83]
	v_mfma_f32_16x16x32_bf16 v[68:71], v[164:167], v[212:215], v[68:71]
	v_mfma_f32_16x16x32_bf16 v[64:67], v[172:175], v[212:215], v[64:67]
	s_setprio 0
	s_barrier
	s_add_i32 s38, s59, s33
	v_lshl_add_u64 v[216:217], v[216:217], 0, s[16:17]
	s_mov_b32 m0, s38
	ds_read_b128 v[176:179], v189 offset:49152
	ds_read_b128 v[180:183], v246 offset:49152
	ds_read_b128 v[192:195], v189 offset:51200
	ds_read_b128 v[196:199], v246 offset:51200
	ds_read_b128 v[200:203], v189 offset:53248
	ds_read_b128 v[204:207], v246 offset:53248
	ds_read_b128 v[208:211], v189 offset:55296
	ds_read_b128 v[212:215], v246 offset:55296
	global_load_lds_dwordx4 v[216:217], off
	s_add_i32 m0, s38, 0x2000
	s_add_u32 s36, s36, 0x40080
	v_lshl_add_u64 v[216:217], v[218:219], 0, s[16:17]
	s_addc_u32 s37, s37, 0
	s_add_i32 s38, s60, s33
	global_load_lds_dwordx4 v[216:217], off
	v_lshl_add_u64 v[216:217], s[36:37], 0, v[138:139]
	s_mov_b32 m0, s38
	s_nop 0
	global_load_lds_dwordx4 v[216:217], off
	v_lshl_add_u64 v[216:217], s[36:37], 0, v[142:143]
	s_add_i32 m0, s38, 0x2000
	s_nop 0
	global_load_lds_dwordx4 v[216:217], off
	v_lshl_add_u64 v[216:217], v[220:221], 0, s[16:17]
	s_mov_b32 m0, s48
	s_nop 0
	global_load_lds_dwordx4 v[216:217], off
	v_lshl_add_u64 v[216:217], v[222:223], 0, s[16:17]
	s_mov_b32 m0, s49
	s_nop 0
	global_load_lds_dwordx4 v[216:217], off
	s_waitcnt vmcnt(8)
	s_waitcnt lgkmcnt(0)
	s_barrier
	s_setprio 0
	s_waitcnt lgkmcnt(0)
	v_mfma_f32_16x16x32_bf16 v[60:63], v[128:131], v[176:179], v[60:63]
	v_mfma_f32_16x16x32_bf16 v[56:59], v[152:155], v[176:179], v[56:59]
	v_mfma_f32_16x16x32_bf16 v[44:47], v[128:131], v[192:195], v[44:47]
	v_mfma_f32_16x16x32_bf16 v[40:43], v[152:155], v[192:195], v[40:43]
	v_mfma_f32_16x16x32_bf16 v[28:31], v[128:131], v[200:203], v[28:31]
	v_mfma_f32_16x16x32_bf16 v[24:27], v[152:155], v[200:203], v[24:27]
	v_mfma_f32_16x16x32_bf16 v[12:15], v[128:131], v[208:211], v[12:15]
	v_mfma_f32_16x16x32_bf16 v[8:11], v[152:155], v[208:211], v[8:11]
	v_mfma_f32_16x16x32_bf16 v[60:63], v[132:135], v[180:183], v[60:63]
	v_mfma_f32_16x16x32_bf16 v[56:59], v[156:159], v[180:183], v[56:59]
	v_mfma_f32_16x16x32_bf16 v[44:47], v[132:135], v[196:199], v[44:47]
	v_mfma_f32_16x16x32_bf16 v[40:43], v[156:159], v[196:199], v[40:43]
	v_mfma_f32_16x16x32_bf16 v[28:31], v[132:135], v[204:207], v[28:31]
	v_mfma_f32_16x16x32_bf16 v[24:27], v[156:159], v[204:207], v[24:27]
	v_mfma_f32_16x16x32_bf16 v[12:15], v[132:135], v[212:215], v[12:15]
	v_mfma_f32_16x16x32_bf16 v[8:11], v[156:159], v[212:215], v[8:11]
	s_setprio 0
	s_setprio 0
	v_mfma_f32_16x16x32_bf16 v[52:55], v[160:163], v[176:179], v[52:55]
	v_mfma_f32_16x16x32_bf16 v[48:51], v[168:171], v[176:179], v[48:51]
	v_mfma_f32_16x16x32_bf16 v[36:39], v[160:163], v[192:195], v[36:39]
	v_mfma_f32_16x16x32_bf16 v[32:35], v[168:171], v[192:195], v[32:35]
	v_mfma_f32_16x16x32_bf16 v[20:23], v[160:163], v[200:203], v[20:23]
	v_mfma_f32_16x16x32_bf16 v[16:19], v[168:171], v[200:203], v[16:19]
	v_mfma_f32_16x16x32_bf16 v[4:7], v[160:163], v[208:211], v[4:7]
	v_mfma_f32_16x16x32_bf16 v[0:3], v[168:171], v[208:211], v[0:3]
	v_mfma_f32_16x16x32_bf16 v[52:55], v[164:167], v[180:183], v[52:55]
	v_mfma_f32_16x16x32_bf16 v[48:51], v[172:175], v[180:183], v[48:51]
	v_mfma_f32_16x16x32_bf16 v[36:39], v[164:167], v[196:199], v[36:39]
	v_mfma_f32_16x16x32_bf16 v[32:35], v[172:175], v[196:199], v[32:35]
	v_mfma_f32_16x16x32_bf16 v[20:23], v[164:167], v[204:207], v[20:23]
	v_mfma_f32_16x16x32_bf16 v[16:19], v[172:175], v[204:207], v[16:19]
	v_mfma_f32_16x16x32_bf16 v[4:7], v[164:167], v[212:215], v[4:7]
	v_mfma_f32_16x16x32_bf16 v[0:3], v[172:175], v[212:215], v[0:3]
	s_setprio 0
	s_barrier
	s_add_i32 s58, s58, 2
	s_add_u32 s34, s34, 0x100
	s_addc_u32 s35, s35, 0
	s_add_u32 s56, s56, 0x100
	s_addc_u32 s57, s57, 0
	s_cmp_gt_u32 s58, 13
	s_cbranch_scc0 .LBB0_1026
	s_and_b64 vcc, exec, s[18:19]
	s_cbranch_vccz .LBB0_1029
	s_barrier

.LBB0_1103:
	s_cmp_lt_i32 s84, 12
	s_cselect_b64 s[0:1], -1, 0
	s_cmp_gt_i32 s85, 11
	s_cselect_b64 s[2:3], -1, 0
	s_and_b64 s[4:5], s[0:1], s[2:3]
	s_andn2_b64 vcc, exec, s[4:5]
	s_cbranch_vccnz .LBB0_1120
	v_mov_b32_e32 v9, v236
	s_cmpk_gt_i32 s96, 0xaff
	s_nop 0
	v_readfirstlane_b32 s1, v9
	s_cbranch_scc1 .LBB0_1120
	v_lshlrev_b32_e32 v0, 4, v9
	s_waitcnt lgkmcnt(0)
	v_add_u32_e32 v1, 0x2000, v0
	v_ashrrev_i32_e32 v2, 31, v1
	v_lshrrev_b32_e32 v2, 22, v2
	v_add_u32_e32 v2, v1, v2
	v_ashrrev_i32_e32 v8, 10, v2
	v_mul_i32_i24_e32 v2, 0x400, v8
	v_sub_u32_e32 v1, v1, v2
	v_lshrrev_b32_e32 v2, 4, v1
	v_bitop3_b32 v1, v2, v1, 32 bitop3:0x6c
	v_ashrrev_i32_e32 v2, 31, v1
	v_lshrrev_b32_e32 v2, 26, v2
	v_add_u32_e32 v2, v1, v2
	v_lshlrev_b32_e32 v3, 3, v8
	v_ashrrev_i32_e32 v10, 6, v2
	v_and_b32_e32 v3, -16, v3
	v_add_u32_e32 v3, v10, v3
	v_and_b32_e32 v4, 3, v10
	s_mov_b32 s0, 0x1fffe0
	v_lshrrev_b32_e32 v5, 2, v3
	v_lshlrev_b32_e32 v6, 1, v3
	v_and_b32_e32 v2, 0xc0, v2
	v_and_or_b32 v4, v3, s0, v4
	v_and_b32_e32 v5, 4, v5
	v_and_b32_e32 v6, 24, v6
	v_sub_u32_e32 v1, v1, v2
	v_mov_b32_e32 v2, 1
	v_or3_b32 v4, v4, v5, v6
	v_lshlrev_b32_e32 v5, 5, v8
	v_ashrrev_i16_sdwa v1, v2, sext(v1) dst_sel:DWORD dst_unused:UNUSED_PAD src0_sel:DWORD src1_sel:BYTE_0
	v_and_b32_e32 v5, 32, v5
	v_bfe_i32 v11, v1, 0, 16
	v_add_lshl_u32 v1, v5, v11, 1
	v_lshrrev_b32_e32 v250, 6, v236
	v_and_b32_e32 v251, 63, v236
	v_lshrrev_b32_e32 v252, 3, v251
	v_and_b32_e32 v251, 7, v251
	v_xor_b32_e32 v251, v251, v252
	v_lshlrev_b32_e32 v251, 4, v251
	v_lshl_add_u32 v253, v250, 3, v252
	v_lshl_add_u32 v246, v253, 11, v251
	v_add_u32_e32 v247, 0x20000, v246
	v_lshrrev_b32_e32 v253, 2, v250
	v_lshlrev_b32_e32 v253, 5, v253
	v_and_b32_e32 v248, 1, v250
	v_lshl_add_u32 v253, v248, 4, v253
	v_bfe_u32 v248, v250, 1, 1
	v_lshl_add_u32 v253, v248, 2, v253
	v_lshrrev_b32_e32 v248, 2, v252
	v_lshl_add_u32 v253, v248, 3, v253
	v_and_b32_e32 v248, 3, v252
	v_add_u32_e32 v253, v253, v248
	v_lshl_add_u32 v248, v253, 11, v251
	v_add_u32_e32 v249, 0x20000, v248
	v_lshl_add_u32 v144, v4, 11, v1
	v_mov_b32_e32 v144, v249
	v_lshl_add_u32 v146, v3, 11, v1
	v_mov_b32_e32 v253, v146
	v_mov_b32_e32 v146, v247
	v_bfe_i32 v1, v9, 27, 1
	v_lshrrev_b32_e32 v1, 22, v1
	v_add_u32_e32 v1, v0, v1
	v_and_b32_e32 v1, 0xfffffc00, v1
	v_sub_u32_e32 v0, v0, v1
	v_lshrrev_b32_e32 v1, 4, v0
	v_bitop3_b32 v1, v1, v0, 32 bitop3:0x6c
	v_ashrrev_i32_e32 v0, 31, v0
	v_lshrrev_b32_e32 v0, 26, v0
	v_add_u32_e32 v0, v1, v0
	v_ashrrev_i32_e32 v12, 6, v0
	v_ashrrev_i32_e32 v0, 31, v9
	v_lshrrev_b32_e32 v0, 26, v0
	v_add_u32_e32 v0, v9, v0
	s_add_u32 s2, s82, 0x16000000
	v_ashrrev_i32_e32 v13, 6, v0
	s_addc_u32 s3, s83, 0
	v_lshlrev_b32_e32 v0, 3, v13
	s_add_u32 s30, s82, 0x1300000
	v_and_b32_e32 v0, -16, v0
	s_addc_u32 s31, s83, 0
	v_add_u32_e32 v0, v12, v0
	v_and_b32_e32 v3, 3, v12
	s_ashr_i32 s34, s96, 31
	v_and_or_b32 v3, v0, s0, v3
	s_lshr_b32 s0, s34, 29
	s_add_i32 s0, s96, s0
	s_ashr_i32 s10, s1, 6
	s_ashr_i32 s6, s0, 3
	s_and_b32 s0, s0, -8
	s_ashr_i32 s12, s1, 8
	s_lshl_b32 s33, s10, 10
	s_sub_i32 s0, s96, s0
	s_cmp_lt_i32 s0, 0
	s_movk_i32 s35, 0x161
	s_cselect_b32 s7, s35, 0x160
	s_mul_i32 s0, s0, s7
	s_add_i32 s0, s0, s6
	s_mul_hi_i32 s6, s0, 0x2e8ba2e9
	s_lshr_b32 s7, s6, 31
	s_ashr_i32 s6, s6, 5
	s_add_i32 s6, s6, s7
	s_lshl_b32 s7, s6, 3
	s_mulk_i32 s6, 0xb0
	s_sub_i32 s6, s0, s6
	s_sext_i32_i16 s0, s6
	s_bfe_u32 s0, s0, 0x3001c
	s_add_i32 s8, s6, s0
	s_sext_i32_i16 s0, s8
	s_and_b32 s8, s8, 0xfff8
	v_lshrrev_b32_e32 v4, 2, v0
	v_lshlrev_b32_e32 v5, 1, v0
	s_sub_i32 s6, s6, s8
	v_and_b32_e32 v4, 4, v4
	v_and_b32_e32 v5, 24, v5
	s_sext_i32_i16 s6, s6
	v_or3_b32 v3, v3, v4, v5
	v_mul_i32_i24_e32 v5, 64, v12
	s_lshr_b32 s0, s0, 3
	s_add_i32 s22, s7, s6
	v_sub_u32_e32 v1, v1, v5
	s_ashr_i32 s23, s22, 31
	s_bfe_i64 s[8:9], s[0:1], 0x100000
	v_lshlrev_b32_e32 v4, 5, v13
	v_ashrrev_i16_sdwa v1, v2, sext(v1) dst_sel:DWORD dst_unused:UNUSED_PAD src0_sel:DWORD src1_sel:BYTE_0
	s_lshl_b64 s[6:7], s[22:23], 19
	s_lshl_b64 s[8:9], s[8:9], 19
	v_and_b32_e32 v4, 32, v4
	v_bfe_i32 v14, v1, 0, 16
	s_add_u32 s26, s30, s8
	v_add_lshl_u32 v1, v4, v14, 1
	s_addc_u32 s27, s31, s9
	s_add_i32 s23, s33, 0
	v_lshl_add_u32 v148, v3, 11, v1
	v_mov_b32_e32 v148, v248
	s_add_i32 m0, s23, 0x10000
	v_lshl_add_u32 v150, v0, 11, v1
	v_mov_b32_e32 v252, v150
	v_mov_b32_e32 v150, v246
	global_load_lds_dwordx4 v148, s[26:27]
	s_add_i32 m0, s23, 0x12000
	s_add_u32 s8, s26, 0x40000
	global_load_lds_dwordx4 v144, s[26:27]
	s_addc_u32 s9, s27, 0
	s_add_i32 m0, s23, 0x14000
	v_mov_b32_e32 v149, 0
	global_load_lds_dwordx4 v148, s[8:9]
	s_add_i32 m0, s23, 0x16000
	s_add_u32 s24, s2, s6
	s_addc_u32 s25, s3, s7
	s_add_i32 s36, s23, 0x2000
	global_load_lds_dwordx4 v144, s[8:9]
	s_mov_b32 m0, s23
	s_add_u32 s6, s24, 0x40000
	global_load_lds_dwordx4 v150, s[24:25]
	s_mov_b32 m0, s36
	s_addc_u32 s7, s25, 0
	s_add_i32 s37, s23, 0x4000
	global_load_lds_dwordx4 v146, s[24:25]
	s_mov_b32 m0, s37
	s_add_i32 s38, s23, 0x6000
	global_load_lds_dwordx4 v150, s[6:7]
	s_mov_b32 m0, s38
	v_mov_b32_e32 v145, v149
	global_load_lds_dwordx4 v146, s[6:7]
	v_mov_b32_e32 v151, v149
	v_mov_b32_e32 v147, v149
	s_cmp_eq_u32 s12, 1
	s_mov_b32 s39, 0
	v_lshl_add_u64 v[6:7], s[26:27], 0, v[148:149]
	v_lshl_add_u64 v[4:5], s[26:27], 0, v[144:145]
	v_lshl_add_u64 v[0:1], s[24:25], 0, v[150:151]
	s_cselect_b64 s[6:7], -1, 0
	s_cmp_lg_u32 s12, 1
	v_lshl_add_u64 v[2:3], s[24:25], 0, v[146:147]
	s_cbranch_scc1 .LBB0_1107
	s_barrier
.LBB0_1107:
	s_add_u32 s8, s82, 0x2f00000
	s_addc_u32 s9, s83, 0
	s_add_u32 s40, s82, 0x2f40000
	s_addc_u32 s41, s83, 0
	s_lshl_b32 s10, s10, 5
	s_and_b32 s16, s10, 0x60
	s_mov_b64 s[10:11], 0x80
	s_add_i32 m0, s23, 0x18000
	v_lshl_add_u64 v[6:7], v[6:7], 0, s[10:11]
	s_ashr_i32 s42, s86, 31
	s_lshl_b32 s13, s12, 13
	s_lshl_b32 s17, s16, 7
	s_waitcnt vmcnt(2)
	s_barrier
	global_load_lds_dwordx4 v[6:7], off
	v_lshl_add_u64 v[4:5], v[4:5], 0, s[10:11]
	s_add_i32 m0, s23, 0x1a000
	s_add_i32 s43, s23, 0x8000
	s_add_i32 s44, s23, 0xa000
	global_load_lds_dwordx4 v[4:5], off
	v_lshl_add_u64 v[0:1], v[0:1], 0, s[10:11]
	s_mov_b32 m0, s43
	s_add_u32 s14, s26, 0x40080
	global_load_lds_dwordx4 v[0:1], off
	v_lshl_add_u64 v[0:1], v[2:3], 0, s[10:11]
	s_mov_b32 m0, s44
	s_addc_u32 s15, s27, 0
	global_load_lds_dwordx4 v[0:1], off
	s_add_i32 m0, s23, 0x1c000
	v_lshl_add_u64 v[0:1], s[14:15], 0, v[148:149]
	global_load_lds_dwordx4 v[0:1], off
	v_lshl_add_u64 v[0:1], s[14:15], 0, v[144:145]
	s_add_i32 m0, s23, 0x1e000
	s_cmpk_lt_u32 s1, 0x100
	global_load_lds_dwordx4 v[0:1], off
	v_lshrrev_b32_e32 v0, 1, v9
	v_and_b32_e32 v0, 24, v0
	v_and_b32_e32 v1, 15, v9
	v_lshlrev_b32_e32 v2, 1, v0
	v_lshl_or_b32 v161, s12, 6, v1
	v_lshl_or_b32 v1, v1, 6, v2
	v_lshlrev_b32_e32 v2, 2, v9
	v_and_b32_e32 v2, 32, v2
	v_bitop3_b32 v3, v1, s13, v2 bitop3:0xde
	v_bitop3_b32 v167, v1, s17, v2 bitop3:0xde
	v_lshlrev_b32_e32 v1, 14, v13
	v_and_b32_e32 v1, 0xffff8000, v1
	v_lshl_add_u32 v1, v12, 11, v1
	v_and_b32_e32 v2, 1, v13
	v_lshl_or_b32 v1, v2, 6, v1
	v_lshl_add_u32 v152, v14, 1, v1
	v_lshlrev_b32_e32 v1, 14, v8
	v_and_b32_e32 v1, 0xffff8000, v1
	s_waitcnt vmcnt(6)
	v_lshl_add_u32 v1, v10, 11, v1
	v_and_b32_e32 v2, 1, v8
	s_cselect_b64 s[12:13], -1, 0
	v_lshl_or_b32 v1, v2, 6, v1
	s_add_i32 s46, 0, 0x10000
	s_add_i32 s47, 0, 0x14000
	s_sext_i32_i16 s50, s0
	s_mov_b32 s45, s86
	v_or_b32_e32 v169, s16, v0
	v_mov_b32_e32 v153, v149
	v_lshl_add_u32 v154, v11, 1, v1
	v_mov_b32_e32 v155, v149
	v_mov_b64_e32 v[156:157], 0xb00
	v_mov_b64_e32 v[158:159], 0xaff
	v_add_u32_e32 v171, s46, v167
	v_add_u32_e32 v175, s47, v167
	v_add_u32_e32 v179, 0, v3
	s_lshl_b32 s48, s16, 2
	v_lshlrev_b32_e32 v180, 2, v0
	v_mov_b32_e32 v181, 0x358637bd
	s_movk_i32 s49, 0x1600
	s_barrier
	v_sub_u32_e32 v152, v152, v252
	v_add_u32_e32 v152, v152, v150
	v_sub_u32_e32 v154, v154, v253
	v_add_u32_e32 v154, v154, v146
	v_and_b32_e32 v250, 63, v236
	v_and_b32_e32 v251, 15, v250
	v_lshrrev_b32_e32 v252, 4, v250
	v_and_b32_e32 v253, 7, v251
	v_xor_b32_e32 v252, v252, v253
	v_lshlrev_b32_e32 v252, 4, v252
	v_lshl_add_u32 v252, v251, 7, v252
	v_lshrrev_b32_e32 v250, 6, v236
	v_lshrrev_b32_e32 v251, 2, v250
	v_lshl_add_u32 v179, v251, 13, v252
	v_and_b32_e32 v251, 3, v250
	v_lshl_add_u32 v167, v251, 12, v252
	v_add_u32_e32 v171, s46, v167
	v_add_u32_e32 v175, s47, v167
	s_branch .LBB0_1110

.LBB0_1112:
	s_ashr_i32 s17, s16, 31
	s_lshl_b64 s[18:19], s[16:17], 19
	s_add_u32 s18, s2, s18
	s_addc_u32 s19, s3, s19
	s_and_b64 s[20:21], s[0:1], exec
	s_cselect_b32 s17, s19, s25
	s_cselect_b32 s51, s18, s24
	s_ashr_i32 s15, s14, 31
	s_lshl_b64 s[20:21], s[14:15], 19
	s_add_u32 s20, s30, s20
	s_addc_u32 s21, s31, s21
	s_and_b64 s[28:29], s[0:1], exec
	s_cselect_b32 s15, s21, s27
	s_cselect_b32 s52, s20, s26
	s_add_u32 s24, s24, 0x40080
	s_addc_u32 s25, s25, 0
	s_add_u32 s53, s26, 0x100
	v_mov_b32_e32 v0, 0
	s_addc_u32 s54, s27, 0
	s_mov_b32 s55, -2
	v_mov_b32_e32 v1, v0
	v_mov_b32_e32 v2, v0
	v_mov_b32_e32 v3, v0
	v_mov_b32_e32 v4, v0
	v_mov_b32_e32 v5, v0
	v_mov_b32_e32 v6, v0
	v_mov_b32_e32 v7, v0
	v_mov_b32_e32 v16, v0
	v_mov_b32_e32 v17, v0
	v_mov_b32_e32 v18, v0
	v_mov_b32_e32 v19, v0
	v_mov_b32_e32 v20, v0
	v_mov_b32_e32 v21, v0
	v_mov_b32_e32 v22, v0
	v_mov_b32_e32 v23, v0
	v_mov_b32_e32 v32, v0
	v_mov_b32_e32 v33, v0
	v_mov_b32_e32 v34, v0
	v_mov_b32_e32 v35, v0
	v_mov_b32_e32 v36, v0
	v_mov_b32_e32 v37, v0
	v_mov_b32_e32 v38, v0
	v_mov_b32_e32 v39, v0
	v_mov_b32_e32 v48, v0
	v_mov_b32_e32 v49, v0
	v_mov_b32_e32 v50, v0
	v_mov_b32_e32 v51, v0
	v_mov_b32_e32 v52, v0
	v_mov_b32_e32 v53, v0
	v_mov_b32_e32 v54, v0
	v_mov_b32_e32 v55, v0
	v_mov_b32_e32 v8, v0
	v_mov_b32_e32 v9, v0
	v_mov_b32_e32 v10, v0
	v_mov_b32_e32 v11, v0
	v_mov_b32_e32 v12, v0
	v_mov_b32_e32 v13, v0
	v_mov_b32_e32 v14, v0
	v_mov_b32_e32 v15, v0
	v_mov_b32_e32 v24, v0
	v_mov_b32_e32 v25, v0
	v_mov_b32_e32 v26, v0
	v_mov_b32_e32 v27, v0
	v_mov_b32_e32 v28, v0
	v_mov_b32_e32 v29, v0
	v_mov_b32_e32 v30, v0
	v_mov_b32_e32 v31, v0
	v_mov_b32_e32 v40, v0
	v_mov_b32_e32 v41, v0
	v_mov_b32_e32 v42, v0
	v_mov_b32_e32 v43, v0
	v_mov_b32_e32 v44, v0
	v_mov_b32_e32 v45, v0
	v_mov_b32_e32 v46, v0
	v_mov_b32_e32 v47, v0
	v_mov_b32_e32 v56, v0
	v_mov_b32_e32 v57, v0
	v_mov_b32_e32 v58, v0
	v_mov_b32_e32 v59, v0
	v_mov_b32_e32 v60, v0
	v_mov_b32_e32 v61, v0
	v_mov_b32_e32 v62, v0
	v_mov_b32_e32 v63, v0
	v_mov_b32_e32 v64, v0
	v_mov_b32_e32 v65, v0
	v_mov_b32_e32 v66, v0
	v_mov_b32_e32 v67, v0
	v_mov_b32_e32 v68, v0
	v_mov_b32_e32 v69, v0
	v_mov_b32_e32 v70, v0
	v_mov_b32_e32 v71, v0
	v_mov_b32_e32 v80, v0
	v_mov_b32_e32 v81, v0
	v_mov_b32_e32 v82, v0
	v_mov_b32_e32 v83, v0
	v_mov_b32_e32 v84, v0
	v_mov_b32_e32 v85, v0
	v_mov_b32_e32 v86, v0
	v_mov_b32_e32 v87, v0
	v_mov_b32_e32 v96, v0
	v_mov_b32_e32 v97, v0
	v_mov_b32_e32 v98, v0
	v_mov_b32_e32 v99, v0
	v_mov_b32_e32 v100, v0
	v_mov_b32_e32 v101, v0
	v_mov_b32_e32 v102, v0
	v_mov_b32_e32 v103, v0
	v_mov_b32_e32 v112, v0
	v_mov_b32_e32 v113, v0
	v_mov_b32_e32 v114, v0
	v_mov_b32_e32 v115, v0
	v_mov_b32_e32 v116, v0
	v_mov_b32_e32 v117, v0
	v_mov_b32_e32 v118, v0
	v_mov_b32_e32 v119, v0
	v_mov_b32_e32 v72, v0
	s_waitcnt vmcnt(0)
	v_mov_b32_e32 v73, v0
	v_mov_b32_e32 v74, v0
	v_mov_b32_e32 v75, v0
	v_mov_b32_e32 v76, v0
	v_mov_b32_e32 v77, v0
	v_mov_b32_e32 v78, v0
	v_mov_b32_e32 v79, v0
	v_mov_b32_e32 v88, v0
	v_mov_b32_e32 v89, v0
	v_mov_b32_e32 v90, v0
	v_mov_b32_e32 v91, v0
	v_mov_b32_e32 v92, v0
	v_mov_b32_e32 v93, v0
	v_mov_b32_e32 v94, v0
	v_mov_b32_e32 v95, v0
	v_mov_b32_e32 v104, v0
	v_mov_b32_e32 v105, v0
	v_mov_b32_e32 v106, v0
	v_mov_b32_e32 v107, v0
	v_mov_b32_e32 v108, v0
	v_mov_b32_e32 v109, v0
	v_mov_b32_e32 v110, v0
	v_mov_b32_e32 v111, v0
	v_mov_b32_e32 v120, v0
	v_mov_b32_e32 v121, v0
	v_mov_b32_e32 v122, v0
	v_mov_b32_e32 v123, v0
	v_mov_b32_e32 v128, v0
	v_mov_b32_e32 v129, v0
	v_mov_b32_e32 v130, v0
	v_mov_b32_e32 v131, v0
	v_xor_b32_e32 v246, 64, v179
	v_xor_b32_e32 v247, 64, v167
	v_add_u32_e32 v248, s46, v247
	v_add_u32_e32 v249, s47, v247
.LBB0_1113:
	ds_read_b128 v[124:127], v171
	ds_read_b128 v[132:135], v248
	ds_read_b128 v[136:139], v171 offset:2048
	ds_read_b128 v[140:143], v248 offset:2048
	ds_read_b128 v[162:165], v175
	ds_read_b128 v[182:185], v249
	ds_read_b128 v[186:189], v175 offset:2048
	ds_read_b128 v[190:193], v249 offset:2048
	s_add_u32 s26, s24, 0xfffc0080
	s_addc_u32 s27, s25, -1
	s_cmp_eq_u32 s55, 12
	s_cselect_b32 s29, s17, s27
	s_cselect_b32 s28, s51, s26
	s_cselect_b32 s27, s15, s54
	s_cselect_b32 s26, s52, s53
	v_lshl_add_u64 v[172:173], s[24:25], 0, v[152:153]
	s_add_i32 m0, s23, 0xc000
	ds_read_b128 v[194:197], v179
	ds_read_b128 v[198:201], v246
	ds_read_b128 v[202:205], v179 offset:2048
	ds_read_b128 v[206:209], v246 offset:2048
	ds_read_b128 v[210:213], v179 offset:4096
	ds_read_b128 v[214:217], v246 offset:4096
	ds_read_b128 v[218:221], v179 offset:6144
	ds_read_b128 v[222:225], v246 offset:6144
	global_load_lds_dwordx4 v[172:173], off
	v_lshl_add_u64 v[172:173], s[24:25], 0, v[154:155]
	s_add_i32 m0, s23, 0xe000
	s_nop 0
	global_load_lds_dwordx4 v[172:173], off
	s_waitcnt vmcnt(8)
	s_waitcnt lgkmcnt(0)
	s_barrier
	s_setprio 0
	s_waitcnt lgkmcnt(0)
	v_mfma_f32_16x16x32_bf16 v[128:131], v[124:127], v[194:197], v[128:131]
	v_mfma_f32_16x16x32_bf16 v[120:123], v[136:139], v[194:197], v[120:123]
	v_mfma_f32_16x16x32_bf16 v[108:111], v[124:127], v[202:205], v[108:111]
	v_mfma_f32_16x16x32_bf16 v[104:107], v[136:139], v[202:205], v[104:107]
	v_mfma_f32_16x16x32_bf16 v[92:95], v[124:127], v[210:213], v[92:95]
	v_mfma_f32_16x16x32_bf16 v[88:91], v[136:139], v[210:213], v[88:91]
	v_mfma_f32_16x16x32_bf16 v[76:79], v[124:127], v[218:221], v[76:79]
	v_mfma_f32_16x16x32_bf16 v[72:75], v[136:139], v[218:221], v[72:75]
	v_mfma_f32_16x16x32_bf16 v[128:131], v[132:135], v[198:201], v[128:131]
	v_mfma_f32_16x16x32_bf16 v[120:123], v[140:143], v[198:201], v[120:123]
	v_mfma_f32_16x16x32_bf16 v[108:111], v[132:135], v[206:209], v[108:111]
	v_mfma_f32_16x16x32_bf16 v[104:107], v[140:143], v[206:209], v[104:107]
	v_mfma_f32_16x16x32_bf16 v[92:95], v[132:135], v[214:217], v[92:95]
	v_mfma_f32_16x16x32_bf16 v[88:91], v[140:143], v[214:217], v[88:91]
	v_mfma_f32_16x16x32_bf16 v[76:79], v[132:135], v[222:225], v[76:79]
	v_mfma_f32_16x16x32_bf16 v[72:75], v[140:143], v[222:225], v[72:75]
	s_setprio 0
	s_setprio 0
	v_mfma_f32_16x16x32_bf16 v[116:119], v[162:165], v[194:197], v[116:119]
	v_mfma_f32_16x16x32_bf16 v[112:115], v[186:189], v[194:197], v[112:115]
	v_mfma_f32_16x16x32_bf16 v[100:103], v[162:165], v[202:205], v[100:103]
	v_mfma_f32_16x16x32_bf16 v[96:99], v[186:189], v[202:205], v[96:99]
	v_mfma_f32_16x16x32_bf16 v[84:87], v[162:165], v[210:213], v[84:87]
	v_mfma_f32_16x16x32_bf16 v[80:83], v[186:189], v[210:213], v[80:83]
	v_mfma_f32_16x16x32_bf16 v[68:71], v[162:165], v[218:221], v[68:71]
	v_mfma_f32_16x16x32_bf16 v[64:67], v[186:189], v[218:221], v[64:67]
	v_mfma_f32_16x16x32_bf16 v[116:119], v[182:185], v[198:201], v[116:119]
	v_mfma_f32_16x16x32_bf16 v[112:115], v[190:193], v[198:201], v[112:115]
	v_mfma_f32_16x16x32_bf16 v[100:103], v[182:185], v[206:209], v[100:103]
	v_mfma_f32_16x16x32_bf16 v[96:99], v[190:193], v[206:209], v[96:99]
	v_mfma_f32_16x16x32_bf16 v[84:87], v[182:185], v[214:217], v[84:87]
	v_mfma_f32_16x16x32_bf16 v[80:83], v[190:193], v[214:217], v[80:83]
	v_mfma_f32_16x16x32_bf16 v[68:71], v[182:185], v[222:225], v[68:71]
	v_mfma_f32_16x16x32_bf16 v[64:67], v[190:193], v[222:225], v[64:67]
	s_setprio 0
	s_barrier
	s_add_i32 s56, s46, s33
	v_lshl_add_u64 v[172:173], s[26:27], 0, v[148:149]
	s_mov_b32 m0, s56
	ds_read_b128 v[194:197], v179 offset:16384
	ds_read_b128 v[198:201], v246 offset:16384
	ds_read_b128 v[202:205], v179 offset:18432
	ds_read_b128 v[206:209], v246 offset:18432
	ds_read_b128 v[210:213], v179 offset:20480
	ds_read_b128 v[214:217], v246 offset:20480
	ds_read_b128 v[218:221], v179 offset:22528
	ds_read_b128 v[222:225], v246 offset:22528
	global_load_lds_dwordx4 v[172:173], off
	s_add_i32 m0, s56, 0x2000
	s_add_u32 s56, s26, 0x40000
	v_lshl_add_u64 v[176:177], s[26:27], 0, v[144:145]
	s_addc_u32 s57, s27, 0
	s_add_i32 s58, s47, s33
	global_load_lds_dwordx4 v[176:177], off
	v_lshl_add_u64 v[226:227], s[56:57], 0, v[148:149]
	s_mov_b32 m0, s58
	v_lshl_add_u64 v[228:229], s[28:29], 0, v[146:147]
	global_load_lds_dwordx4 v[226:227], off
	v_lshl_add_u64 v[226:227], s[56:57], 0, v[144:145]
	s_add_i32 m0, s58, 0x2000
	s_nop 0
	global_load_lds_dwordx4 v[226:227], off
	v_lshl_add_u64 v[226:227], s[28:29], 0, v[150:151]
	s_mov_b32 m0, s23
	s_nop 0
	global_load_lds_dwordx4 v[226:227], off
	s_mov_b32 m0, s36
	s_nop 0
	global_load_lds_dwordx4 v[228:229], off
	s_waitcnt vmcnt(8)
	s_waitcnt lgkmcnt(0)
	s_barrier
	s_setprio 0
	s_waitcnt lgkmcnt(0)
	v_mfma_f32_16x16x32_bf16 v[60:63], v[124:127], v[194:197], v[60:63]
	v_mfma_f32_16x16x32_bf16 v[56:59], v[136:139], v[194:197], v[56:59]
	v_mfma_f32_16x16x32_bf16 v[44:47], v[124:127], v[202:205], v[44:47]
	v_mfma_f32_16x16x32_bf16 v[40:43], v[136:139], v[202:205], v[40:43]
	v_mfma_f32_16x16x32_bf16 v[28:31], v[124:127], v[210:213], v[28:31]
	v_mfma_f32_16x16x32_bf16 v[24:27], v[136:139], v[210:213], v[24:27]
	v_mfma_f32_16x16x32_bf16 v[12:15], v[124:127], v[218:221], v[12:15]
	v_mfma_f32_16x16x32_bf16 v[8:11], v[136:139], v[218:221], v[8:11]
	v_mfma_f32_16x16x32_bf16 v[60:63], v[132:135], v[198:201], v[60:63]
	v_mfma_f32_16x16x32_bf16 v[56:59], v[140:143], v[198:201], v[56:59]
	v_mfma_f32_16x16x32_bf16 v[44:47], v[132:135], v[206:209], v[44:47]
	v_mfma_f32_16x16x32_bf16 v[40:43], v[140:143], v[206:209], v[40:43]
	v_mfma_f32_16x16x32_bf16 v[28:31], v[132:135], v[214:217], v[28:31]
	v_mfma_f32_16x16x32_bf16 v[24:27], v[140:143], v[214:217], v[24:27]
	v_mfma_f32_16x16x32_bf16 v[12:15], v[132:135], v[222:225], v[12:15]
	v_mfma_f32_16x16x32_bf16 v[8:11], v[140:143], v[222:225], v[8:11]
	s_setprio 0
	s_setprio 0
	v_mfma_f32_16x16x32_bf16 v[52:55], v[162:165], v[194:197], v[52:55]
	v_mfma_f32_16x16x32_bf16 v[48:51], v[186:189], v[194:197], v[48:51]
	v_mfma_f32_16x16x32_bf16 v[36:39], v[162:165], v[202:205], v[36:39]
	v_mfma_f32_16x16x32_bf16 v[32:35], v[186:189], v[202:205], v[32:35]
	v_mfma_f32_16x16x32_bf16 v[20:23], v[162:165], v[210:213], v[20:23]
	v_mfma_f32_16x16x32_bf16 v[16:19], v[186:189], v[210:213], v[16:19]
	v_mfma_f32_16x16x32_bf16 v[4:7], v[162:165], v[218:221], v[4:7]
	v_mfma_f32_16x16x32_bf16 v[0:3], v[186:189], v[218:221], v[0:3]
	v_mfma_f32_16x16x32_bf16 v[52:55], v[182:185], v[198:201], v[52:55]
	v_mfma_f32_16x16x32_bf16 v[48:51], v[190:193], v[198:201], v[48:51]
	v_mfma_f32_16x16x32_bf16 v[36:39], v[182:185], v[206:209], v[36:39]
	v_mfma_f32_16x16x32_bf16 v[32:35], v[190:193], v[206:209], v[32:35]
	v_mfma_f32_16x16x32_bf16 v[20:23], v[182:185], v[214:217], v[20:23]
	v_mfma_f32_16x16x32_bf16 v[16:19], v[190:193], v[214:217], v[16:19]
	v_mfma_f32_16x16x32_bf16 v[4:7], v[182:185], v[222:225], v[4:7]
	v_mfma_f32_16x16x32_bf16 v[0:3], v[190:193], v[222:225], v[0:3]
	s_setprio 0
	s_barrier
	s_add_i32 s56, 0, 0x18000
	s_add_i32 s57, 0, 0x1c000
	v_add_u32_e32 v140, s56, v167
	v_add_u32_e32 v250, s56, v247
	v_add_u32_e32 v160, s57, v167
	v_add_u32_e32 v251, s57, v247
	ds_read_b128 v[124:127], v140
	ds_read_b128 v[132:135], v250
	ds_read_b128 v[136:139], v140 offset:2048
	ds_read_b128 v[140:143], v250 offset:2048
	ds_read_b128 v[162:165], v160
	ds_read_b128 v[182:185], v251
	ds_read_b128 v[186:189], v160 offset:2048
	ds_read_b128 v[190:193], v251 offset:2048
	s_add_u32 s28, s28, 0x40000
	s_addc_u32 s29, s29, 0
	s_mov_b32 m0, s37
	v_lshl_add_u64 v[230:231], s[28:29], 0, v[150:151]
	ds_read_b128 v[194:197], v179 offset:32768
	ds_read_b128 v[198:201], v246 offset:32768
	ds_read_b128 v[202:205], v179 offset:34816
	ds_read_b128 v[206:209], v246 offset:34816
	ds_read_b128 v[210:213], v179 offset:36864
	ds_read_b128 v[214:217], v246 offset:36864
	ds_read_b128 v[218:221], v179 offset:38912
	ds_read_b128 v[222:225], v246 offset:38912
	global_load_lds_dwordx4 v[230:231], off
	v_lshl_add_u64 v[230:231], s[28:29], 0, v[146:147]
	s_mov_b32 m0, s38
	s_nop 0
	global_load_lds_dwordx4 v[230:231], off
	s_waitcnt vmcnt(8)
	s_waitcnt lgkmcnt(0)
	s_barrier
	s_setprio 0
	s_waitcnt lgkmcnt(0)
	v_mfma_f32_16x16x32_bf16 v[128:131], v[124:127], v[194:197], v[128:131]
	v_mfma_f32_16x16x32_bf16 v[120:123], v[136:139], v[194:197], v[120:123]
	v_mfma_f32_16x16x32_bf16 v[108:111], v[124:127], v[202:205], v[108:111]
	v_mfma_f32_16x16x32_bf16 v[104:107], v[136:139], v[202:205], v[104:107]
	v_mfma_f32_16x16x32_bf16 v[92:95], v[124:127], v[210:213], v[92:95]
	v_mfma_f32_16x16x32_bf16 v[88:91], v[136:139], v[210:213], v[88:91]
	v_mfma_f32_16x16x32_bf16 v[76:79], v[124:127], v[218:221], v[76:79]
	v_mfma_f32_16x16x32_bf16 v[72:75], v[136:139], v[218:221], v[72:75]
	v_mfma_f32_16x16x32_bf16 v[128:131], v[132:135], v[198:201], v[128:131]
	v_mfma_f32_16x16x32_bf16 v[120:123], v[140:143], v[198:201], v[120:123]
	v_mfma_f32_16x16x32_bf16 v[108:111], v[132:135], v[206:209], v[108:111]
	v_mfma_f32_16x16x32_bf16 v[104:107], v[140:143], v[206:209], v[104:107]
	v_mfma_f32_16x16x32_bf16 v[92:95], v[132:135], v[214:217], v[92:95]
	v_mfma_f32_16x16x32_bf16 v[88:91], v[140:143], v[214:217], v[88:91]
	v_mfma_f32_16x16x32_bf16 v[76:79], v[132:135], v[222:225], v[76:79]
	v_mfma_f32_16x16x32_bf16 v[72:75], v[140:143], v[222:225], v[72:75]
	s_setprio 0
	s_setprio 0
	v_mfma_f32_16x16x32_bf16 v[116:119], v[162:165], v[194:197], v[116:119]
	v_mfma_f32_16x16x32_bf16 v[112:115], v[186:189], v[194:197], v[112:115]
	v_mfma_f32_16x16x32_bf16 v[100:103], v[162:165], v[202:205], v[100:103]
	v_mfma_f32_16x16x32_bf16 v[96:99], v[186:189], v[202:205], v[96:99]
	v_mfma_f32_16x16x32_bf16 v[84:87], v[162:165], v[210:213], v[84:87]
	v_mfma_f32_16x16x32_bf16 v[80:83], v[186:189], v[210:213], v[80:83]
	v_mfma_f32_16x16x32_bf16 v[68:71], v[162:165], v[218:221], v[68:71]
	v_mfma_f32_16x16x32_bf16 v[64:67], v[186:189], v[218:221], v[64:67]
	v_mfma_f32_16x16x32_bf16 v[116:119], v[182:185], v[198:201], v[116:119]
	v_mfma_f32_16x16x32_bf16 v[112:115], v[190:193], v[198:201], v[112:115]
	v_mfma_f32_16x16x32_bf16 v[100:103], v[182:185], v[206:209], v[100:103]
	v_mfma_f32_16x16x32_bf16 v[96:99], v[190:193], v[206:209], v[96:99]
	v_mfma_f32_16x16x32_bf16 v[84:87], v[182:185], v[214:217], v[84:87]
	v_mfma_f32_16x16x32_bf16 v[80:83], v[190:193], v[214:217], v[80:83]
	v_mfma_f32_16x16x32_bf16 v[68:71], v[182:185], v[222:225], v[68:71]
	v_mfma_f32_16x16x32_bf16 v[64:67], v[190:193], v[222:225], v[64:67]
	s_setprio 0
	s_barrier
	s_add_i32 s28, s56, s33
	v_lshl_add_u64 v[172:173], v[172:173], 0, s[10:11]
	s_mov_b32 m0, s28
	ds_read_b128 v[194:197], v179 offset:49152
	ds_read_b128 v[198:201], v246 offset:49152
	ds_read_b128 v[202:205], v179 offset:51200
	ds_read_b128 v[206:209], v246 offset:51200
	ds_read_b128 v[210:213], v179 offset:53248
	ds_read_b128 v[214:217], v246 offset:53248
	ds_read_b128 v[218:221], v179 offset:55296
	ds_read_b128 v[222:225], v246 offset:55296
	global_load_lds_dwordx4 v[172:173], off
	s_add_i32 m0, s28, 0x2000
	s_add_u32 s26, s26, 0x40080
	v_lshl_add_u64 v[172:173], v[176:177], 0, s[10:11]
	s_addc_u32 s27, s27, 0
	s_add_i32 s28, s57, s33
	global_load_lds_dwordx4 v[172:173], off
	v_lshl_add_u64 v[172:173], s[26:27], 0, v[148:149]
	s_mov_b32 m0, s28
	s_nop 0
	global_load_lds_dwordx4 v[172:173], off
	v_lshl_add_u64 v[172:173], s[26:27], 0, v[144:145]
	s_add_i32 m0, s28, 0x2000
	s_nop 0
	global_load_lds_dwordx4 v[172:173], off
	v_lshl_add_u64 v[172:173], v[226:227], 0, s[10:11]
	s_mov_b32 m0, s43
	s_nop 0
	global_load_lds_dwordx4 v[172:173], off
	v_lshl_add_u64 v[172:173], v[228:229], 0, s[10:11]
	s_mov_b32 m0, s44
	s_nop 0
	global_load_lds_dwordx4 v[172:173], off
	s_waitcnt vmcnt(8)
	s_waitcnt lgkmcnt(0)
	s_barrier
	s_setprio 0
	s_waitcnt lgkmcnt(0)
	v_mfma_f32_16x16x32_bf16 v[60:63], v[124:127], v[194:197], v[60:63]
	v_mfma_f32_16x16x32_bf16 v[56:59], v[136:139], v[194:197], v[56:59]
	v_mfma_f32_16x16x32_bf16 v[44:47], v[124:127], v[202:205], v[44:47]
	v_mfma_f32_16x16x32_bf16 v[40:43], v[136:139], v[202:205], v[40:43]
	v_mfma_f32_16x16x32_bf16 v[28:31], v[124:127], v[210:213], v[28:31]
	v_mfma_f32_16x16x32_bf16 v[24:27], v[136:139], v[210:213], v[24:27]
	v_mfma_f32_16x16x32_bf16 v[12:15], v[124:127], v[218:221], v[12:15]
	v_mfma_f32_16x16x32_bf16 v[8:11], v[136:139], v[218:221], v[8:11]
	v_mfma_f32_16x16x32_bf16 v[60:63], v[132:135], v[198:201], v[60:63]
	v_mfma_f32_16x16x32_bf16 v[56:59], v[140:143], v[198:201], v[56:59]
	v_mfma_f32_16x16x32_bf16 v[44:47], v[132:135], v[206:209], v[44:47]
	v_mfma_f32_16x16x32_bf16 v[40:43], v[140:143], v[206:209], v[40:43]
	v_mfma_f32_16x16x32_bf16 v[28:31], v[132:135], v[214:217], v[28:31]
	v_mfma_f32_16x16x32_bf16 v[24:27], v[140:143], v[214:217], v[24:27]
	v_mfma_f32_16x16x32_bf16 v[12:15], v[132:135], v[222:225], v[12:15]
	v_mfma_f32_16x16x32_bf16 v[8:11], v[140:143], v[222:225], v[8:11]
	s_setprio 0
	s_setprio 0
	v_mfma_f32_16x16x32_bf16 v[52:55], v[162:165], v[194:197], v[52:55]
	v_mfma_f32_16x16x32_bf16 v[48:51], v[186:189], v[194:197], v[48:51]
	v_mfma_f32_16x16x32_bf16 v[36:39], v[162:165], v[202:205], v[36:39]
	v_mfma_f32_16x16x32_bf16 v[32:35], v[186:189], v[202:205], v[32:35]
	v_mfma_f32_16x16x32_bf16 v[20:23], v[162:165], v[210:213], v[20:23]
	v_mfma_f32_16x16x32_bf16 v[16:19], v[186:189], v[210:213], v[16:19]
	v_mfma_f32_16x16x32_bf16 v[4:7], v[162:165], v[218:221], v[4:7]
	v_mfma_f32_16x16x32_bf16 v[0:3], v[186:189], v[218:221], v[0:3]
	v_mfma_f32_16x16x32_bf16 v[52:55], v[182:185], v[198:201], v[52:55]
	v_mfma_f32_16x16x32_bf16 v[48:51], v[190:193], v[198:201], v[48:51]
	v_mfma_f32_16x16x32_bf16 v[36:39], v[182:185], v[206:209], v[36:39]
	v_mfma_f32_16x16x32_bf16 v[32:35], v[190:193], v[206:209], v[32:35]
	v_mfma_f32_16x16x32_bf16 v[20:23], v[182:185], v[214:217], v[20:23]
	v_mfma_f32_16x16x32_bf16 v[16:19], v[190:193], v[214:217], v[16:19]
	v_mfma_f32_16x16x32_bf16 v[4:7], v[182:185], v[222:225], v[4:7]
	v_mfma_f32_16x16x32_bf16 v[0:3], v[190:193], v[222:225], v[0:3]
	s_setprio 0
	s_barrier
	s_add_i32 s55, s55, 2
	s_add_u32 s24, s24, 0x100
	s_addc_u32 s25, s25, 0
	s_add_u32 s53, s53, 0x100
	s_addc_u32 s54, s54, 0
	s_cmp_gt_u32 s55, 13
	s_cbranch_scc0 .LBB0_1113
	s_and_b64 vcc, exec, s[12:13]
	s_cbranch_vccz .LBB0_1116
	s_barrier

.LBB0_1180:
	s_waitcnt lgkmcnt(0)
	v_ashrrev_i32_e32 v1, 31, v236
	v_lshrrev_b32_e32 v1, 26, v1
	v_add_u32_e32 v1, v236, v1
	v_ashrrev_i32_e32 v8, 6, v1
	v_bfe_i32 v1, v236, 27, 1
	v_lshlrev_b32_e32 v0, 4, v236
	v_lshrrev_b32_e32 v1, 22, v1
	v_add_u32_e32 v1, v0, v1
	v_and_b32_e32 v1, 0xfffffc00, v1
	v_sub_u32_e32 v1, v0, v1
	v_lshrrev_b32_e32 v2, 4, v1
	v_bitop3_b32 v2, v2, v1, 32 bitop3:0x6c
	v_ashrrev_i32_e32 v1, 31, v1
	v_lshrrev_b32_e32 v1, 26, v1
	v_lshlrev_b32_e32 v3, 3, v8
	v_add_u32_e32 v1, v2, v1
	v_and_b32_e32 v3, -16, v3
	v_ashrrev_i32_e32 v10, 6, v1
	v_add_u32_e32 v1, v10, v3
	v_lshlrev_b32_e32 v3, 5, v8
	v_and_b32_e32 v9, 32, v3
	v_mul_i32_i24_e32 v3, 64, v10
	v_sub_u32_e32 v2, v2, v3
	v_mov_b32_e32 v3, 1
	v_ashrrev_i16_sdwa v2, v3, sext(v2) dst_sel:DWORD dst_unused:UNUSED_PAD src0_sel:DWORD src1_sel:BYTE_0
	v_lshlrev_b32_e32 v4, 1, v1
	v_lshrrev_b32_e32 v5, 2, v1
	v_and_b32_e32 v6, 3, v10
	s_mov_b32 s7, 0xffffe0
	v_bfe_i32 v11, v2, 0, 16
	v_and_b32_e32 v4, 24, v4
	v_and_b32_e32 v5, 4, v5
	v_and_or_b32 v6, v1, s7, v6
	s_movk_i32 s1, 0xb00
	v_add_u32_e32 v2, v9, v11
	v_or3_b32 v4, v6, v5, v4
	v_mul_lo_u32 v1, v1, s1
	v_lshrrev_b32_e32 v250, 6, v236
	v_and_b32_e32 v251, 63, v236
	v_lshrrev_b32_e32 v252, 3, v251
	v_and_b32_e32 v251, 7, v251
	v_xor_b32_e32 v251, v251, v252
	v_lshlrev_b32_e32 v251, 4, v251
	v_lshl_add_u32 v253, v250, 3, v252
	v_mul_u32_u24_e32 v246, 0x1600, v253
	v_add_u32_e32 v246, v246, v251
	v_add_u32_e32 v247, 0x58000, v246
	v_lshrrev_b32_e32 v253, 2, v250
	v_lshlrev_b32_e32 v253, 5, v253
	v_and_b32_e32 v248, 1, v250
	v_lshl_add_u32 v253, v248, 4, v253
	v_bfe_u32 v248, v250, 1, 1
	v_lshl_add_u32 v253, v248, 2, v253
	v_lshrrev_b32_e32 v248, 2, v252
	v_lshl_add_u32 v253, v248, 3, v253
	v_and_b32_e32 v248, 3, v252
	v_add_u32_e32 v253, v253, v248
	v_mul_u32_u24_e32 v248, 0x1600, v253
	v_add_u32_e32 v248, v248, v251
	v_add_u32_e32 v249, 0x58000, v248
	v_add_lshl_u32 v128, v2, v1, 1
	v_mov_b32_e32 v252, v128
	v_mov_b32_e32 v128, v246
	v_mul_u32_u24_e32 v1, 0xb00, v4
	v_add_u32_e32 v0, 0x2000, v0
	v_add_lshl_u32 v130, v1, v2, 1
	v_mov_b32_e32 v130, v248
	v_ashrrev_i32_e32 v1, 31, v0
	v_lshrrev_b32_e32 v1, 22, v1
	v_add_u32_e32 v1, v0, v1
	v_ashrrev_i32_e32 v12, 10, v1
	v_mul_i32_i24_e32 v1, 0x400, v12
	v_sub_u32_e32 v0, v0, v1
	v_lshrrev_b32_e32 v1, 4, v0
	v_bitop3_b32 v0, v1, v0, 32 bitop3:0x6c
	s_add_u32 s3, s82, 0x1e00000
	v_ashrrev_i32_e32 v2, 31, v0
	s_addc_u32 s22, s83, 0
	v_lshrrev_b32_e32 v2, 26, v2
	s_add_i32 s5, s5, s6
	v_lshlrev_b32_e32 v1, 3, v12
	v_add_u32_e32 v2, v0, v2
	s_ashr_i32 s6, s5, 31
	v_and_b32_e32 v1, -16, v1
	v_ashrrev_i32_e32 v13, 6, v2
	v_lshlrev_b32_e32 v4, 5, v12
	s_lshr_b32 s6, s6, 27
	v_add_u32_e32 v1, v13, v1
	v_and_b32_e32 v14, 32, v4
	v_and_b32_e32 v4, 3, v13
	s_add_i32 s6, s5, s6
	v_and_or_b32 v4, v1, s7, v4
	s_ashr_i32 s7, s6, 5
	s_and_b32 s6, s6, 0xffe0
	s_sub_i32 s6, s5, s6
	s_bfe_i32 s5, s6, 0x80000
	s_bfe_u32 s5, s5, 0x3000c
	s_add_i32 s9, s6, s5
	s_bfe_i32 s5, s9, 0x80000
	s_and_b32 s9, s9, 0xf8
	s_sub_i32 s6, s6, s9
	s_lshl_b32 s7, s7, 3
	s_sext_i32_i16 s10, s5
	s_sext_i32_i8 s6, s6
	v_and_b32_e32 v2, 0xc0, v2
	s_ashr_i32 s8, s4, 6
	s_add_i32 s39, s7, s6
	s_ashr_i32 s6, s10, 3
	s_ashr_i32 s0, s4, 8
	v_sub_u32_e32 v0, v0, v2
	s_lshl_b32 s23, s8, 10
	s_lshr_b32 s5, s10, 3
	s_mul_hi_i32 s7, s6, 0x160000
	s_mul_i32 s6, s6, 0x160000
	v_ashrrev_i16_sdwa v0, v3, sext(v0) dst_sel:DWORD dst_unused:UNUSED_PAD src0_sel:DWORD src1_sel:BYTE_0
	v_lshlrev_b32_e32 v2, 1, v1
	v_lshrrev_b32_e32 v3, 2, v1
	s_add_u32 s16, s3, s6
	v_bfe_i32 v15, v0, 0, 16
	v_and_b32_e32 v2, 24, v2
	v_and_b32_e32 v3, 4, v3
	s_addc_u32 s17, s22, s7
	s_add_i32 s24, s23, 0
	v_add_u32_e32 v0, v14, v15
	v_or3_b32 v2, v4, v3, v2
	v_mul_lo_u32 v1, v1, s1
	s_add_i32 m0, s24, 0x10000
	v_add_lshl_u32 v132, v0, v1, 1
	v_mov_b32_e32 v253, v132
	v_mov_b32_e32 v132, v247
	v_mul_u32_u24_e32 v1, 0xb00, v2
	global_load_lds_dwordx4 v130, s[16:17]
	s_add_i32 m0, s24, 0x12000
	v_add_lshl_u32 v134, v1, v0, 1
	v_mov_b32_e32 v134, v249
	s_add_u32 s6, s16, 0xb0000
	global_load_lds_dwordx4 v134, s[16:17]
	s_addc_u32 s7, s17, 0
	s_add_i32 m0, s24, 0x14000
	s_mul_i32 s11, s39, 0x160000
	global_load_lds_dwordx4 v130, s[6:7]
	s_add_i32 m0, s24, 0x16000
	s_mul_hi_i32 s9, s39, 0x160000
	s_add_u32 s14, s92, s11
	s_addc_u32 s15, s93, s9
	s_add_i32 s25, s24, 0x2000
	global_load_lds_dwordx4 v134, s[6:7]
	s_mov_b32 m0, s24
	s_add_u32 s6, s14, 0xb0000
	global_load_lds_dwordx4 v128, s[14:15]
	s_mov_b32 m0, s25
	s_addc_u32 s7, s15, 0
	s_add_i32 s26, s24, 0x4000
	global_load_lds_dwordx4 v132, s[14:15]
	s_mov_b32 m0, s26
	s_add_i32 s27, s24, 0x6000
	global_load_lds_dwordx4 v128, s[6:7]
	s_mov_b32 m0, s27
	v_mov_b32_e32 v131, 0
	global_load_lds_dwordx4 v132, s[6:7]
	v_mov_b32_e32 v135, v131
	v_mov_b32_e32 v129, v131
	v_mov_b32_e32 v133, v131
	s_cmp_eq_u32 s0, 1
	s_mov_b32 s28, 0
	v_lshl_add_u64 v[6:7], s[16:17], 0, v[130:131]
	v_lshl_add_u64 v[4:5], s[16:17], 0, v[134:135]
	v_lshl_add_u64 v[0:1], s[14:15], 0, v[128:129]
	s_cselect_b64 s[6:7], -1, 0
	s_cmp_lg_u32 s0, 1
	v_lshl_add_u64 v[2:3], s[14:15], 0, v[132:133]
	s_cbranch_scc1 .LBB0_1182
	s_barrier
.LBB0_1182:
	s_add_u32 s29, s82, 0x18000
	s_addc_u32 s30, s83, 0
	s_lshl_b32 s8, s8, 5
	s_and_b32 s18, s8, 0x60
	s_mov_b64 s[8:9], 0x80
	s_add_i32 m0, s24, 0x18000
	v_lshl_add_u64 v[6:7], v[6:7], 0, s[8:9]
	s_lshl_b32 s12, s0, 13
	s_lshl_b32 s13, s18, 7
	s_waitcnt vmcnt(2)
	s_barrier
	global_load_lds_dwordx4 v[6:7], off
	v_lshl_add_u64 v[4:5], v[4:5], 0, s[8:9]
	s_add_i32 m0, s24, 0x1a000
	s_add_i32 s31, s24, 0x8000
	s_add_i32 s33, s24, 0xa000
	global_load_lds_dwordx4 v[4:5], off
	v_lshl_add_u64 v[0:1], v[0:1], 0, s[8:9]
	s_mov_b32 m0, s31
	s_add_u32 s10, s16, 0xb0080
	global_load_lds_dwordx4 v[0:1], off
	v_lshl_add_u64 v[0:1], v[2:3], 0, s[8:9]
	s_mov_b32 m0, s33
	s_addc_u32 s11, s17, 0
	global_load_lds_dwordx4 v[0:1], off
	s_add_i32 m0, s24, 0x1c000
	v_lshl_add_u64 v[0:1], s[10:11], 0, v[130:131]
	global_load_lds_dwordx4 v[0:1], off
	v_lshl_add_u64 v[0:1], s[10:11], 0, v[134:135]
	s_add_i32 m0, s24, 0x1e000
	s_sext_i32_i8 s40, s5
	global_load_lds_dwordx4 v[0:1], off
	v_lshrrev_b32_e32 v1, 1, v236
	v_and_b32_e32 v1, 24, v1
	v_and_b32_e32 v0, 15, v236
	v_lshlrev_b32_e32 v2, 1, v1
	v_lshl_or_b32 v168, s0, 6, v0
	v_lshl_or_b32 v0, v0, 6, v2
	v_lshlrev_b32_e32 v2, 2, v236
	v_and_b32_e32 v2, 32, v2
	v_bitop3_b32 v3, v0, s12, v2 bitop3:0xde
	v_bitop3_b32 v169, v0, s13, v2 bitop3:0xde
	v_or_b32_e32 v170, s18, v1
	v_lshrrev_b32_e32 v1, 1, v8
	v_mul_lo_u32 v0, v10, s1
	s_mov_b32 s0, 0xb000
	s_cmpk_lt_u32 s4, 0x100
	v_mad_u64_u32 v[0:1], s[4:5], v1, s0, v[0:1]
	v_or_b32_e32 v0, v0, v9
	s_mov_b64 s[12:13], 0xb0080
	v_add_lshl_u32 v0, v0, v11, 1
	v_mov_b32_e32 v1, v131
	v_lshl_add_u64 v[136:137], v[0:1], 0, s[12:13]
	v_lshrrev_b32_e32 v1, 1, v12
	v_mul_lo_u32 v0, v13, s1
	v_mad_u64_u32 v[0:1], s[0:1], v1, s0, v[0:1]
	s_waitcnt vmcnt(6)
	v_or_b32_e32 v0, v0, v14
	s_cselect_b64 s[10:11], -1, 0
	v_add_lshl_u32 v0, v0, v15, 1
	v_mov_b32_e32 v1, v131
	s_add_i32 s35, 0, 0x10000
	s_add_i32 s36, 0, 0x14000
	s_ashr_i32 s34, s86, 31
	v_lshl_add_u64 v[138:139], v[0:1], 0, s[12:13]
	v_mov_b64_e32 v[140:141], 0x200
	v_mov_b64_e32 v[142:143], 0x1ff
	v_add_u32_e32 v171, s35, v169
	v_add_u32_e32 v172, s36, v169
	v_add_u32_e32 v173, 0, v3
	s_barrier
	v_sub_u32_e32 v136, v136, v252
	v_add_u32_e32 v136, v136, v128
	v_sub_u32_e32 v138, v138, v253
	v_add_u32_e32 v138, v138, v132
	v_and_b32_e32 v250, 63, v236
	v_and_b32_e32 v251, 15, v250
	v_lshrrev_b32_e32 v252, 4, v250
	v_and_b32_e32 v253, 7, v251
	v_xor_b32_e32 v252, v252, v253
	v_lshlrev_b32_e32 v252, 4, v252
	v_lshl_add_u32 v252, v251, 7, v252
	v_lshrrev_b32_e32 v250, 6, v236
	v_lshrrev_b32_e32 v251, 2, v250
	v_lshl_add_u32 v173, v251, 13, v252
	v_and_b32_e32 v251, 3, v250
	v_lshl_add_u32 v169, v251, 12, v252
	v_add_u32_e32 v171, s35, v169
	v_add_u32_e32 v172, s36, v169
	s_branch .LBB0_1185

.LBB0_1195:
	s_add_u32 s41, s16, 0x100
	v_mov_b32_e32 v0, 0
	s_addc_u32 s42, s17, 0
	s_mov_b32 s43, -2
	v_mov_b32_e32 v1, v0
	v_mov_b32_e32 v2, v0
	v_mov_b32_e32 v3, v0
	v_mov_b32_e32 v4, v0
	v_mov_b32_e32 v5, v0
	v_mov_b32_e32 v6, v0
	v_mov_b32_e32 v7, v0
	v_mov_b32_e32 v12, v0
	v_mov_b32_e32 v13, v0
	v_mov_b32_e32 v14, v0
	v_mov_b32_e32 v15, v0
	v_mov_b32_e32 v20, v0
	v_mov_b32_e32 v21, v0
	v_mov_b32_e32 v22, v0
	v_mov_b32_e32 v23, v0
	v_mov_b32_e32 v28, v0
	v_mov_b32_e32 v29, v0
	v_mov_b32_e32 v30, v0
	v_mov_b32_e32 v31, v0
	v_mov_b32_e32 v36, v0
	v_mov_b32_e32 v37, v0
	v_mov_b32_e32 v38, v0
	v_mov_b32_e32 v39, v0
	v_mov_b32_e32 v44, v0
	v_mov_b32_e32 v45, v0
	v_mov_b32_e32 v46, v0
	v_mov_b32_e32 v47, v0
	v_mov_b32_e32 v52, v0
	v_mov_b32_e32 v53, v0
	v_mov_b32_e32 v54, v0
	v_mov_b32_e32 v55, v0
	v_mov_b32_e32 v8, v0
	v_mov_b32_e32 v9, v0
	v_mov_b32_e32 v10, v0
	v_mov_b32_e32 v11, v0
	v_mov_b32_e32 v16, v0
	v_mov_b32_e32 v17, v0
	v_mov_b32_e32 v18, v0
	v_mov_b32_e32 v19, v0
	v_mov_b32_e32 v24, v0
	v_mov_b32_e32 v25, v0
	v_mov_b32_e32 v26, v0
	v_mov_b32_e32 v27, v0
	v_mov_b32_e32 v32, v0
	v_mov_b32_e32 v33, v0
	v_mov_b32_e32 v34, v0
	v_mov_b32_e32 v35, v0
	v_mov_b32_e32 v40, v0
	v_mov_b32_e32 v41, v0
	v_mov_b32_e32 v42, v0
	v_mov_b32_e32 v43, v0
	v_mov_b32_e32 v48, v0
	v_mov_b32_e32 v49, v0
	v_mov_b32_e32 v50, v0
	v_mov_b32_e32 v51, v0
	v_mov_b32_e32 v56, v0
	v_mov_b32_e32 v57, v0
	v_mov_b32_e32 v58, v0
	v_mov_b32_e32 v59, v0
	v_mov_b32_e32 v60, v0
	v_mov_b32_e32 v61, v0
	v_mov_b32_e32 v62, v0
	v_mov_b32_e32 v63, v0
	v_mov_b32_e32 v64, v0
	v_mov_b32_e32 v65, v0
	v_mov_b32_e32 v66, v0
	v_mov_b32_e32 v67, v0
	v_mov_b32_e32 v68, v0
	v_mov_b32_e32 v69, v0
	v_mov_b32_e32 v70, v0
	v_mov_b32_e32 v71, v0
	v_mov_b32_e32 v76, v0
	v_mov_b32_e32 v77, v0
	v_mov_b32_e32 v78, v0
	v_mov_b32_e32 v79, v0
	v_mov_b32_e32 v84, v0
	v_mov_b32_e32 v85, v0
	v_mov_b32_e32 v86, v0
	v_mov_b32_e32 v87, v0
	v_mov_b32_e32 v92, v0
	v_mov_b32_e32 v93, v0
	v_mov_b32_e32 v94, v0
	v_mov_b32_e32 v95, v0
	v_mov_b32_e32 v100, v0
	v_mov_b32_e32 v101, v0
	v_mov_b32_e32 v102, v0
	v_mov_b32_e32 v103, v0
	v_mov_b32_e32 v108, v0
	v_mov_b32_e32 v109, v0
	v_mov_b32_e32 v110, v0
	v_mov_b32_e32 v111, v0
	v_mov_b32_e32 v116, v0
	v_mov_b32_e32 v117, v0
	v_mov_b32_e32 v118, v0
	v_mov_b32_e32 v119, v0
	v_mov_b32_e32 v72, v0
	s_waitcnt vmcnt(0)
	v_mov_b32_e32 v73, v0
	v_mov_b32_e32 v74, v0
	v_mov_b32_e32 v75, v0
	v_mov_b32_e32 v80, v0
	v_mov_b32_e32 v81, v0
	v_mov_b32_e32 v82, v0
	v_mov_b32_e32 v83, v0
	v_mov_b32_e32 v88, v0
	v_mov_b32_e32 v89, v0
	v_mov_b32_e32 v90, v0
	v_mov_b32_e32 v91, v0
	v_mov_b32_e32 v96, v0
	v_mov_b32_e32 v97, v0
	v_mov_b32_e32 v98, v0
	v_mov_b32_e32 v99, v0
	v_mov_b32_e32 v104, v0
	v_mov_b32_e32 v105, v0
	v_mov_b32_e32 v106, v0
	v_mov_b32_e32 v107, v0
	v_mov_b32_e32 v112, v0
	v_mov_b32_e32 v113, v0
	v_mov_b32_e32 v114, v0
	v_mov_b32_e32 v115, v0
	v_mov_b32_e32 v120, v0
	v_mov_b32_e32 v121, v0
	v_mov_b32_e32 v122, v0
	v_mov_b32_e32 v123, v0
	v_mov_b32_e32 v124, v0
	v_mov_b32_e32 v125, v0
	v_mov_b32_e32 v126, v0
	v_mov_b32_e32 v127, v0
	v_xor_b32_e32 v246, 64, v173
	v_xor_b32_e32 v247, 64, v169
	v_add_u32_e32 v248, s35, v247
	v_add_u32_e32 v249, s36, v247
.LBB0_1196:
	ds_read_b128 v[144:147], v171
	ds_read_b128 v[148:151], v248
	ds_read_b128 v[152:155], v171 offset:2048
	ds_read_b128 v[156:159], v248 offset:2048
	ds_read_b128 v[160:163], v172
	ds_read_b128 v[164:167], v249
	ds_read_b128 v[174:177], v172 offset:2048
	ds_read_b128 v[178:181], v249 offset:2048
	s_add_u32 s16, s14, 0x100
	s_addc_u32 s17, s15, 0
	s_cmp_eq_u32 s43, 40
	s_cselect_b32 s21, s5, s17
	s_cselect_b32 s20, s4, s16
	s_cselect_b32 s19, s13, s42
	s_cselect_b32 s18, s12, s41
	v_lshl_add_u64 v[214:215], s[14:15], 0, v[136:137]
	s_add_i32 m0, s24, 0xc000
	ds_read_b128 v[182:185], v173
	ds_read_b128 v[186:189], v246
	ds_read_b128 v[190:193], v173 offset:2048
	ds_read_b128 v[194:197], v246 offset:2048
	ds_read_b128 v[198:201], v173 offset:4096
	ds_read_b128 v[202:205], v246 offset:4096
	ds_read_b128 v[206:209], v173 offset:6144
	ds_read_b128 v[210:213], v246 offset:6144
	global_load_lds_dwordx4 v[214:215], off
	v_lshl_add_u64 v[214:215], s[14:15], 0, v[138:139]
	s_add_i32 m0, s24, 0xe000
	s_nop 0
	global_load_lds_dwordx4 v[214:215], off
	s_waitcnt vmcnt(8)
	s_waitcnt lgkmcnt(0)
	s_barrier
	s_setprio 0
	s_waitcnt lgkmcnt(0)
	v_mfma_f32_16x16x32_bf16 v[124:127], v[144:147], v[182:185], v[124:127]
	v_mfma_f32_16x16x32_bf16 v[120:123], v[152:155], v[182:185], v[120:123]
	v_mfma_f32_16x16x32_bf16 v[112:115], v[144:147], v[190:193], v[112:115]
	v_mfma_f32_16x16x32_bf16 v[104:107], v[152:155], v[190:193], v[104:107]
	v_mfma_f32_16x16x32_bf16 v[96:99], v[144:147], v[198:201], v[96:99]
	v_mfma_f32_16x16x32_bf16 v[88:91], v[152:155], v[198:201], v[88:91]
	v_mfma_f32_16x16x32_bf16 v[80:83], v[144:147], v[206:209], v[80:83]
	v_mfma_f32_16x16x32_bf16 v[72:75], v[152:155], v[206:209], v[72:75]
	v_mfma_f32_16x16x32_bf16 v[124:127], v[148:151], v[186:189], v[124:127]
	v_mfma_f32_16x16x32_bf16 v[120:123], v[156:159], v[186:189], v[120:123]
	v_mfma_f32_16x16x32_bf16 v[112:115], v[148:151], v[194:197], v[112:115]
	v_mfma_f32_16x16x32_bf16 v[104:107], v[156:159], v[194:197], v[104:107]
	v_mfma_f32_16x16x32_bf16 v[96:99], v[148:151], v[202:205], v[96:99]
	v_mfma_f32_16x16x32_bf16 v[88:91], v[156:159], v[202:205], v[88:91]
	v_mfma_f32_16x16x32_bf16 v[80:83], v[148:151], v[210:213], v[80:83]
	v_mfma_f32_16x16x32_bf16 v[72:75], v[156:159], v[210:213], v[72:75]
	s_setprio 0
	s_setprio 0
	v_mfma_f32_16x16x32_bf16 v[116:119], v[160:163], v[182:185], v[116:119]
	v_mfma_f32_16x16x32_bf16 v[108:111], v[174:177], v[182:185], v[108:111]
	v_mfma_f32_16x16x32_bf16 v[100:103], v[160:163], v[190:193], v[100:103]
	v_mfma_f32_16x16x32_bf16 v[92:95], v[174:177], v[190:193], v[92:95]
	v_mfma_f32_16x16x32_bf16 v[84:87], v[160:163], v[198:201], v[84:87]
	v_mfma_f32_16x16x32_bf16 v[76:79], v[174:177], v[198:201], v[76:79]
	v_mfma_f32_16x16x32_bf16 v[68:71], v[160:163], v[206:209], v[68:71]
	v_mfma_f32_16x16x32_bf16 v[64:67], v[174:177], v[206:209], v[64:67]
	v_mfma_f32_16x16x32_bf16 v[116:119], v[164:167], v[186:189], v[116:119]
	v_mfma_f32_16x16x32_bf16 v[108:111], v[178:181], v[186:189], v[108:111]
	v_mfma_f32_16x16x32_bf16 v[100:103], v[164:167], v[194:197], v[100:103]
	v_mfma_f32_16x16x32_bf16 v[92:95], v[178:181], v[194:197], v[92:95]
	v_mfma_f32_16x16x32_bf16 v[84:87], v[164:167], v[202:205], v[84:87]
	v_mfma_f32_16x16x32_bf16 v[76:79], v[178:181], v[202:205], v[76:79]
	v_mfma_f32_16x16x32_bf16 v[68:71], v[164:167], v[210:213], v[68:71]
	v_mfma_f32_16x16x32_bf16 v[64:67], v[178:181], v[210:213], v[64:67]
	s_setprio 0
	s_barrier
	s_add_i32 s14, s35, s23
	v_lshl_add_u64 v[214:215], s[18:19], 0, v[130:131]
	s_mov_b32 m0, s14
	ds_read_b128 v[182:185], v173 offset:16384
	ds_read_b128 v[186:189], v246 offset:16384
	ds_read_b128 v[190:193], v173 offset:18432
	ds_read_b128 v[194:197], v246 offset:18432
	ds_read_b128 v[198:201], v173 offset:20480
	ds_read_b128 v[202:205], v246 offset:20480
	ds_read_b128 v[206:209], v173 offset:22528
	ds_read_b128 v[210:213], v246 offset:22528
	global_load_lds_dwordx4 v[214:215], off
	s_add_i32 m0, s14, 0x2000
	s_add_u32 s14, s18, 0xb0000
	v_lshl_add_u64 v[216:217], s[18:19], 0, v[134:135]
	s_addc_u32 s15, s19, 0
	s_add_i32 s44, s36, s23
	global_load_lds_dwordx4 v[216:217], off
	v_lshl_add_u64 v[218:219], s[14:15], 0, v[130:131]
	s_mov_b32 m0, s44
	v_lshl_add_u64 v[220:221], s[20:21], 0, v[132:133]
	global_load_lds_dwordx4 v[218:219], off
	v_lshl_add_u64 v[218:219], s[14:15], 0, v[134:135]
	s_add_i32 m0, s44, 0x2000
	s_nop 0
	global_load_lds_dwordx4 v[218:219], off
	v_lshl_add_u64 v[218:219], s[20:21], 0, v[128:129]
	s_mov_b32 m0, s24
	s_nop 0
	global_load_lds_dwordx4 v[218:219], off
	s_mov_b32 m0, s25
	s_nop 0
	global_load_lds_dwordx4 v[220:221], off
	s_waitcnt vmcnt(8)
	s_waitcnt lgkmcnt(0)
	s_barrier
	s_setprio 0
	s_waitcnt lgkmcnt(0)
	v_mfma_f32_16x16x32_bf16 v[60:63], v[144:147], v[182:185], v[60:63]
	v_mfma_f32_16x16x32_bf16 v[56:59], v[152:155], v[182:185], v[56:59]
	v_mfma_f32_16x16x32_bf16 v[48:51], v[144:147], v[190:193], v[48:51]
	v_mfma_f32_16x16x32_bf16 v[40:43], v[152:155], v[190:193], v[40:43]
	v_mfma_f32_16x16x32_bf16 v[32:35], v[144:147], v[198:201], v[32:35]
	v_mfma_f32_16x16x32_bf16 v[24:27], v[152:155], v[198:201], v[24:27]
	v_mfma_f32_16x16x32_bf16 v[16:19], v[144:147], v[206:209], v[16:19]
	v_mfma_f32_16x16x32_bf16 v[8:11], v[152:155], v[206:209], v[8:11]
	v_mfma_f32_16x16x32_bf16 v[60:63], v[148:151], v[186:189], v[60:63]
	v_mfma_f32_16x16x32_bf16 v[56:59], v[156:159], v[186:189], v[56:59]
	v_mfma_f32_16x16x32_bf16 v[48:51], v[148:151], v[194:197], v[48:51]
	v_mfma_f32_16x16x32_bf16 v[40:43], v[156:159], v[194:197], v[40:43]
	v_mfma_f32_16x16x32_bf16 v[32:35], v[148:151], v[202:205], v[32:35]
	v_mfma_f32_16x16x32_bf16 v[24:27], v[156:159], v[202:205], v[24:27]
	v_mfma_f32_16x16x32_bf16 v[16:19], v[148:151], v[210:213], v[16:19]
	v_mfma_f32_16x16x32_bf16 v[8:11], v[156:159], v[210:213], v[8:11]
	s_setprio 0
	s_setprio 0
	v_mfma_f32_16x16x32_bf16 v[52:55], v[160:163], v[182:185], v[52:55]
	v_mfma_f32_16x16x32_bf16 v[44:47], v[174:177], v[182:185], v[44:47]
	v_mfma_f32_16x16x32_bf16 v[36:39], v[160:163], v[190:193], v[36:39]
	v_mfma_f32_16x16x32_bf16 v[28:31], v[174:177], v[190:193], v[28:31]
	v_mfma_f32_16x16x32_bf16 v[20:23], v[160:163], v[198:201], v[20:23]
	v_mfma_f32_16x16x32_bf16 v[12:15], v[174:177], v[198:201], v[12:15]
	v_mfma_f32_16x16x32_bf16 v[4:7], v[160:163], v[206:209], v[4:7]
	v_mfma_f32_16x16x32_bf16 v[0:3], v[174:177], v[206:209], v[0:3]
	v_mfma_f32_16x16x32_bf16 v[52:55], v[164:167], v[186:189], v[52:55]
	v_mfma_f32_16x16x32_bf16 v[44:47], v[178:181], v[186:189], v[44:47]
	v_mfma_f32_16x16x32_bf16 v[36:39], v[164:167], v[194:197], v[36:39]
	v_mfma_f32_16x16x32_bf16 v[28:31], v[178:181], v[194:197], v[28:31]
	v_mfma_f32_16x16x32_bf16 v[20:23], v[164:167], v[202:205], v[20:23]
	v_mfma_f32_16x16x32_bf16 v[12:15], v[178:181], v[202:205], v[12:15]
	v_mfma_f32_16x16x32_bf16 v[4:7], v[164:167], v[210:213], v[4:7]
	v_mfma_f32_16x16x32_bf16 v[0:3], v[178:181], v[210:213], v[0:3]
	s_setprio 0
	s_barrier
	s_add_i32 s44, 0, 0x18000
	s_add_i32 s45, 0, 0x1c000
	v_add_u32_e32 v156, s44, v169
	v_add_u32_e32 v250, s44, v247
	v_add_u32_e32 v178, s45, v169
	v_add_u32_e32 v251, s45, v247
	ds_read_b128 v[144:147], v156
	ds_read_b128 v[148:151], v250
	ds_read_b128 v[152:155], v156 offset:2048
	ds_read_b128 v[156:159], v250 offset:2048
	ds_read_b128 v[160:163], v178
	ds_read_b128 v[164:167], v251
	ds_read_b128 v[174:177], v178 offset:2048
	ds_read_b128 v[178:181], v251 offset:2048
	s_add_u32 s14, s20, 0xb0000
	s_addc_u32 s15, s21, 0
	s_mov_b32 m0, s26
	v_lshl_add_u64 v[222:223], s[14:15], 0, v[128:129]
	ds_read_b128 v[182:185], v173 offset:32768
	ds_read_b128 v[186:189], v246 offset:32768
	ds_read_b128 v[190:193], v173 offset:34816
	ds_read_b128 v[194:197], v246 offset:34816
	ds_read_b128 v[198:201], v173 offset:36864
	ds_read_b128 v[202:205], v246 offset:36864
	ds_read_b128 v[206:209], v173 offset:38912
	ds_read_b128 v[210:213], v246 offset:38912
	global_load_lds_dwordx4 v[222:223], off
	v_lshl_add_u64 v[222:223], s[14:15], 0, v[132:133]
	s_mov_b32 m0, s27
	s_nop 0
	global_load_lds_dwordx4 v[222:223], off
	s_waitcnt vmcnt(8)
	s_waitcnt lgkmcnt(0)
	s_barrier
	s_setprio 0
	s_waitcnt lgkmcnt(0)
	v_mfma_f32_16x16x32_bf16 v[124:127], v[144:147], v[182:185], v[124:127]
	v_mfma_f32_16x16x32_bf16 v[120:123], v[152:155], v[182:185], v[120:123]
	v_mfma_f32_16x16x32_bf16 v[112:115], v[144:147], v[190:193], v[112:115]
	v_mfma_f32_16x16x32_bf16 v[104:107], v[152:155], v[190:193], v[104:107]
	v_mfma_f32_16x16x32_bf16 v[96:99], v[144:147], v[198:201], v[96:99]
	v_mfma_f32_16x16x32_bf16 v[88:91], v[152:155], v[198:201], v[88:91]
	v_mfma_f32_16x16x32_bf16 v[80:83], v[144:147], v[206:209], v[80:83]
	v_mfma_f32_16x16x32_bf16 v[72:75], v[152:155], v[206:209], v[72:75]
	v_mfma_f32_16x16x32_bf16 v[124:127], v[148:151], v[186:189], v[124:127]
	v_mfma_f32_16x16x32_bf16 v[120:123], v[156:159], v[186:189], v[120:123]
	v_mfma_f32_16x16x32_bf16 v[112:115], v[148:151], v[194:197], v[112:115]
	v_mfma_f32_16x16x32_bf16 v[104:107], v[156:159], v[194:197], v[104:107]
	v_mfma_f32_16x16x32_bf16 v[96:99], v[148:151], v[202:205], v[96:99]
	v_mfma_f32_16x16x32_bf16 v[88:91], v[156:159], v[202:205], v[88:91]
	v_mfma_f32_16x16x32_bf16 v[80:83], v[148:151], v[210:213], v[80:83]
	v_mfma_f32_16x16x32_bf16 v[72:75], v[156:159], v[210:213], v[72:75]
	s_setprio 0
	s_setprio 0
	v_mfma_f32_16x16x32_bf16 v[116:119], v[160:163], v[182:185], v[116:119]
	v_mfma_f32_16x16x32_bf16 v[108:111], v[174:177], v[182:185], v[108:111]
	v_mfma_f32_16x16x32_bf16 v[100:103], v[160:163], v[190:193], v[100:103]
	v_mfma_f32_16x16x32_bf16 v[92:95], v[174:177], v[190:193], v[92:95]
	v_mfma_f32_16x16x32_bf16 v[84:87], v[160:163], v[198:201], v[84:87]
	v_mfma_f32_16x16x32_bf16 v[76:79], v[174:177], v[198:201], v[76:79]
	v_mfma_f32_16x16x32_bf16 v[68:71], v[160:163], v[206:209], v[68:71]
	v_mfma_f32_16x16x32_bf16 v[64:67], v[174:177], v[206:209], v[64:67]
	v_mfma_f32_16x16x32_bf16 v[116:119], v[164:167], v[186:189], v[116:119]
	v_mfma_f32_16x16x32_bf16 v[108:111], v[178:181], v[186:189], v[108:111]
	v_mfma_f32_16x16x32_bf16 v[100:103], v[164:167], v[194:197], v[100:103]
	v_mfma_f32_16x16x32_bf16 v[92:95], v[178:181], v[194:197], v[92:95]
	v_mfma_f32_16x16x32_bf16 v[84:87], v[164:167], v[202:205], v[84:87]
	v_mfma_f32_16x16x32_bf16 v[76:79], v[178:181], v[202:205], v[76:79]
	v_mfma_f32_16x16x32_bf16 v[68:71], v[164:167], v[210:213], v[68:71]
	v_mfma_f32_16x16x32_bf16 v[64:67], v[178:181], v[210:213], v[64:67]
	s_setprio 0
	s_barrier
	s_add_i32 s14, s44, s23
	v_lshl_add_u64 v[214:215], v[214:215], 0, s[8:9]
	s_mov_b32 m0, s14
	ds_read_b128 v[182:185], v173 offset:49152
	ds_read_b128 v[186:189], v246 offset:49152
	ds_read_b128 v[190:193], v173 offset:51200
	ds_read_b128 v[194:197], v246 offset:51200
	ds_read_b128 v[198:201], v173 offset:53248
	ds_read_b128 v[202:205], v246 offset:53248
	ds_read_b128 v[206:209], v173 offset:55296
	ds_read_b128 v[210:213], v246 offset:55296
	global_load_lds_dwordx4 v[214:215], off
	s_add_i32 m0, s14, 0x2000
	s_add_u32 s14, s18, 0xb0080
	v_lshl_add_u64 v[214:215], v[216:217], 0, s[8:9]
	s_addc_u32 s15, s19, 0
	s_add_i32 s18, s45, s23
	global_load_lds_dwordx4 v[214:215], off
	v_lshl_add_u64 v[214:215], s[14:15], 0, v[130:131]
	s_mov_b32 m0, s18
	s_nop 0
	global_load_lds_dwordx4 v[214:215], off
	v_lshl_add_u64 v[214:215], s[14:15], 0, v[134:135]
	s_add_i32 m0, s18, 0x2000
	s_nop 0
	global_load_lds_dwordx4 v[214:215], off
	v_lshl_add_u64 v[214:215], v[218:219], 0, s[8:9]
	s_mov_b32 m0, s31
	s_nop 0
	global_load_lds_dwordx4 v[214:215], off
	v_lshl_add_u64 v[214:215], v[220:221], 0, s[8:9]
	s_mov_b32 m0, s33
	s_nop 0
	global_load_lds_dwordx4 v[214:215], off
	s_waitcnt vmcnt(8)
	s_waitcnt lgkmcnt(0)
	s_barrier
	s_setprio 0
	s_waitcnt lgkmcnt(0)
	v_mfma_f32_16x16x32_bf16 v[60:63], v[144:147], v[182:185], v[60:63]
	v_mfma_f32_16x16x32_bf16 v[56:59], v[152:155], v[182:185], v[56:59]
	v_mfma_f32_16x16x32_bf16 v[48:51], v[144:147], v[190:193], v[48:51]
	v_mfma_f32_16x16x32_bf16 v[40:43], v[152:155], v[190:193], v[40:43]
	v_mfma_f32_16x16x32_bf16 v[32:35], v[144:147], v[198:201], v[32:35]
	v_mfma_f32_16x16x32_bf16 v[24:27], v[152:155], v[198:201], v[24:27]
	v_mfma_f32_16x16x32_bf16 v[16:19], v[144:147], v[206:209], v[16:19]
	v_mfma_f32_16x16x32_bf16 v[8:11], v[152:155], v[206:209], v[8:11]
	v_mfma_f32_16x16x32_bf16 v[60:63], v[148:151], v[186:189], v[60:63]
	v_mfma_f32_16x16x32_bf16 v[56:59], v[156:159], v[186:189], v[56:59]
	v_mfma_f32_16x16x32_bf16 v[48:51], v[148:151], v[194:197], v[48:51]
	v_mfma_f32_16x16x32_bf16 v[40:43], v[156:159], v[194:197], v[40:43]
	v_mfma_f32_16x16x32_bf16 v[32:35], v[148:151], v[202:205], v[32:35]
	v_mfma_f32_16x16x32_bf16 v[24:27], v[156:159], v[202:205], v[24:27]
	v_mfma_f32_16x16x32_bf16 v[16:19], v[148:151], v[210:213], v[16:19]
	v_mfma_f32_16x16x32_bf16 v[8:11], v[156:159], v[210:213], v[8:11]
	s_setprio 0
	s_setprio 0
	v_mfma_f32_16x16x32_bf16 v[52:55], v[160:163], v[182:185], v[52:55]
	v_mfma_f32_16x16x32_bf16 v[44:47], v[174:177], v[182:185], v[44:47]
	v_mfma_f32_16x16x32_bf16 v[36:39], v[160:163], v[190:193], v[36:39]
	v_mfma_f32_16x16x32_bf16 v[28:31], v[174:177], v[190:193], v[28:31]
	v_mfma_f32_16x16x32_bf16 v[20:23], v[160:163], v[198:201], v[20:23]
	v_mfma_f32_16x16x32_bf16 v[12:15], v[174:177], v[198:201], v[12:15]
	v_mfma_f32_16x16x32_bf16 v[4:7], v[160:163], v[206:209], v[4:7]
	v_mfma_f32_16x16x32_bf16 v[0:3], v[174:177], v[206:209], v[0:3]
	v_mfma_f32_16x16x32_bf16 v[52:55], v[164:167], v[186:189], v[52:55]
	v_mfma_f32_16x16x32_bf16 v[44:47], v[178:181], v[186:189], v[44:47]
	v_mfma_f32_16x16x32_bf16 v[36:39], v[164:167], v[194:197], v[36:39]
	v_mfma_f32_16x16x32_bf16 v[28:31], v[178:181], v[194:197], v[28:31]
	v_mfma_f32_16x16x32_bf16 v[20:23], v[164:167], v[202:205], v[20:23]
	v_mfma_f32_16x16x32_bf16 v[12:15], v[178:181], v[202:205], v[12:15]
	v_mfma_f32_16x16x32_bf16 v[4:7], v[164:167], v[210:213], v[4:7]
	v_mfma_f32_16x16x32_bf16 v[0:3], v[178:181], v[210:213], v[0:3]
	s_setprio 0
	s_barrier
	s_add_i32 s43, s43, 2
	s_add_u32 s41, s41, 0x100
	s_addc_u32 s42, s42, 0
	s_cmp_gt_u32 s43, 41
	s_mov_b64 s[14:15], s[16:17]
	s_cbranch_scc0 .LBB0_1196
	s_and_b64 vcc, exec, s[10:11]
	s_cbranch_vccz .LBB0_1199
	s_barrier
